# b11 + nt on all GEMM-phase epilogue dwordx4 stores
# baseline (speedup 1.0000x reference)
.LBB0_286:
	ds_read_b128 v[128:131], v162
	ds_read_b128 v[148:151], v162 offset:1024
	ds_read_b128 v[152:155], v162 offset:2048
	ds_read_b128 v[166:169], v162 offset:3072
	s_add_u32 s36, s34, 0xfffc0080
	s_addc_u32 s37, s35, -1
	s_cmp_eq_u32 s59, 12
	s_cselect_b32 s39, s23, s37
	s_cselect_b32 s38, s55, s36
	s_cselect_b32 s37, s21, s58
	s_cselect_b32 s36, s56, s57
	v_lshl_add_u64 v[156:157], s[34:35], 0, v[140:141]
	s_add_i32 m0, s31, 0xc000
	ds_read_b128 v[170:173], v163
	ds_read_b128 v[174:177], v163 offset:1024
	ds_read_b128 v[178:181], v163 offset:2048
	ds_read_b128 v[182:185], v163 offset:3072
	ds_read_b128 v[190:193], v163 offset:4096
	ds_read_b128 v[194:197], v163 offset:5120
	ds_read_b128 v[198:201], v163 offset:6144
	ds_read_b128 v[202:205], v163 offset:7168
	global_load_lds_dwordx4 v[156:157], off
	v_lshl_add_u64 v[156:157], s[34:35], 0, v[142:143]
	s_add_i32 m0, s31, 0xe000
	s_nop 0
	global_load_lds_dwordx4 v[156:157], off
	s_waitcnt lgkmcnt(8)
	s_barrier
	s_waitcnt lgkmcnt(0)
	s_setprio 1
	s_waitcnt lgkmcnt(0)
	v_mfma_f32_16x16x32_bf16 v[124:127], v[128:131], v[170:173], v[124:127]
	v_mfma_f32_16x16x32_bf16 v[120:123], v[152:155], v[170:173], v[120:123]
	v_mfma_f32_16x16x32_bf16 v[108:111], v[128:131], v[178:181], v[108:111]
	v_mfma_f32_16x16x32_bf16 v[104:107], v[152:155], v[178:181], v[104:107]
	v_mfma_f32_16x16x32_bf16 v[92:95], v[128:131], v[190:193], v[92:95]
	v_mfma_f32_16x16x32_bf16 v[88:91], v[152:155], v[190:193], v[88:91]
	v_mfma_f32_16x16x32_bf16 v[76:79], v[128:131], v[198:201], v[76:79]
	v_mfma_f32_16x16x32_bf16 v[72:75], v[152:155], v[198:201], v[72:75]
	v_mfma_f32_16x16x32_bf16 v[124:127], v[148:151], v[174:177], v[124:127]
	v_mfma_f32_16x16x32_bf16 v[120:123], v[166:169], v[174:177], v[120:123]
	v_mfma_f32_16x16x32_bf16 v[108:111], v[148:151], v[182:185], v[108:111]
	v_mfma_f32_16x16x32_bf16 v[104:107], v[166:169], v[182:185], v[104:107]
	v_mfma_f32_16x16x32_bf16 v[92:95], v[148:151], v[194:197], v[92:95]
	v_mfma_f32_16x16x32_bf16 v[88:91], v[166:169], v[194:197], v[88:91]
	v_mfma_f32_16x16x32_bf16 v[76:79], v[148:151], v[202:205], v[76:79]
	v_mfma_f32_16x16x32_bf16 v[72:75], v[166:169], v[202:205], v[72:75]
	s_setprio 0
	s_barrier
	s_add_i32 s60, s52, s44
	v_lshl_add_u64 v[156:157], s[36:37], 0, v[134:135]
	s_mov_b32 m0, s60
	ds_read_b128 v[206:209], v164
	ds_read_b128 v[210:213], v164 offset:1024
	ds_read_b128 v[214:217], v164 offset:2048
	ds_read_b128 v[218:221], v164 offset:3072
	global_load_lds_dwordx4 v[156:157], off
	v_lshl_add_u64 v[186:187], s[36:37], 0, v[138:139]
	s_add_i32 m0, s60, 0x2000
	s_nop 0
	global_load_lds_dwordx4 v[186:187], off
	s_barrier
	s_waitcnt lgkmcnt(0)
	s_setprio 1
	s_waitcnt lgkmcnt(0)
	v_mfma_f32_16x16x32_bf16 v[116:119], v[206:209], v[170:173], v[116:119]
	v_mfma_f32_16x16x32_bf16 v[112:115], v[214:217], v[170:173], v[112:115]
	v_mfma_f32_16x16x32_bf16 v[100:103], v[206:209], v[178:181], v[100:103]
	v_mfma_f32_16x16x32_bf16 v[96:99], v[214:217], v[178:181], v[96:99]
	v_mfma_f32_16x16x32_bf16 v[84:87], v[206:209], v[190:193], v[84:87]
	v_mfma_f32_16x16x32_bf16 v[80:83], v[214:217], v[190:193], v[80:83]
	v_mfma_f32_16x16x32_bf16 v[68:71], v[206:209], v[198:201], v[68:71]
	v_mfma_f32_16x16x32_bf16 v[64:67], v[214:217], v[198:201], v[64:67]
	v_mfma_f32_16x16x32_bf16 v[116:119], v[210:213], v[174:177], v[116:119]
	v_mfma_f32_16x16x32_bf16 v[112:115], v[218:221], v[174:177], v[112:115]
	v_mfma_f32_16x16x32_bf16 v[100:103], v[210:213], v[182:185], v[100:103]
	v_mfma_f32_16x16x32_bf16 v[96:99], v[218:221], v[182:185], v[96:99]
	v_mfma_f32_16x16x32_bf16 v[84:87], v[210:213], v[194:197], v[84:87]
	v_mfma_f32_16x16x32_bf16 v[80:83], v[218:221], v[194:197], v[80:83]
	v_mfma_f32_16x16x32_bf16 v[68:71], v[210:213], v[202:205], v[68:71]
	v_mfma_f32_16x16x32_bf16 v[64:67], v[218:221], v[202:205], v[64:67]
	s_setprio 0
	s_mov_b32 m0, s31
	v_lshl_add_u64 v[222:223], s[38:39], 0, v[132:133]
	s_barrier
	ds_read_b128 v[170:173], v163 offset:16384
	ds_read_b128 v[174:177], v163 offset:17408
	ds_read_b128 v[178:181], v163 offset:18432
	ds_read_b128 v[182:185], v163 offset:19456
	ds_read_b128 v[190:193], v163 offset:20480
	ds_read_b128 v[194:197], v163 offset:21504
	ds_read_b128 v[198:201], v163 offset:22528
	ds_read_b128 v[202:205], v163 offset:23552
	global_load_lds_dwordx4 v[222:223], off
	v_lshl_add_u64 v[224:225], s[38:39], 0, v[136:137]
	s_mov_b32 m0, s45
	s_nop 0
	global_load_lds_dwordx4 v[224:225], off
	s_barrier
	s_waitcnt lgkmcnt(0)
	s_setprio 1
	s_waitcnt lgkmcnt(0)
	v_mfma_f32_16x16x32_bf16 v[60:63], v[128:131], v[170:173], v[60:63]
	v_mfma_f32_16x16x32_bf16 v[56:59], v[152:155], v[170:173], v[56:59]
	v_mfma_f32_16x16x32_bf16 v[44:47], v[128:131], v[178:181], v[44:47]
	v_mfma_f32_16x16x32_bf16 v[40:43], v[152:155], v[178:181], v[40:43]
	v_mfma_f32_16x16x32_bf16 v[28:31], v[128:131], v[190:193], v[28:31]
	v_mfma_f32_16x16x32_bf16 v[24:27], v[152:155], v[190:193], v[24:27]
	v_mfma_f32_16x16x32_bf16 v[12:15], v[128:131], v[198:201], v[12:15]
	v_mfma_f32_16x16x32_bf16 v[8:11], v[152:155], v[198:201], v[8:11]
	v_mfma_f32_16x16x32_bf16 v[60:63], v[148:151], v[174:177], v[60:63]
	v_mfma_f32_16x16x32_bf16 v[56:59], v[166:169], v[174:177], v[56:59]
	v_mfma_f32_16x16x32_bf16 v[44:47], v[148:151], v[182:185], v[44:47]
	v_mfma_f32_16x16x32_bf16 v[40:43], v[166:169], v[182:185], v[40:43]
	v_mfma_f32_16x16x32_bf16 v[28:31], v[148:151], v[194:197], v[28:31]
	v_mfma_f32_16x16x32_bf16 v[24:27], v[166:169], v[194:197], v[24:27]
	v_mfma_f32_16x16x32_bf16 v[12:15], v[148:151], v[202:205], v[12:15]
	v_mfma_f32_16x16x32_bf16 v[8:11], v[166:169], v[202:205], v[8:11]
	s_setprio 0
	s_barrier
	s_add_u32 s60, s36, 0x40000
	s_addc_u32 s61, s37, 0
	s_add_i32 s62, s53, s44
	v_lshl_add_u64 v[128:129], s[60:61], 0, v[134:135]
	s_mov_b32 m0, s62
	s_nop 0
	global_load_lds_dwordx4 v[128:129], off
	v_lshl_add_u64 v[128:129], s[60:61], 0, v[138:139]
	s_add_i32 m0, s62, 0x2000
	s_nop 0
	global_load_lds_dwordx4 v[128:129], off
	s_waitcnt vmcnt(6)
	s_barrier
	s_setprio 1
	v_mfma_f32_16x16x32_bf16 v[52:55], v[206:209], v[170:173], v[52:55]
	v_mfma_f32_16x16x32_bf16 v[48:51], v[214:217], v[170:173], v[48:51]
	v_mfma_f32_16x16x32_bf16 v[36:39], v[206:209], v[178:181], v[36:39]
	v_mfma_f32_16x16x32_bf16 v[32:35], v[214:217], v[178:181], v[32:35]
	v_mfma_f32_16x16x32_bf16 v[20:23], v[206:209], v[190:193], v[20:23]
	v_mfma_f32_16x16x32_bf16 v[16:19], v[214:217], v[190:193], v[16:19]
	v_mfma_f32_16x16x32_bf16 v[4:7], v[206:209], v[198:201], v[4:7]
	v_mfma_f32_16x16x32_bf16 v[0:3], v[214:217], v[198:201], v[0:3]
	v_mfma_f32_16x16x32_bf16 v[52:55], v[210:213], v[174:177], v[52:55]
	v_mfma_f32_16x16x32_bf16 v[48:51], v[218:221], v[174:177], v[48:51]
	v_mfma_f32_16x16x32_bf16 v[36:39], v[210:213], v[182:185], v[36:39]
	v_mfma_f32_16x16x32_bf16 v[32:35], v[218:221], v[182:185], v[32:35]
	v_mfma_f32_16x16x32_bf16 v[20:23], v[210:213], v[194:197], v[20:23]
	v_mfma_f32_16x16x32_bf16 v[16:19], v[218:221], v[194:197], v[16:19]
	v_mfma_f32_16x16x32_bf16 v[4:7], v[210:213], v[202:205], v[4:7]
	v_mfma_f32_16x16x32_bf16 v[0:3], v[218:221], v[202:205], v[0:3]
	s_setprio 0
	s_add_i32 s60, 0, 0x18000
	v_add_u32_e32 v158, s60, v160
	s_barrier
	ds_read_b128 v[128:131], v158
	ds_read_b128 v[148:151], v158 offset:1024
	ds_read_b128 v[152:155], v158 offset:2048
	ds_read_b128 v[166:169], v158 offset:3072
	s_add_u32 s38, s38, 0x40000
	s_addc_u32 s39, s39, 0
	s_mov_b32 m0, s46
	v_lshl_add_u64 v[206:207], s[38:39], 0, v[132:133]
	ds_read_b128 v[170:173], v163 offset:32768
	ds_read_b128 v[174:177], v163 offset:33792
	ds_read_b128 v[178:181], v163 offset:34816
	ds_read_b128 v[182:185], v163 offset:35840
	ds_read_b128 v[190:193], v163 offset:36864
	ds_read_b128 v[194:197], v163 offset:37888
	ds_read_b128 v[198:201], v163 offset:38912
	ds_read_b128 v[202:205], v163 offset:39936
	global_load_lds_dwordx4 v[206:207], off
	v_lshl_add_u64 v[206:207], s[38:39], 0, v[136:137]
	s_mov_b32 m0, s47
	s_nop 0
	global_load_lds_dwordx4 v[206:207], off
	s_waitcnt lgkmcnt(8)
	s_barrier
	s_waitcnt lgkmcnt(0)
	s_setprio 1
	s_waitcnt lgkmcnt(0)
	v_mfma_f32_16x16x32_bf16 v[124:127], v[128:131], v[170:173], v[124:127]
	v_mfma_f32_16x16x32_bf16 v[120:123], v[152:155], v[170:173], v[120:123]
	v_mfma_f32_16x16x32_bf16 v[108:111], v[128:131], v[178:181], v[108:111]
	v_mfma_f32_16x16x32_bf16 v[104:107], v[152:155], v[178:181], v[104:107]
	v_mfma_f32_16x16x32_bf16 v[92:95], v[128:131], v[190:193], v[92:95]
	v_mfma_f32_16x16x32_bf16 v[88:91], v[152:155], v[190:193], v[88:91]
	v_mfma_f32_16x16x32_bf16 v[76:79], v[128:131], v[198:201], v[76:79]
	v_mfma_f32_16x16x32_bf16 v[72:75], v[152:155], v[198:201], v[72:75]
	v_mfma_f32_16x16x32_bf16 v[124:127], v[148:151], v[174:177], v[124:127]
	v_mfma_f32_16x16x32_bf16 v[120:123], v[166:169], v[174:177], v[120:123]
	v_mfma_f32_16x16x32_bf16 v[108:111], v[148:151], v[182:185], v[108:111]
	v_mfma_f32_16x16x32_bf16 v[104:107], v[166:169], v[182:185], v[104:107]
	v_mfma_f32_16x16x32_bf16 v[92:95], v[148:151], v[194:197], v[92:95]
	v_mfma_f32_16x16x32_bf16 v[88:91], v[166:169], v[194:197], v[88:91]
	v_mfma_f32_16x16x32_bf16 v[76:79], v[148:151], v[202:205], v[76:79]
	v_mfma_f32_16x16x32_bf16 v[72:75], v[166:169], v[202:205], v[72:75]
	s_setprio 0
	s_barrier
	s_add_i32 s38, 0, 0x1c000
	s_add_i32 s39, s60, s44
	v_add_u32_e32 v158, s38, v160
	v_lshl_add_u64 v[156:157], v[156:157], 0, s[8:9]
	s_mov_b32 m0, s39
	ds_read_b128 v[206:209], v158
	ds_read_b128 v[210:213], v158 offset:1024
	ds_read_b128 v[214:217], v158 offset:2048
	ds_read_b128 v[218:221], v158 offset:3072
	global_load_lds_dwordx4 v[156:157], off
	v_lshl_add_u64 v[156:157], v[186:187], 0, s[8:9]
	s_add_i32 m0, s39, 0x2000
	s_nop 0
	global_load_lds_dwordx4 v[156:157], off
	s_barrier
	s_waitcnt lgkmcnt(0)
	s_setprio 1
	s_waitcnt lgkmcnt(0)
	v_mfma_f32_16x16x32_bf16 v[116:119], v[206:209], v[170:173], v[116:119]
	v_mfma_f32_16x16x32_bf16 v[112:115], v[214:217], v[170:173], v[112:115]
	v_mfma_f32_16x16x32_bf16 v[100:103], v[206:209], v[178:181], v[100:103]
	v_mfma_f32_16x16x32_bf16 v[96:99], v[214:217], v[178:181], v[96:99]
	v_mfma_f32_16x16x32_bf16 v[84:87], v[206:209], v[190:193], v[84:87]
	v_mfma_f32_16x16x32_bf16 v[80:83], v[214:217], v[190:193], v[80:83]
	v_mfma_f32_16x16x32_bf16 v[68:71], v[206:209], v[198:201], v[68:71]
	v_mfma_f32_16x16x32_bf16 v[64:67], v[214:217], v[198:201], v[64:67]
	v_mfma_f32_16x16x32_bf16 v[116:119], v[210:213], v[174:177], v[116:119]
	v_mfma_f32_16x16x32_bf16 v[112:115], v[218:221], v[174:177], v[112:115]
	v_mfma_f32_16x16x32_bf16 v[100:103], v[210:213], v[182:185], v[100:103]
	v_mfma_f32_16x16x32_bf16 v[96:99], v[218:221], v[182:185], v[96:99]
	v_mfma_f32_16x16x32_bf16 v[84:87], v[210:213], v[194:197], v[84:87]
	v_mfma_f32_16x16x32_bf16 v[80:83], v[218:221], v[194:197], v[80:83]
	v_mfma_f32_16x16x32_bf16 v[68:71], v[210:213], v[202:205], v[68:71]
	v_mfma_f32_16x16x32_bf16 v[64:67], v[218:221], v[202:205], v[64:67]
	s_setprio 0
	s_mov_b32 m0, s49
	v_lshl_add_u64 v[156:157], v[222:223], 0, s[8:9]
	s_barrier
	ds_read_b128 v[170:173], v163 offset:49152
	ds_read_b128 v[174:177], v163 offset:50176
	ds_read_b128 v[178:181], v163 offset:51200
	ds_read_b128 v[182:185], v163 offset:52224
	ds_read_b128 v[190:193], v163 offset:53248
	ds_read_b128 v[194:197], v163 offset:54272
	ds_read_b128 v[198:201], v163 offset:55296
	ds_read_b128 v[202:205], v163 offset:56320
	global_load_lds_dwordx4 v[156:157], off
	v_lshl_add_u64 v[156:157], v[224:225], 0, s[8:9]
	s_mov_b32 m0, s50
	s_nop 0
	global_load_lds_dwordx4 v[156:157], off
	s_barrier
	s_waitcnt lgkmcnt(0)
	s_setprio 1
	s_waitcnt lgkmcnt(0)
	v_mfma_f32_16x16x32_bf16 v[60:63], v[128:131], v[170:173], v[60:63]
	v_mfma_f32_16x16x32_bf16 v[56:59], v[152:155], v[170:173], v[56:59]
	v_mfma_f32_16x16x32_bf16 v[44:47], v[128:131], v[178:181], v[44:47]
	v_mfma_f32_16x16x32_bf16 v[40:43], v[152:155], v[178:181], v[40:43]
	v_mfma_f32_16x16x32_bf16 v[28:31], v[128:131], v[190:193], v[28:31]
	v_mfma_f32_16x16x32_bf16 v[24:27], v[152:155], v[190:193], v[24:27]
	v_mfma_f32_16x16x32_bf16 v[12:15], v[128:131], v[198:201], v[12:15]
	v_mfma_f32_16x16x32_bf16 v[8:11], v[152:155], v[198:201], v[8:11]
	v_mfma_f32_16x16x32_bf16 v[60:63], v[148:151], v[174:177], v[60:63]
	v_mfma_f32_16x16x32_bf16 v[56:59], v[166:169], v[174:177], v[56:59]
	v_mfma_f32_16x16x32_bf16 v[44:47], v[148:151], v[182:185], v[44:47]
	v_mfma_f32_16x16x32_bf16 v[40:43], v[166:169], v[182:185], v[40:43]
	v_mfma_f32_16x16x32_bf16 v[28:31], v[148:151], v[194:197], v[28:31]
	v_mfma_f32_16x16x32_bf16 v[24:27], v[166:169], v[194:197], v[24:27]
	v_mfma_f32_16x16x32_bf16 v[12:15], v[148:151], v[202:205], v[12:15]
	v_mfma_f32_16x16x32_bf16 v[8:11], v[166:169], v[202:205], v[8:11]
	s_setprio 0
	s_barrier
	s_add_u32 s36, s36, 0x40080
	s_addc_u32 s37, s37, 0
	s_add_i32 s38, s38, s44
	v_lshl_add_u64 v[128:129], s[36:37], 0, v[134:135]
	s_mov_b32 m0, s38
	s_nop 0
	global_load_lds_dwordx4 v[128:129], off
	v_lshl_add_u64 v[128:129], s[36:37], 0, v[138:139]
	s_add_i32 m0, s38, 0x2000
	s_nop 0
	global_load_lds_dwordx4 v[128:129], off
	s_waitcnt vmcnt(6)
	s_barrier
	s_setprio 1
	v_mfma_f32_16x16x32_bf16 v[52:55], v[206:209], v[170:173], v[52:55]
	v_mfma_f32_16x16x32_bf16 v[48:51], v[214:217], v[170:173], v[48:51]
	v_mfma_f32_16x16x32_bf16 v[36:39], v[206:209], v[178:181], v[36:39]
	v_mfma_f32_16x16x32_bf16 v[32:35], v[214:217], v[178:181], v[32:35]
	v_mfma_f32_16x16x32_bf16 v[20:23], v[206:209], v[190:193], v[20:23]
	v_mfma_f32_16x16x32_bf16 v[16:19], v[214:217], v[190:193], v[16:19]
	v_mfma_f32_16x16x32_bf16 v[4:7], v[206:209], v[198:201], v[4:7]
	v_mfma_f32_16x16x32_bf16 v[0:3], v[214:217], v[198:201], v[0:3]
	v_mfma_f32_16x16x32_bf16 v[52:55], v[210:213], v[174:177], v[52:55]
	v_mfma_f32_16x16x32_bf16 v[48:51], v[218:221], v[174:177], v[48:51]
	v_mfma_f32_16x16x32_bf16 v[36:39], v[210:213], v[182:185], v[36:39]
	v_mfma_f32_16x16x32_bf16 v[32:35], v[218:221], v[182:185], v[32:35]
	v_mfma_f32_16x16x32_bf16 v[20:23], v[210:213], v[194:197], v[20:23]
	v_mfma_f32_16x16x32_bf16 v[16:19], v[218:221], v[194:197], v[16:19]
	v_mfma_f32_16x16x32_bf16 v[4:7], v[210:213], v[202:205], v[4:7]
	v_mfma_f32_16x16x32_bf16 v[0:3], v[218:221], v[202:205], v[0:3]
	s_setprio 0
	s_add_i32 s59, s59, 2
	s_add_u32 s34, s34, 0x100
	s_addc_u32 s35, s35, 0
	s_add_u32 s57, s57, 0x100
	s_addc_u32 s58, s58, 0
	s_cmp_gt_u32 s59, 13
	s_barrier
	s_cbranch_scc0 .LBB0_286
	v_lshl_add_u32 v128, s30, 8, v159
	v_or_b32_e32 v156, 16, v128
	v_lshl_or_b32 v130, s54, 8, v161
	v_ashrrev_i32_e32 v129, 31, v128
	v_ashrrev_i32_e32 v157, 31, v156
	v_ashrrev_i32_e32 v131, 31, v130
	v_lshl_add_u64 v[152:153], v[128:129], 2, s[10:11]
	v_lshlrev_b64 v[154:155], 11, v[128:129]
	v_lshl_add_u64 v[170:171], v[156:157], 2, s[10:11]
	v_lshlrev_b64 v[186:187], 11, v[156:157]
	v_or_b32_e32 v156, 32, v128
	v_or_b32_e32 v128, 48, v128
	v_lshlrev_b64 v[148:149], 1, v[130:131]
	v_ashrrev_i32_e32 v157, 31, v156
	v_ashrrev_i32_e32 v129, 31, v128
	v_lshl_add_u64 v[150:151], s[0:1], 0, v[148:149]
	v_lshl_add_u64 v[182:183], v[156:157], 2, s[10:11]
	v_lshlrev_b64 v[198:199], 11, v[156:157]
	v_lshlrev_b64 v[156:157], 11, v[128:129]
	v_lshl_add_u64 v[130:131], v[150:151], 0, v[154:155]
	v_lshl_add_u64 v[178:179], v[150:151], 0, v[186:187]
	v_lshl_add_u64 v[190:191], v[150:151], 0, v[198:199]
	v_lshl_add_u64 v[192:193], v[128:129], 2, s[10:11]
	v_lshl_add_u64 v[128:129], v[150:151], 0, v[156:157]
	global_load_dword v200, v[152:153], off
	global_load_dwordx4 v[166:169], v[130:131], off
	global_load_dword v202, v[170:171], off
	s_nop 0
	global_load_dwordx4 v[170:173], v[130:131], off offset:256
	global_load_dwordx4 v[174:177], v[178:179], off
	s_nop 0
	global_load_dwordx4 v[178:181], v[178:179], off offset:256
	s_nop 0
	global_load_dword v204, v[182:183], off
	s_nop 0
	global_load_dwordx4 v[182:185], v[190:191], off
	global_load_dword v158, v[192:193], off
	s_nop 0
	global_load_dwordx4 v[190:193], v[190:191], off offset:256
	s_nop 0
	global_load_dwordx4 v[194:197], v[128:129], off
	s_nop 0
	global_load_dwordx4 v[128:131], v[128:129], off offset:256
	s_waitcnt vmcnt(0)
	v_pk_mul_f32 v[124:125], v[124:125], v[200:201] op_sel_hi:[1,0]
	v_pk_mul_f32 v[206:207], v[122:123], v[200:201] op_sel_hi:[1,0]
	v_pk_mul_f32 v[122:123], v[120:121], v[200:201] op_sel_hi:[1,0]
	v_lshlrev_b32_e32 v120, 16, v166
	v_and_b32_e32 v121, 0xffff0000, v166
	v_mul_f32_e32 v120, v124, v120
	v_mul_f32_e32 v121, v125, v121
	v_pk_mul_f32 v[126:127], v[126:127], v[200:201] op_sel_hi:[1,0]
	v_cvt_pk_bf16_f32 v120, v120, v121
	v_lshlrev_b32_e32 v121, 16, v167
	v_and_b32_e32 v124, 0xffff0000, v167
	v_mul_f32_e32 v121, v126, v121
	v_mul_f32_e32 v124, v127, v124
	v_cvt_pk_bf16_f32 v121, v121, v124
	v_lshlrev_b32_e32 v124, 16, v168
	v_mul_f32_e32 v122, v122, v124
	v_and_b32_e32 v124, 0xffff0000, v168
	v_mul_f32_e32 v123, v123, v124
	v_cvt_pk_bf16_f32 v122, v122, v123
	v_lshlrev_b32_e32 v123, 16, v169
	v_and_b32_e32 v124, 0xffff0000, v169
	v_mul_f32_e32 v123, v206, v123
	v_mul_f32_e32 v124, v207, v124
	v_cvt_pk_bf16_f32 v123, v123, v124
	v_lshl_add_u64 v[124:125], s[26:27], 0, v[154:155]
	v_lshl_add_u64 v[124:125], v[124:125], 0, v[148:149]
	global_store_dwordx4 v[124:125], v[120:123], off nt
	v_pk_mul_f32 v[116:117], v[116:117], v[200:201] op_sel_hi:[1,0]
	v_pk_mul_f32 v[118:119], v[118:119], v[200:201] op_sel_hi:[1,0]
	v_pk_mul_f32 v[120:121], v[114:115], v[200:201] op_sel_hi:[1,0]
	v_pk_mul_f32 v[114:115], v[112:113], v[200:201] op_sel_hi:[1,0]
	v_lshlrev_b32_e32 v112, 16, v170
	v_and_b32_e32 v113, 0xffff0000, v170
	v_mul_f32_e32 v112, v116, v112
	v_mul_f32_e32 v113, v117, v113
	v_cvt_pk_bf16_f32 v112, v112, v113
	v_lshlrev_b32_e32 v113, 16, v171
	v_and_b32_e32 v116, 0xffff0000, v171
	v_mul_f32_e32 v113, v118, v113
	v_mul_f32_e32 v116, v119, v116
	v_cvt_pk_bf16_f32 v113, v113, v116
	v_lshlrev_b32_e32 v116, 16, v172
	v_mul_f32_e32 v114, v114, v116
	v_and_b32_e32 v116, 0xffff0000, v172
	v_mul_f32_e32 v115, v115, v116
	v_cvt_pk_bf16_f32 v114, v114, v115
	v_lshlrev_b32_e32 v115, 16, v173
	v_mul_f32_e32 v115, v120, v115
	v_and_b32_e32 v116, 0xffff0000, v173
	v_mul_f32_e32 v116, v121, v116
	v_cvt_pk_bf16_f32 v115, v115, v116
	global_store_dwordx4 v[124:125], v[112:115], off offset:256 nt
	v_pk_mul_f32 v[108:109], v[108:109], v[202:203] op_sel_hi:[1,0]
	v_pk_mul_f32 v[110:111], v[110:111], v[202:203] op_sel_hi:[1,0]
	v_pk_mul_f32 v[112:113], v[106:107], v[202:203] op_sel_hi:[1,0]
	v_pk_mul_f32 v[106:107], v[104:105], v[202:203] op_sel_hi:[1,0]
	v_lshlrev_b32_e32 v104, 16, v174
	v_and_b32_e32 v105, 0xffff0000, v174
	v_mul_f32_e32 v104, v108, v104
	v_mul_f32_e32 v105, v109, v105
	v_cvt_pk_bf16_f32 v104, v104, v105
	v_lshlrev_b32_e32 v105, 16, v175
	v_and_b32_e32 v108, 0xffff0000, v175
	v_mul_f32_e32 v105, v110, v105
	v_mul_f32_e32 v108, v111, v108
	v_cvt_pk_bf16_f32 v105, v105, v108
	v_lshlrev_b32_e32 v108, 16, v176
	v_mul_f32_e32 v106, v106, v108
	v_and_b32_e32 v108, 0xffff0000, v176
	v_mul_f32_e32 v107, v107, v108
	v_cvt_pk_bf16_f32 v106, v106, v107
	v_lshlrev_b32_e32 v107, 16, v177
	v_and_b32_e32 v108, 0xffff0000, v177
	v_mul_f32_e32 v107, v112, v107
	v_mul_f32_e32 v108, v113, v108
	v_cvt_pk_bf16_f32 v107, v107, v108
	v_lshl_add_u64 v[108:109], s[26:27], 0, v[186:187]
	v_lshl_add_u64 v[108:109], v[108:109], 0, v[148:149]
	global_store_dwordx4 v[108:109], v[104:107], off nt
	v_pk_mul_f32 v[100:101], v[100:101], v[202:203] op_sel_hi:[1,0]
	v_pk_mul_f32 v[102:103], v[102:103], v[202:203] op_sel_hi:[1,0]
	v_pk_mul_f32 v[104:105], v[98:99], v[202:203] op_sel_hi:[1,0]
	v_pk_mul_f32 v[98:99], v[96:97], v[202:203] op_sel_hi:[1,0]
	v_lshlrev_b32_e32 v96, 16, v178
	v_and_b32_e32 v97, 0xffff0000, v178
	v_mul_f32_e32 v96, v100, v96
	v_mul_f32_e32 v97, v101, v97
	v_cvt_pk_bf16_f32 v96, v96, v97
	v_lshlrev_b32_e32 v97, 16, v179
	v_and_b32_e32 v100, 0xffff0000, v179
	v_mul_f32_e32 v97, v102, v97
	v_mul_f32_e32 v100, v103, v100
	v_cvt_pk_bf16_f32 v97, v97, v100
	v_lshlrev_b32_e32 v100, 16, v180
	v_mul_f32_e32 v98, v98, v100
	v_and_b32_e32 v100, 0xffff0000, v180
	v_mul_f32_e32 v99, v99, v100
	v_cvt_pk_bf16_f32 v98, v98, v99
	v_lshlrev_b32_e32 v99, 16, v181
	v_mul_f32_e32 v99, v104, v99
	v_and_b32_e32 v100, 0xffff0000, v181
	v_mul_f32_e32 v100, v105, v100
	v_cvt_pk_bf16_f32 v99, v99, v100
	global_store_dwordx4 v[108:109], v[96:99], off offset:256 nt
	v_pk_mul_f32 v[92:93], v[92:93], v[204:205] op_sel_hi:[1,0]
	v_pk_mul_f32 v[94:95], v[94:95], v[204:205] op_sel_hi:[1,0]
	v_pk_mul_f32 v[96:97], v[90:91], v[204:205] op_sel_hi:[1,0]
	v_pk_mul_f32 v[90:91], v[88:89], v[204:205] op_sel_hi:[1,0]
	v_lshlrev_b32_e32 v88, 16, v182
	v_and_b32_e32 v89, 0xffff0000, v182
	v_mul_f32_e32 v88, v92, v88
	v_mul_f32_e32 v89, v93, v89
	v_cvt_pk_bf16_f32 v88, v88, v89
	v_lshlrev_b32_e32 v89, 16, v183
	v_and_b32_e32 v92, 0xffff0000, v183
	v_mul_f32_e32 v89, v94, v89
	v_mul_f32_e32 v92, v95, v92
	v_cvt_pk_bf16_f32 v89, v89, v92
	v_lshlrev_b32_e32 v92, 16, v184
	v_mul_f32_e32 v90, v90, v92
	v_and_b32_e32 v92, 0xffff0000, v184
	v_mul_f32_e32 v91, v91, v92
	v_cvt_pk_bf16_f32 v90, v90, v91
	v_lshlrev_b32_e32 v91, 16, v185
	v_and_b32_e32 v92, 0xffff0000, v185
	v_mul_f32_e32 v91, v96, v91
	v_mul_f32_e32 v92, v97, v92
	v_cvt_pk_bf16_f32 v91, v91, v92
	v_lshl_add_u64 v[92:93], s[26:27], 0, v[198:199]
	v_lshl_add_u64 v[92:93], v[92:93], 0, v[148:149]
	global_store_dwordx4 v[92:93], v[88:91], off nt
	v_pk_mul_f32 v[84:85], v[84:85], v[204:205] op_sel_hi:[1,0]
	v_pk_mul_f32 v[86:87], v[86:87], v[204:205] op_sel_hi:[1,0]
	v_pk_mul_f32 v[88:89], v[82:83], v[204:205] op_sel_hi:[1,0]
	v_pk_mul_f32 v[82:83], v[80:81], v[204:205] op_sel_hi:[1,0]
	v_lshlrev_b32_e32 v80, 16, v190
	v_and_b32_e32 v81, 0xffff0000, v190
	v_mul_f32_e32 v80, v84, v80
	v_mul_f32_e32 v81, v85, v81
	v_cvt_pk_bf16_f32 v80, v80, v81
	v_lshlrev_b32_e32 v81, 16, v191
	v_and_b32_e32 v84, 0xffff0000, v191
	v_mul_f32_e32 v81, v86, v81
	v_mul_f32_e32 v84, v87, v84
	v_cvt_pk_bf16_f32 v81, v81, v84
	v_lshlrev_b32_e32 v84, 16, v192
	v_mul_f32_e32 v82, v82, v84
	v_and_b32_e32 v84, 0xffff0000, v192
	v_mul_f32_e32 v83, v83, v84
	v_cvt_pk_bf16_f32 v82, v82, v83
	v_lshlrev_b32_e32 v83, 16, v193
	v_mul_f32_e32 v83, v88, v83
	v_and_b32_e32 v84, 0xffff0000, v193
	v_mul_f32_e32 v84, v89, v84
	v_cvt_pk_bf16_f32 v83, v83, v84
	global_store_dwordx4 v[92:93], v[80:83], off offset:256 nt
	v_pk_mul_f32 v[76:77], v[76:77], v[158:159] op_sel_hi:[1,0]
	v_pk_mul_f32 v[78:79], v[78:79], v[158:159] op_sel_hi:[1,0]
	v_pk_mul_f32 v[80:81], v[74:75], v[158:159] op_sel_hi:[1,0]
	v_pk_mul_f32 v[74:75], v[72:73], v[158:159] op_sel_hi:[1,0]
	v_lshlrev_b32_e32 v72, 16, v194
	v_and_b32_e32 v73, 0xffff0000, v194
	v_mul_f32_e32 v72, v76, v72
	v_mul_f32_e32 v73, v77, v73
	v_cvt_pk_bf16_f32 v72, v72, v73
	v_lshlrev_b32_e32 v73, 16, v195
	v_and_b32_e32 v76, 0xffff0000, v195
	v_mul_f32_e32 v73, v78, v73
	v_mul_f32_e32 v76, v79, v76
	v_cvt_pk_bf16_f32 v73, v73, v76
	v_lshlrev_b32_e32 v76, 16, v196
	v_mul_f32_e32 v74, v74, v76
	v_and_b32_e32 v76, 0xffff0000, v196
	v_mul_f32_e32 v75, v75, v76
	v_cvt_pk_bf16_f32 v74, v74, v75
	v_lshlrev_b32_e32 v75, 16, v197
	v_and_b32_e32 v76, 0xffff0000, v197
	v_mul_f32_e32 v75, v80, v75
	v_mul_f32_e32 v76, v81, v76
	v_cvt_pk_bf16_f32 v75, v75, v76
	v_lshl_add_u64 v[76:77], s[26:27], 0, v[156:157]
	v_lshl_add_u64 v[76:77], v[76:77], 0, v[148:149]
	global_store_dwordx4 v[76:77], v[72:75], off nt
	v_pk_mul_f32 v[68:69], v[68:69], v[158:159] op_sel_hi:[1,0]
	v_pk_mul_f32 v[70:71], v[70:71], v[158:159] op_sel_hi:[1,0]
	v_pk_mul_f32 v[72:73], v[66:67], v[158:159] op_sel_hi:[1,0]
	v_pk_mul_f32 v[66:67], v[64:65], v[158:159] op_sel_hi:[1,0]
	v_lshlrev_b32_e32 v64, 16, v128
	v_and_b32_e32 v65, 0xffff0000, v128
	v_mul_f32_e32 v64, v68, v64
	v_mul_f32_e32 v65, v69, v65
	v_cvt_pk_bf16_f32 v64, v64, v65
	v_lshlrev_b32_e32 v65, 16, v129
	v_and_b32_e32 v68, 0xffff0000, v129
	v_mul_f32_e32 v65, v70, v65
	v_mul_f32_e32 v68, v71, v68
	v_cvt_pk_bf16_f32 v65, v65, v68
	v_lshlrev_b32_e32 v68, 16, v130
	v_mul_f32_e32 v66, v66, v68
	v_and_b32_e32 v68, 0xffff0000, v130
	v_mul_f32_e32 v67, v67, v68
	v_cvt_pk_bf16_f32 v66, v66, v67
	v_lshlrev_b32_e32 v67, 16, v131
	v_mul_f32_e32 v67, v72, v67
	v_and_b32_e32 v68, 0xffff0000, v131
	v_mul_f32_e32 v68, v73, v68
	v_cvt_pk_bf16_f32 v67, v67, v68
	v_lshl_add_u64 v[100:101], v[154:155], 0, s[6:7]
	v_lshl_add_u64 v[102:103], v[154:155], 0, s[12:13]
	v_lshl_add_u64 v[104:105], v[154:155], 0, s[14:15]
	global_store_dwordx4 v[76:77], v[64:67], off offset:256 nt
	v_lshl_add_u64 v[92:93], v[150:151], 0, v[104:105]
	v_lshl_add_u64 v[70:71], v[154:155], 0, s[18:19]
	v_lshl_add_u64 v[64:65], v[150:151], 0, v[100:101]
	v_lshl_add_u64 v[66:67], v[150:151], 0, v[102:103]
	global_load_dword v106, v[152:153], off offset:512
	global_load_dword v108, v[152:153], off offset:576
	global_load_dword v110, v[152:153], off offset:640
	global_load_dword v68, v[152:153], off offset:704
	v_lshl_add_u64 v[112:113], v[150:151], 0, v[70:71]
	global_load_dwordx4 v[72:75], v[64:65], off
	global_load_dwordx4 v[76:79], v[64:65], off offset:256
	global_load_dwordx4 v[80:83], v[66:67], off
	global_load_dwordx4 v[84:87], v[66:67], off offset:256
	global_load_dwordx4 v[88:91], v[92:93], off
	s_nop 0
	global_load_dwordx4 v[92:95], v[92:93], off offset:256
	s_nop 0
	global_load_dwordx4 v[96:99], v[112:113], off
	global_load_dwordx4 v[64:67], v[112:113], off offset:256
	s_waitcnt vmcnt(0)
	v_pk_mul_f32 v[60:61], v[60:61], v[106:107] op_sel_hi:[1,0]
	v_pk_mul_f32 v[112:113], v[58:59], v[106:107] op_sel_hi:[1,0]
	v_pk_mul_f32 v[58:59], v[56:57], v[106:107] op_sel_hi:[1,0]
	v_lshlrev_b32_e32 v56, 16, v72
	v_and_b32_e32 v57, 0xffff0000, v72
	v_mul_f32_e32 v56, v60, v56
	v_mul_f32_e32 v57, v61, v57
	v_pk_mul_f32 v[62:63], v[62:63], v[106:107] op_sel_hi:[1,0]
	v_cvt_pk_bf16_f32 v56, v56, v57
	v_lshlrev_b32_e32 v57, 16, v73
	v_and_b32_e32 v60, 0xffff0000, v73
	v_mul_f32_e32 v57, v62, v57
	v_mul_f32_e32 v60, v63, v60
	v_cvt_pk_bf16_f32 v57, v57, v60
	v_lshlrev_b32_e32 v60, 16, v74
	v_mul_f32_e32 v58, v58, v60
	v_and_b32_e32 v60, 0xffff0000, v74
	v_mul_f32_e32 v59, v59, v60
	v_cvt_pk_bf16_f32 v58, v58, v59
	v_lshlrev_b32_e32 v59, 16, v75
	v_and_b32_e32 v60, 0xffff0000, v75
	v_mul_f32_e32 v59, v112, v59
	v_mul_f32_e32 v60, v113, v60
	v_cvt_pk_bf16_f32 v59, v59, v60
	v_lshl_add_u64 v[60:61], s[26:27], 0, v[100:101]
	v_lshl_add_u64 v[60:61], v[60:61], 0, v[148:149]
	global_store_dwordx4 v[60:61], v[56:59], off nt
	v_pk_mul_f32 v[52:53], v[52:53], v[106:107] op_sel_hi:[1,0]
	v_pk_mul_f32 v[54:55], v[54:55], v[106:107] op_sel_hi:[1,0]
	v_pk_mul_f32 v[56:57], v[50:51], v[106:107] op_sel_hi:[1,0]
	v_pk_mul_f32 v[50:51], v[48:49], v[106:107] op_sel_hi:[1,0]
	v_lshlrev_b32_e32 v48, 16, v76
	v_and_b32_e32 v49, 0xffff0000, v76
	v_mul_f32_e32 v48, v52, v48
	v_mul_f32_e32 v49, v53, v49
	v_cvt_pk_bf16_f32 v48, v48, v49
	v_lshlrev_b32_e32 v49, 16, v77
	v_and_b32_e32 v52, 0xffff0000, v77
	v_mul_f32_e32 v49, v54, v49
	v_mul_f32_e32 v52, v55, v52
	v_cvt_pk_bf16_f32 v49, v49, v52
	v_lshlrev_b32_e32 v52, 16, v78
	v_mul_f32_e32 v50, v50, v52
	v_and_b32_e32 v52, 0xffff0000, v78
	v_mul_f32_e32 v51, v51, v52
	v_cvt_pk_bf16_f32 v50, v50, v51
	v_lshlrev_b32_e32 v51, 16, v79
	v_mul_f32_e32 v51, v56, v51
	v_and_b32_e32 v52, 0xffff0000, v79
	v_mul_f32_e32 v52, v57, v52
	v_cvt_pk_bf16_f32 v51, v51, v52
	global_store_dwordx4 v[60:61], v[48:51], off offset:256 nt
	v_pk_mul_f32 v[44:45], v[44:45], v[108:109] op_sel_hi:[1,0]
	v_pk_mul_f32 v[46:47], v[46:47], v[108:109] op_sel_hi:[1,0]
	v_pk_mul_f32 v[48:49], v[42:43], v[108:109] op_sel_hi:[1,0]
	v_pk_mul_f32 v[42:43], v[40:41], v[108:109] op_sel_hi:[1,0]
	v_lshlrev_b32_e32 v40, 16, v80
	v_and_b32_e32 v41, 0xffff0000, v80
	v_mul_f32_e32 v40, v44, v40
	v_mul_f32_e32 v41, v45, v41
	v_cvt_pk_bf16_f32 v40, v40, v41
	v_lshlrev_b32_e32 v41, 16, v81
	v_and_b32_e32 v44, 0xffff0000, v81
	v_mul_f32_e32 v41, v46, v41
	v_mul_f32_e32 v44, v47, v44
	v_cvt_pk_bf16_f32 v41, v41, v44
	v_lshlrev_b32_e32 v44, 16, v82
	v_mul_f32_e32 v42, v42, v44
	v_and_b32_e32 v44, 0xffff0000, v82
	v_mul_f32_e32 v43, v43, v44
	v_cvt_pk_bf16_f32 v42, v42, v43
	v_lshlrev_b32_e32 v43, 16, v83
	v_and_b32_e32 v44, 0xffff0000, v83
	v_mul_f32_e32 v43, v48, v43
	v_mul_f32_e32 v44, v49, v44
	v_cvt_pk_bf16_f32 v43, v43, v44
	v_lshl_add_u64 v[44:45], s[26:27], 0, v[102:103]
	v_lshl_add_u64 v[44:45], v[44:45], 0, v[148:149]
	global_store_dwordx4 v[44:45], v[40:43], off nt
	v_pk_mul_f32 v[36:37], v[36:37], v[108:109] op_sel_hi:[1,0]
	v_pk_mul_f32 v[38:39], v[38:39], v[108:109] op_sel_hi:[1,0]
	v_pk_mul_f32 v[40:41], v[34:35], v[108:109] op_sel_hi:[1,0]
	v_pk_mul_f32 v[34:35], v[32:33], v[108:109] op_sel_hi:[1,0]
	v_lshlrev_b32_e32 v32, 16, v84
	v_and_b32_e32 v33, 0xffff0000, v84
	v_mul_f32_e32 v32, v36, v32
	v_mul_f32_e32 v33, v37, v33
	v_cvt_pk_bf16_f32 v32, v32, v33
	v_lshlrev_b32_e32 v33, 16, v85
	v_and_b32_e32 v36, 0xffff0000, v85
	v_mul_f32_e32 v33, v38, v33
	v_mul_f32_e32 v36, v39, v36
	v_cvt_pk_bf16_f32 v33, v33, v36
	v_lshlrev_b32_e32 v36, 16, v86
	v_mul_f32_e32 v34, v34, v36
	v_and_b32_e32 v36, 0xffff0000, v86
	v_mul_f32_e32 v35, v35, v36
	v_cvt_pk_bf16_f32 v34, v34, v35
	v_lshlrev_b32_e32 v35, 16, v87
	v_mul_f32_e32 v35, v40, v35
	v_and_b32_e32 v36, 0xffff0000, v87
	v_mul_f32_e32 v36, v41, v36
	v_cvt_pk_bf16_f32 v35, v35, v36
	global_store_dwordx4 v[44:45], v[32:35], off offset:256 nt
	v_pk_mul_f32 v[28:29], v[28:29], v[110:111] op_sel_hi:[1,0]
	v_pk_mul_f32 v[30:31], v[30:31], v[110:111] op_sel_hi:[1,0]
	v_pk_mul_f32 v[32:33], v[26:27], v[110:111] op_sel_hi:[1,0]
	v_pk_mul_f32 v[26:27], v[24:25], v[110:111] op_sel_hi:[1,0]
	v_lshlrev_b32_e32 v24, 16, v88
	v_and_b32_e32 v25, 0xffff0000, v88
	v_mul_f32_e32 v24, v28, v24
	v_mul_f32_e32 v25, v29, v25
	v_cvt_pk_bf16_f32 v24, v24, v25
	v_lshlrev_b32_e32 v25, 16, v89
	v_and_b32_e32 v28, 0xffff0000, v89
	v_mul_f32_e32 v25, v30, v25
	v_mul_f32_e32 v28, v31, v28
	v_cvt_pk_bf16_f32 v25, v25, v28
	v_lshlrev_b32_e32 v28, 16, v90
	v_mul_f32_e32 v26, v26, v28
	v_and_b32_e32 v28, 0xffff0000, v90
	v_mul_f32_e32 v27, v27, v28
	v_cvt_pk_bf16_f32 v26, v26, v27
	v_lshlrev_b32_e32 v27, 16, v91
	v_and_b32_e32 v28, 0xffff0000, v91
	v_mul_f32_e32 v27, v32, v27
	v_mul_f32_e32 v28, v33, v28
	v_cvt_pk_bf16_f32 v27, v27, v28
	v_lshl_add_u64 v[28:29], s[26:27], 0, v[104:105]
	v_lshl_add_u64 v[28:29], v[28:29], 0, v[148:149]
	global_store_dwordx4 v[28:29], v[24:27], off nt
	v_pk_mul_f32 v[20:21], v[20:21], v[110:111] op_sel_hi:[1,0]
	v_pk_mul_f32 v[22:23], v[22:23], v[110:111] op_sel_hi:[1,0]
	v_pk_mul_f32 v[24:25], v[18:19], v[110:111] op_sel_hi:[1,0]
	v_pk_mul_f32 v[18:19], v[16:17], v[110:111] op_sel_hi:[1,0]
	v_lshlrev_b32_e32 v16, 16, v92
	v_and_b32_e32 v17, 0xffff0000, v92
	v_mul_f32_e32 v16, v20, v16
	v_mul_f32_e32 v17, v21, v17
	v_cvt_pk_bf16_f32 v16, v16, v17
	v_lshlrev_b32_e32 v17, 16, v93
	v_and_b32_e32 v20, 0xffff0000, v93
	v_mul_f32_e32 v17, v22, v17
	v_mul_f32_e32 v20, v23, v20
	v_cvt_pk_bf16_f32 v17, v17, v20
	v_lshlrev_b32_e32 v20, 16, v94
	v_mul_f32_e32 v18, v18, v20
	v_and_b32_e32 v20, 0xffff0000, v94
	v_mul_f32_e32 v19, v19, v20
	v_cvt_pk_bf16_f32 v18, v18, v19
	v_lshlrev_b32_e32 v19, 16, v95
	v_mul_f32_e32 v19, v24, v19
	v_and_b32_e32 v20, 0xffff0000, v95
	v_mul_f32_e32 v20, v25, v20
	v_cvt_pk_bf16_f32 v19, v19, v20
	global_store_dwordx4 v[28:29], v[16:19], off offset:256 nt
	v_pk_mul_f32 v[12:13], v[12:13], v[68:69] op_sel_hi:[1,0]
	v_pk_mul_f32 v[14:15], v[14:15], v[68:69] op_sel_hi:[1,0]
	v_pk_mul_f32 v[16:17], v[10:11], v[68:69] op_sel_hi:[1,0]
	v_pk_mul_f32 v[10:11], v[8:9], v[68:69] op_sel_hi:[1,0]
	v_lshlrev_b32_e32 v8, 16, v96
	v_and_b32_e32 v9, 0xffff0000, v96
	v_mul_f32_e32 v8, v12, v8
	v_mul_f32_e32 v9, v13, v9
	v_cvt_pk_bf16_f32 v8, v8, v9
	v_lshlrev_b32_e32 v9, 16, v97
	v_and_b32_e32 v12, 0xffff0000, v97
	v_mul_f32_e32 v9, v14, v9
	v_mul_f32_e32 v12, v15, v12
	v_cvt_pk_bf16_f32 v9, v9, v12
	v_lshlrev_b32_e32 v12, 16, v98
	v_mul_f32_e32 v10, v10, v12
	v_and_b32_e32 v12, 0xffff0000, v98
	v_mul_f32_e32 v11, v11, v12
	v_cvt_pk_bf16_f32 v10, v10, v11
	v_lshlrev_b32_e32 v11, 16, v99
	v_and_b32_e32 v12, 0xffff0000, v99
	v_mul_f32_e32 v11, v16, v11
	v_mul_f32_e32 v12, v17, v12
	v_cvt_pk_bf16_f32 v11, v11, v12
	v_lshl_add_u64 v[12:13], s[26:27], 0, v[70:71]
	v_lshl_add_u64 v[12:13], v[12:13], 0, v[148:149]
	global_store_dwordx4 v[12:13], v[8:11], off nt
	v_pk_mul_f32 v[4:5], v[4:5], v[68:69] op_sel_hi:[1,0]
	v_pk_mul_f32 v[6:7], v[6:7], v[68:69] op_sel_hi:[1,0]
	v_pk_mul_f32 v[8:9], v[2:3], v[68:69] op_sel_hi:[1,0]
	v_pk_mul_f32 v[2:3], v[0:1], v[68:69] op_sel_hi:[1,0]
	v_lshlrev_b32_e32 v0, 16, v64
	v_and_b32_e32 v1, 0xffff0000, v64
	v_mul_f32_e32 v0, v4, v0
	v_mul_f32_e32 v1, v5, v1
	v_cvt_pk_bf16_f32 v0, v0, v1
	v_lshlrev_b32_e32 v1, 16, v65
	v_and_b32_e32 v4, 0xffff0000, v65
	v_mul_f32_e32 v1, v6, v1
	v_mul_f32_e32 v4, v7, v4
	v_cvt_pk_bf16_f32 v1, v1, v4
	v_lshlrev_b32_e32 v4, 16, v66
	v_mul_f32_e32 v2, v2, v4
	v_and_b32_e32 v4, 0xffff0000, v66
	v_mul_f32_e32 v3, v3, v4
	v_cvt_pk_bf16_f32 v2, v2, v3
	v_lshlrev_b32_e32 v3, 16, v67
	v_mul_f32_e32 v3, v8, v3
	v_and_b32_e32 v4, 0xffff0000, v67
	s_and_b64 vcc, exec, s[2:3]
	s_mov_b32 s54, s20
	s_mov_b32 s30, s22
	s_mov_b64 s[36:37], s[28:29]
	s_mov_b64 s[34:35], s[24:25]
	v_mul_f32_e32 v4, v9, v4
	v_cvt_pk_bf16_f32 v3, v3, v4
	global_store_dwordx4 v[12:13], v[0:3], off offset:256 nt
	s_cbranch_vccz .LBB0_279
	s_waitcnt vmcnt(0)
	s_cmpk_gt_u32 s40, 0xff
	s_cbranch_scc1 .LBB0_290
	s_barrier

.LBB0_364:
	ds_read_b128 v[128:131], v208
	ds_read_b128 v[132:135], v208 offset:1024
	ds_read_b128 v[136:139], v208 offset:2048
	ds_read_b128 v[140:143], v208 offset:3072
	s_add_u32 s24, s22, 0xfffc0080
	s_addc_u32 s25, s23, -1
	s_cmp_eq_u32 s51, 12
	s_cselect_b32 s29, s13, s25
	s_cselect_b32 s28, s21, s24
	s_cselect_b32 s25, s11, s50
	s_cselect_b32 s24, s48, s49
	v_lshl_add_u64 v[194:195], s[22:23], 0, v[184:185]
	s_add_i32 m0, s36, 0xc000
	ds_read_b128 v[144:147], v209
	ds_read_b128 v[148:151], v209 offset:1024
	ds_read_b128 v[152:155], v209 offset:2048
	ds_read_b128 v[156:159], v209 offset:3072
	ds_read_b128 v[160:163], v209 offset:4096
	ds_read_b128 v[164:167], v209 offset:5120
	ds_read_b128 v[168:171], v209 offset:6144
	ds_read_b128 v[172:175], v209 offset:7168
	global_load_lds_dwordx4 v[194:195], off
	v_lshl_add_u64 v[194:195], s[22:23], 0, v[186:187]
	s_add_i32 m0, s36, 0xe000
	s_nop 0
	global_load_lds_dwordx4 v[194:195], off
	s_waitcnt lgkmcnt(8)
	s_barrier
	s_waitcnt lgkmcnt(0)
	s_setprio 1
	s_waitcnt lgkmcnt(0)
	v_mfma_f32_16x16x32_bf16 v[124:127], v[128:131], v[144:147], v[124:127]
	v_mfma_f32_16x16x32_bf16 v[120:123], v[136:139], v[144:147], v[120:123]
	v_mfma_f32_16x16x32_bf16 v[108:111], v[128:131], v[152:155], v[108:111]
	v_mfma_f32_16x16x32_bf16 v[104:107], v[136:139], v[152:155], v[104:107]
	v_mfma_f32_16x16x32_bf16 v[92:95], v[128:131], v[160:163], v[92:95]
	v_mfma_f32_16x16x32_bf16 v[88:91], v[136:139], v[160:163], v[88:91]
	v_mfma_f32_16x16x32_bf16 v[76:79], v[128:131], v[168:171], v[76:79]
	v_mfma_f32_16x16x32_bf16 v[72:75], v[136:139], v[168:171], v[72:75]
	v_mfma_f32_16x16x32_bf16 v[124:127], v[132:135], v[148:151], v[124:127]
	v_mfma_f32_16x16x32_bf16 v[120:123], v[140:143], v[148:151], v[120:123]
	v_mfma_f32_16x16x32_bf16 v[108:111], v[132:135], v[156:159], v[108:111]
	v_mfma_f32_16x16x32_bf16 v[104:107], v[140:143], v[156:159], v[104:107]
	v_mfma_f32_16x16x32_bf16 v[92:95], v[132:135], v[164:167], v[92:95]
	v_mfma_f32_16x16x32_bf16 v[88:91], v[140:143], v[164:167], v[88:91]
	v_mfma_f32_16x16x32_bf16 v[76:79], v[132:135], v[172:175], v[76:79]
	v_mfma_f32_16x16x32_bf16 v[72:75], v[140:143], v[172:175], v[72:75]
	s_setprio 0
	s_barrier
	s_add_i32 s52, s45, s35
	v_lshl_add_u64 v[216:217], s[24:25], 0, v[178:179]
	s_mov_b32 m0, s52
	ds_read_b128 v[194:197], v210
	ds_read_b128 v[198:201], v210 offset:1024
	ds_read_b128 v[202:205], v210 offset:2048
	ds_read_b128 v[212:215], v210 offset:3072
	global_load_lds_dwordx4 v[216:217], off
	v_lshl_add_u64 v[218:219], s[24:25], 0, v[182:183]
	s_add_i32 m0, s52, 0x2000
	s_nop 0
	global_load_lds_dwordx4 v[218:219], off
	s_barrier
	s_waitcnt lgkmcnt(0)
	s_setprio 1
	s_waitcnt lgkmcnt(0)
	v_mfma_f32_16x16x32_bf16 v[116:119], v[194:197], v[144:147], v[116:119]
	v_mfma_f32_16x16x32_bf16 v[112:115], v[202:205], v[144:147], v[112:115]
	v_mfma_f32_16x16x32_bf16 v[100:103], v[194:197], v[152:155], v[100:103]
	v_mfma_f32_16x16x32_bf16 v[96:99], v[202:205], v[152:155], v[96:99]
	v_mfma_f32_16x16x32_bf16 v[84:87], v[194:197], v[160:163], v[84:87]
	v_mfma_f32_16x16x32_bf16 v[80:83], v[202:205], v[160:163], v[80:83]
	v_mfma_f32_16x16x32_bf16 v[68:71], v[194:197], v[168:171], v[68:71]
	v_mfma_f32_16x16x32_bf16 v[64:67], v[202:205], v[168:171], v[64:67]
	v_mfma_f32_16x16x32_bf16 v[116:119], v[198:201], v[148:151], v[116:119]
	v_mfma_f32_16x16x32_bf16 v[112:115], v[212:215], v[148:151], v[112:115]
	v_mfma_f32_16x16x32_bf16 v[100:103], v[198:201], v[156:159], v[100:103]
	v_mfma_f32_16x16x32_bf16 v[96:99], v[212:215], v[156:159], v[96:99]
	v_mfma_f32_16x16x32_bf16 v[84:87], v[198:201], v[164:167], v[84:87]
	v_mfma_f32_16x16x32_bf16 v[80:83], v[212:215], v[164:167], v[80:83]
	v_mfma_f32_16x16x32_bf16 v[68:71], v[198:201], v[172:175], v[68:71]
	v_mfma_f32_16x16x32_bf16 v[64:67], v[212:215], v[172:175], v[64:67]
	s_setprio 0
	s_mov_b32 m0, s36
	v_lshl_add_u64 v[220:221], s[28:29], 0, v[176:177]
	s_barrier
	ds_read_b128 v[144:147], v209 offset:16384
	ds_read_b128 v[148:151], v209 offset:17408
	ds_read_b128 v[152:155], v209 offset:18432
	ds_read_b128 v[156:159], v209 offset:19456
	ds_read_b128 v[160:163], v209 offset:20480
	ds_read_b128 v[164:167], v209 offset:21504
	ds_read_b128 v[168:171], v209 offset:22528
	ds_read_b128 v[172:175], v209 offset:23552
	global_load_lds_dwordx4 v[220:221], off
	v_lshl_add_u64 v[222:223], s[28:29], 0, v[180:181]
	s_mov_b32 m0, s37
	s_nop 0
	global_load_lds_dwordx4 v[222:223], off
	s_barrier
	s_waitcnt lgkmcnt(0)
	s_setprio 1
	s_waitcnt lgkmcnt(0)
	v_mfma_f32_16x16x32_bf16 v[60:63], v[128:131], v[144:147], v[60:63]
	v_mfma_f32_16x16x32_bf16 v[56:59], v[136:139], v[144:147], v[56:59]
	v_mfma_f32_16x16x32_bf16 v[44:47], v[128:131], v[152:155], v[44:47]
	v_mfma_f32_16x16x32_bf16 v[40:43], v[136:139], v[152:155], v[40:43]
	v_mfma_f32_16x16x32_bf16 v[28:31], v[128:131], v[160:163], v[28:31]
	v_mfma_f32_16x16x32_bf16 v[24:27], v[136:139], v[160:163], v[24:27]
	v_mfma_f32_16x16x32_bf16 v[12:15], v[128:131], v[168:171], v[12:15]
	v_mfma_f32_16x16x32_bf16 v[8:11], v[136:139], v[168:171], v[8:11]
	v_mfma_f32_16x16x32_bf16 v[60:63], v[132:135], v[148:151], v[60:63]
	v_mfma_f32_16x16x32_bf16 v[56:59], v[140:143], v[148:151], v[56:59]
	v_mfma_f32_16x16x32_bf16 v[44:47], v[132:135], v[156:159], v[44:47]
	v_mfma_f32_16x16x32_bf16 v[40:43], v[140:143], v[156:159], v[40:43]
	v_mfma_f32_16x16x32_bf16 v[28:31], v[132:135], v[164:167], v[28:31]
	v_mfma_f32_16x16x32_bf16 v[24:27], v[140:143], v[164:167], v[24:27]
	v_mfma_f32_16x16x32_bf16 v[12:15], v[132:135], v[172:175], v[12:15]
	v_mfma_f32_16x16x32_bf16 v[8:11], v[140:143], v[172:175], v[8:11]
	s_setprio 0
	s_barrier
	s_add_u32 s52, s24, 0x40000
	s_addc_u32 s53, s25, 0
	s_add_i32 s54, s46, s35
	v_lshl_add_u64 v[128:129], s[52:53], 0, v[178:179]
	s_mov_b32 m0, s54
	s_nop 0
	global_load_lds_dwordx4 v[128:129], off
	v_lshl_add_u64 v[128:129], s[52:53], 0, v[182:183]
	s_add_i32 m0, s54, 0x2000
	s_nop 0
	global_load_lds_dwordx4 v[128:129], off
	s_waitcnt vmcnt(6)
	s_barrier
	s_setprio 1
	v_mfma_f32_16x16x32_bf16 v[52:55], v[194:197], v[144:147], v[52:55]
	v_mfma_f32_16x16x32_bf16 v[48:51], v[202:205], v[144:147], v[48:51]
	v_mfma_f32_16x16x32_bf16 v[36:39], v[194:197], v[152:155], v[36:39]
	v_mfma_f32_16x16x32_bf16 v[32:35], v[202:205], v[152:155], v[32:35]
	v_mfma_f32_16x16x32_bf16 v[20:23], v[194:197], v[160:163], v[20:23]
	v_mfma_f32_16x16x32_bf16 v[16:19], v[202:205], v[160:163], v[16:19]
	v_mfma_f32_16x16x32_bf16 v[4:7], v[194:197], v[168:171], v[4:7]
	v_mfma_f32_16x16x32_bf16 v[0:3], v[202:205], v[168:171], v[0:3]
	v_mfma_f32_16x16x32_bf16 v[52:55], v[198:201], v[148:151], v[52:55]
	v_mfma_f32_16x16x32_bf16 v[48:51], v[212:215], v[148:151], v[48:51]
	v_mfma_f32_16x16x32_bf16 v[36:39], v[198:201], v[156:159], v[36:39]
	v_mfma_f32_16x16x32_bf16 v[32:35], v[212:215], v[156:159], v[32:35]
	v_mfma_f32_16x16x32_bf16 v[20:23], v[198:201], v[164:167], v[20:23]
	v_mfma_f32_16x16x32_bf16 v[16:19], v[212:215], v[164:167], v[16:19]
	v_mfma_f32_16x16x32_bf16 v[4:7], v[198:201], v[172:175], v[4:7]
	v_mfma_f32_16x16x32_bf16 v[0:3], v[212:215], v[172:175], v[0:3]
	s_setprio 0
	s_add_i32 s52, 0, 0x18000
	v_add_u32_e32 v140, s52, v206
	s_barrier
	ds_read_b128 v[128:131], v140
	ds_read_b128 v[132:135], v140 offset:1024
	ds_read_b128 v[136:139], v140 offset:2048
	ds_read_b128 v[140:143], v140 offset:3072
	s_add_u32 s28, s28, 0x40000
	s_addc_u32 s29, s29, 0
	s_mov_b32 m0, s38
	v_lshl_add_u64 v[194:195], s[28:29], 0, v[176:177]
	ds_read_b128 v[144:147], v209 offset:32768
	ds_read_b128 v[148:151], v209 offset:33792
	ds_read_b128 v[152:155], v209 offset:34816
	ds_read_b128 v[156:159], v209 offset:35840
	ds_read_b128 v[160:163], v209 offset:36864
	ds_read_b128 v[164:167], v209 offset:37888
	ds_read_b128 v[168:171], v209 offset:38912
	ds_read_b128 v[172:175], v209 offset:39936
	global_load_lds_dwordx4 v[194:195], off
	v_lshl_add_u64 v[194:195], s[28:29], 0, v[180:181]
	s_mov_b32 m0, s39
	s_nop 0
	global_load_lds_dwordx4 v[194:195], off
	s_waitcnt lgkmcnt(8)
	s_barrier
	s_waitcnt lgkmcnt(0)
	s_setprio 1
	s_waitcnt lgkmcnt(0)
	v_mfma_f32_16x16x32_bf16 v[124:127], v[128:131], v[144:147], v[124:127]
	v_mfma_f32_16x16x32_bf16 v[120:123], v[136:139], v[144:147], v[120:123]
	v_mfma_f32_16x16x32_bf16 v[108:111], v[128:131], v[152:155], v[108:111]
	v_mfma_f32_16x16x32_bf16 v[104:107], v[136:139], v[152:155], v[104:107]
	v_mfma_f32_16x16x32_bf16 v[92:95], v[128:131], v[160:163], v[92:95]
	v_mfma_f32_16x16x32_bf16 v[88:91], v[136:139], v[160:163], v[88:91]
	v_mfma_f32_16x16x32_bf16 v[76:79], v[128:131], v[168:171], v[76:79]
	v_mfma_f32_16x16x32_bf16 v[72:75], v[136:139], v[168:171], v[72:75]
	v_mfma_f32_16x16x32_bf16 v[124:127], v[132:135], v[148:151], v[124:127]
	v_mfma_f32_16x16x32_bf16 v[120:123], v[140:143], v[148:151], v[120:123]
	v_mfma_f32_16x16x32_bf16 v[108:111], v[132:135], v[156:159], v[108:111]
	v_mfma_f32_16x16x32_bf16 v[104:107], v[140:143], v[156:159], v[104:107]
	v_mfma_f32_16x16x32_bf16 v[92:95], v[132:135], v[164:167], v[92:95]
	v_mfma_f32_16x16x32_bf16 v[88:91], v[140:143], v[164:167], v[88:91]
	v_mfma_f32_16x16x32_bf16 v[76:79], v[132:135], v[172:175], v[76:79]
	v_mfma_f32_16x16x32_bf16 v[72:75], v[140:143], v[172:175], v[72:75]
	s_setprio 0
	s_barrier
	s_add_i32 s28, 0, 0x1c000
	s_add_i32 s29, s52, s35
	v_add_u32_e32 v212, s28, v206
	v_lshl_add_u64 v[216:217], v[216:217], 0, s[8:9]
	s_mov_b32 m0, s29
	ds_read_b128 v[194:197], v212
	ds_read_b128 v[198:201], v212 offset:1024
	ds_read_b128 v[202:205], v212 offset:2048
	ds_read_b128 v[212:215], v212 offset:3072
	global_load_lds_dwordx4 v[216:217], off
	v_lshl_add_u64 v[216:217], v[218:219], 0, s[8:9]
	s_add_i32 m0, s29, 0x2000
	s_nop 0
	global_load_lds_dwordx4 v[216:217], off
	s_barrier
	s_waitcnt lgkmcnt(0)
	s_setprio 1
	s_waitcnt lgkmcnt(0)
	v_mfma_f32_16x16x32_bf16 v[116:119], v[194:197], v[144:147], v[116:119]
	v_mfma_f32_16x16x32_bf16 v[112:115], v[202:205], v[144:147], v[112:115]
	v_mfma_f32_16x16x32_bf16 v[100:103], v[194:197], v[152:155], v[100:103]
	v_mfma_f32_16x16x32_bf16 v[96:99], v[202:205], v[152:155], v[96:99]
	v_mfma_f32_16x16x32_bf16 v[84:87], v[194:197], v[160:163], v[84:87]
	v_mfma_f32_16x16x32_bf16 v[80:83], v[202:205], v[160:163], v[80:83]
	v_mfma_f32_16x16x32_bf16 v[68:71], v[194:197], v[168:171], v[68:71]
	v_mfma_f32_16x16x32_bf16 v[64:67], v[202:205], v[168:171], v[64:67]
	v_mfma_f32_16x16x32_bf16 v[116:119], v[198:201], v[148:151], v[116:119]
	v_mfma_f32_16x16x32_bf16 v[112:115], v[212:215], v[148:151], v[112:115]
	v_mfma_f32_16x16x32_bf16 v[100:103], v[198:201], v[156:159], v[100:103]
	v_mfma_f32_16x16x32_bf16 v[96:99], v[212:215], v[156:159], v[96:99]
	v_mfma_f32_16x16x32_bf16 v[84:87], v[198:201], v[164:167], v[84:87]
	v_mfma_f32_16x16x32_bf16 v[80:83], v[212:215], v[164:167], v[80:83]
	v_mfma_f32_16x16x32_bf16 v[68:71], v[198:201], v[172:175], v[68:71]
	v_mfma_f32_16x16x32_bf16 v[64:67], v[212:215], v[172:175], v[64:67]
	s_setprio 0
	s_mov_b32 m0, s41
	v_lshl_add_u64 v[216:217], v[220:221], 0, s[8:9]
	s_barrier
	ds_read_b128 v[144:147], v209 offset:49152
	ds_read_b128 v[148:151], v209 offset:50176
	ds_read_b128 v[152:155], v209 offset:51200
	ds_read_b128 v[156:159], v209 offset:52224
	ds_read_b128 v[160:163], v209 offset:53248
	ds_read_b128 v[164:167], v209 offset:54272
	ds_read_b128 v[168:171], v209 offset:55296
	ds_read_b128 v[172:175], v209 offset:56320
	global_load_lds_dwordx4 v[216:217], off
	v_lshl_add_u64 v[216:217], v[222:223], 0, s[8:9]
	s_mov_b32 m0, s42
	s_nop 0
	global_load_lds_dwordx4 v[216:217], off
	s_barrier
	s_waitcnt lgkmcnt(0)
	s_setprio 1
	s_waitcnt lgkmcnt(0)
	v_mfma_f32_16x16x32_bf16 v[60:63], v[128:131], v[144:147], v[60:63]
	v_mfma_f32_16x16x32_bf16 v[56:59], v[136:139], v[144:147], v[56:59]
	v_mfma_f32_16x16x32_bf16 v[44:47], v[128:131], v[152:155], v[44:47]
	v_mfma_f32_16x16x32_bf16 v[40:43], v[136:139], v[152:155], v[40:43]
	v_mfma_f32_16x16x32_bf16 v[28:31], v[128:131], v[160:163], v[28:31]
	v_mfma_f32_16x16x32_bf16 v[24:27], v[136:139], v[160:163], v[24:27]
	v_mfma_f32_16x16x32_bf16 v[12:15], v[128:131], v[168:171], v[12:15]
	v_mfma_f32_16x16x32_bf16 v[8:11], v[136:139], v[168:171], v[8:11]
	v_mfma_f32_16x16x32_bf16 v[60:63], v[132:135], v[148:151], v[60:63]
	v_mfma_f32_16x16x32_bf16 v[56:59], v[140:143], v[148:151], v[56:59]
	v_mfma_f32_16x16x32_bf16 v[44:47], v[132:135], v[156:159], v[44:47]
	v_mfma_f32_16x16x32_bf16 v[40:43], v[140:143], v[156:159], v[40:43]
	v_mfma_f32_16x16x32_bf16 v[28:31], v[132:135], v[164:167], v[28:31]
	v_mfma_f32_16x16x32_bf16 v[24:27], v[140:143], v[164:167], v[24:27]
	v_mfma_f32_16x16x32_bf16 v[12:15], v[132:135], v[172:175], v[12:15]
	v_mfma_f32_16x16x32_bf16 v[8:11], v[140:143], v[172:175], v[8:11]
	s_setprio 0
	s_barrier
	s_add_u32 s24, s24, 0x40080
	s_addc_u32 s25, s25, 0
	s_add_i32 s28, s28, s35
	v_lshl_add_u64 v[128:129], s[24:25], 0, v[178:179]
	s_mov_b32 m0, s28
	s_nop 0
	global_load_lds_dwordx4 v[128:129], off
	v_lshl_add_u64 v[128:129], s[24:25], 0, v[182:183]
	s_add_i32 m0, s28, 0x2000
	s_nop 0
	global_load_lds_dwordx4 v[128:129], off
	s_waitcnt vmcnt(6)
	s_barrier
	s_setprio 1
	v_mfma_f32_16x16x32_bf16 v[52:55], v[194:197], v[144:147], v[52:55]
	v_mfma_f32_16x16x32_bf16 v[48:51], v[202:205], v[144:147], v[48:51]
	v_mfma_f32_16x16x32_bf16 v[36:39], v[194:197], v[152:155], v[36:39]
	v_mfma_f32_16x16x32_bf16 v[32:35], v[202:205], v[152:155], v[32:35]
	v_mfma_f32_16x16x32_bf16 v[20:23], v[194:197], v[160:163], v[20:23]
	v_mfma_f32_16x16x32_bf16 v[16:19], v[202:205], v[160:163], v[16:19]
	v_mfma_f32_16x16x32_bf16 v[4:7], v[194:197], v[168:171], v[4:7]
	v_mfma_f32_16x16x32_bf16 v[0:3], v[202:205], v[168:171], v[0:3]
	v_mfma_f32_16x16x32_bf16 v[52:55], v[198:201], v[148:151], v[52:55]
	v_mfma_f32_16x16x32_bf16 v[48:51], v[212:215], v[148:151], v[48:51]
	v_mfma_f32_16x16x32_bf16 v[36:39], v[198:201], v[156:159], v[36:39]
	v_mfma_f32_16x16x32_bf16 v[32:35], v[212:215], v[156:159], v[32:35]
	v_mfma_f32_16x16x32_bf16 v[20:23], v[198:201], v[164:167], v[20:23]
	v_mfma_f32_16x16x32_bf16 v[16:19], v[212:215], v[164:167], v[16:19]
	v_mfma_f32_16x16x32_bf16 v[4:7], v[198:201], v[172:175], v[4:7]
	v_mfma_f32_16x16x32_bf16 v[0:3], v[212:215], v[172:175], v[0:3]
	s_setprio 0
	s_add_i32 s51, s51, 2
	s_add_u32 s22, s22, 0x100
	s_addc_u32 s23, s23, 0
	s_add_u32 s49, s49, 0x100
	s_addc_u32 s50, s50, 0
	s_cmp_gt_u32 s51, 13
	s_barrier
	s_cbranch_scc0 .LBB0_364
	v_lshl_add_u32 v196, s20, 8, v189
	v_lshl_or_b32 v194, s6, 8, v207
	v_readlane_b32 s48, v235, 5
	v_ashrrev_i32_e32 v195, 31, v194
	v_readlane_b32 s49, v235, 6
	v_ashrrev_i32_e32 v197, 31, v196
	v_lshlrev_b64 v[128:129], 12, v[196:197]
	v_lshl_add_u64 v[198:199], v[194:195], 2, s[48:49]
	v_or_b32_e32 v204, 16, v196
	v_lshl_add_u64 v[128:129], v[198:199], 0, v[128:129]
	v_ashrrev_i32_e32 v205, 31, v204
	global_load_dwordx4 v[212:215], v[128:129], off offset:16 nt
	global_load_dwordx4 v[216:219], v[128:129], off nt
	global_load_dwordx4 v[220:223], v[128:129], off offset:528 nt
	global_load_dwordx4 v[224:227], v[128:129], off offset:512 nt
	v_lshlrev_b64 v[128:129], 12, v[204:205]
	v_or_b32_e32 v202, 32, v196
	v_lshl_add_u64 v[128:129], v[198:199], 0, v[128:129]
	v_ashrrev_i32_e32 v203, 31, v202
	global_load_dwordx4 v[168:171], v[128:129], off offset:16 nt
	global_load_dwordx4 v[172:175], v[128:129], off nt
	global_load_dwordx4 v[160:163], v[128:129], off offset:528 nt
	global_load_dwordx4 v[164:167], v[128:129], off offset:512 nt
	v_lshlrev_b64 v[128:129], 12, v[202:203]
	v_or_b32_e32 v200, 48, v196
	v_lshl_add_u64 v[128:129], v[198:199], 0, v[128:129]
	v_ashrrev_i32_e32 v201, 31, v200
	global_load_dwordx4 v[152:155], v[128:129], off offset:16 nt
	global_load_dwordx4 v[156:159], v[128:129], off nt
	global_load_dwordx4 v[144:147], v[128:129], off offset:528 nt
	global_load_dwordx4 v[148:151], v[128:129], off offset:512 nt
	v_lshlrev_b64 v[128:129], 12, v[200:201]
	v_lshl_add_u64 v[132:133], v[198:199], 0, v[128:129]
	global_load_dwordx4 v[136:139], v[132:133], off offset:16 nt
	global_load_dwordx4 v[140:143], v[132:133], off nt
	global_load_dwordx4 v[128:131], v[132:133], off offset:528 nt
	s_nop 0
	global_load_dwordx4 v[132:135], v[132:133], off offset:512 nt
	s_lshl_b32 s20, s6, 2
	s_ashr_i32 s21, s20, 31
	v_readlane_b32 s50, v235, 7
	v_readlane_b32 s51, v235, 8
	v_readlane_b32 s52, v235, 9
	v_readlane_b32 s53, v235, 10
	v_readlane_b32 s54, v235, 11
	v_readlane_b32 s55, v235, 12
	v_readlane_b32 s56, v235, 13
	v_readlane_b32 s57, v235, 14
	v_readlane_b32 s58, v235, 15
	v_readlane_b32 s59, v235, 16
	v_readlane_b32 s60, v235, 17
	v_readlane_b32 s61, v235, 18
	v_readlane_b32 s62, v235, 19
	v_readlane_b32 s63, v235, 20
	s_waitcnt vmcnt(0)
	v_pk_add_f32 v[126:127], v[126:127], v[218:219]
	v_pk_add_f32 v[124:125], v[124:125], v[216:217]
	v_pk_add_f32 v[214:215], v[122:123], v[214:215]
	v_mul_f32_e32 v122, v125, v125
	v_mul_f32_e32 v123, v127, v127
	v_pk_add_f32 v[120:121], v[120:121], v[212:213]
	v_fmac_f32_e32 v122, v124, v124
	v_fmac_f32_e32 v123, v126, v126
	v_add_f32_e32 v122, v122, v123
	v_mul_f32_e32 v123, v121, v121
	v_mul_f32_e32 v212, v215, v215
	v_fmac_f32_e32 v123, v120, v120
	v_fmac_f32_e32 v212, v214, v214
	v_pk_add_f32 v[118:119], v[118:119], v[226:227]
	v_pk_add_f32 v[116:117], v[116:117], v[224:225]
	v_add_f32_e32 v123, v123, v212
	v_pk_add_f32 v[212:213], v[112:113], v[220:221]
	v_mul_f32_e32 v112, v117, v117
	v_mul_f32_e32 v113, v119, v119
	v_add_f32_e32 v216, v122, v123
	v_cvt_pk_bf16_f32 v122, v124, v125
	v_cvt_pk_bf16_f32 v123, v126, v127
	v_pk_add_f32 v[126:127], v[114:115], v[222:223]
	v_fmac_f32_e32 v112, v116, v116
	v_fmac_f32_e32 v113, v118, v118
	v_add_f32_e32 v112, v112, v113
	v_mul_f32_e32 v113, v213, v213
	v_mul_f32_e32 v114, v127, v127
	v_fmac_f32_e32 v113, v212, v212
	v_fmac_f32_e32 v114, v126, v126
	v_add_f32_e32 v113, v113, v114
	v_add_f32_e32 v112, v112, v113
	v_and_b32_e32 v113, 64, v211
	v_cvt_pk_bf16_f32 v124, v120, v121
	v_add_f32_e32 v115, v216, v112
	v_xor_b32_e32 v112, 16, v211
	v_add_u32_e32 v121, 64, v113
	v_cmp_lt_i32_e32 vcc, v112, v121
	v_lshlrev_b64 v[228:229], 11, v[196:197]
	v_cvt_pk_bf16_f32 v125, v214, v215
	s_nop 0
	v_cndmask_b32_e32 v112, v211, v112, vcc
	v_lshlrev_b32_e32 v120, 2, v112
	ds_bpermute_b32 v216, v120, v115
	v_lshl_add_u64 v[112:113], s[64:65], 0, v[228:229]
	v_lshl_add_u64 v[214:215], v[194:195], 1, v[112:113]
	v_xor_b32_e32 v113, 32, v211
	v_cmp_lt_i32_e32 vcc, v113, v121
	s_waitcnt lgkmcnt(0)
	v_add_f32_e32 v112, v115, v216
	global_store_dwordx4 v[214:215], v[122:125], off nt
	v_cndmask_b32_e32 v113, v211, v113, vcc
	v_lshlrev_b32_e32 v121, 2, v113
	ds_bpermute_b32 v113, v121, v112
	v_cvt_pk_bf16_f32 v114, v116, v117
	v_cvt_pk_bf16_f32 v115, v118, v119
	v_cvt_pk_bf16_f32 v116, v212, v213
	v_cvt_pk_bf16_f32 v117, v126, v127
	global_store_dwordx4 v[214:215], v[114:117], off offset:256 nt
	s_and_saveexec_b64 s[22:23], s[2:3]
	s_cbranch_execz .LBB0_367
	v_lshlrev_b64 v[114:115], 6, v[196:197]
	v_lshl_add_u64 v[114:115], s[74:75], 0, v[114:115]
	v_lshl_add_u64 v[114:115], s[20:21], 2, v[114:115]
	s_lshl_b32 s6, s40, 2
	v_lshl_add_u64 v[114:115], v[114:115], 0, s[6:7]
	s_waitcnt lgkmcnt(0)
	v_add_f32_e32 v112, v112, v113
	global_store_dword v[114:115], v112, off
.LBB0_367:
	s_or_b64 exec, exec, s[22:23]
	v_pk_add_f32 v[110:111], v[110:111], v[174:175]
	v_pk_add_f32 v[108:109], v[108:109], v[172:173]
	v_pk_add_f32 v[114:115], v[106:107], v[170:171]
	v_pk_add_f32 v[106:107], v[104:105], v[168:169]
	v_mul_f32_e32 v104, v109, v109
	v_mul_f32_e32 v105, v111, v111
	v_fmac_f32_e32 v104, v108, v108
	v_fmac_f32_e32 v105, v110, v110
	v_add_f32_e32 v104, v104, v105
	v_mul_f32_e32 v105, v107, v107
	v_mul_f32_e32 v116, v115, v115
	v_fmac_f32_e32 v105, v106, v106
	v_fmac_f32_e32 v116, v114, v114
	v_add_f32_e32 v105, v105, v116
	v_pk_add_f32 v[102:103], v[102:103], v[166:167]
	v_pk_add_f32 v[100:101], v[100:101], v[164:165]
	v_add_f32_e32 v116, v104, v105
	v_cvt_pk_bf16_f32 v104, v108, v109
	v_cvt_pk_bf16_f32 v105, v110, v111
	v_pk_add_f32 v[110:111], v[96:97], v[160:161]
	v_mul_f32_e32 v96, v101, v101
	v_mul_f32_e32 v97, v103, v103
	v_pk_add_f32 v[108:109], v[98:99], v[162:163]
	v_fmac_f32_e32 v96, v100, v100
	v_fmac_f32_e32 v97, v102, v102
	v_add_f32_e32 v96, v96, v97
	v_mul_f32_e32 v97, v111, v111
	v_mul_f32_e32 v98, v109, v109
	v_fmac_f32_e32 v97, v110, v110
	v_fmac_f32_e32 v98, v108, v108
	v_add_f32_e32 v97, v97, v98
	v_add_f32_e32 v96, v96, v97
	v_add_f32_e32 v99, v116, v96
	v_cvt_pk_bf16_f32 v106, v106, v107
	v_cvt_pk_bf16_f32 v107, v114, v115
	ds_bpermute_b32 v114, v120, v99
	s_waitcnt lgkmcnt(1)
	v_lshlrev_b64 v[112:113], 11, v[204:205]
	v_lshl_add_u64 v[96:97], s[64:65], 0, v[112:113]
	v_lshl_add_u64 v[112:113], v[194:195], 1, v[96:97]
	global_store_dwordx4 v[112:113], v[104:107], off nt
	s_waitcnt lgkmcnt(0)
	v_add_f32_e32 v96, v99, v114
	ds_bpermute_b32 v97, v121, v96
	v_cvt_pk_bf16_f32 v98, v100, v101
	v_cvt_pk_bf16_f32 v99, v102, v103
	v_cvt_pk_bf16_f32 v100, v110, v111
	v_cvt_pk_bf16_f32 v101, v108, v109
	global_store_dwordx4 v[112:113], v[98:101], off offset:256 nt
	s_and_saveexec_b64 s[22:23], s[2:3]
	s_cbranch_execz .LBB0_369
	v_lshlrev_b64 v[98:99], 6, v[204:205]
	v_lshl_add_u64 v[98:99], s[74:75], 0, v[98:99]
	v_lshl_add_u64 v[98:99], s[20:21], 2, v[98:99]
	s_lshl_b32 s6, s40, 2
	v_lshl_add_u64 v[98:99], v[98:99], 0, s[6:7]
	s_waitcnt lgkmcnt(0)
	v_add_f32_e32 v96, v96, v97
	global_store_dword v[98:99], v96, off
.LBB0_369:
	s_or_b64 exec, exec, s[22:23]
	v_pk_add_f32 v[94:95], v[94:95], v[158:159]
	v_pk_add_f32 v[92:93], v[92:93], v[156:157]
	v_pk_add_f32 v[98:99], v[90:91], v[154:155]
	v_pk_add_f32 v[90:91], v[88:89], v[152:153]
	v_mul_f32_e32 v88, v93, v93
	v_mul_f32_e32 v89, v95, v95
	v_fmac_f32_e32 v88, v92, v92
	v_fmac_f32_e32 v89, v94, v94
	v_add_f32_e32 v88, v88, v89
	v_mul_f32_e32 v89, v91, v91
	v_mul_f32_e32 v100, v99, v99
	v_fmac_f32_e32 v89, v90, v90
	v_fmac_f32_e32 v100, v98, v98
	v_add_f32_e32 v89, v89, v100
	v_pk_add_f32 v[86:87], v[86:87], v[150:151]
	v_pk_add_f32 v[84:85], v[84:85], v[148:149]
	v_add_f32_e32 v100, v88, v89
	v_cvt_pk_bf16_f32 v88, v92, v93
	v_cvt_pk_bf16_f32 v89, v94, v95
	v_pk_add_f32 v[94:95], v[80:81], v[144:145]
	v_mul_f32_e32 v80, v85, v85
	v_mul_f32_e32 v81, v87, v87
	v_pk_add_f32 v[92:93], v[82:83], v[146:147]
	v_fmac_f32_e32 v80, v84, v84
	v_fmac_f32_e32 v81, v86, v86
	v_add_f32_e32 v80, v80, v81
	v_mul_f32_e32 v81, v95, v95
	v_mul_f32_e32 v82, v93, v93
	v_fmac_f32_e32 v81, v94, v94
	v_fmac_f32_e32 v82, v92, v92
	v_add_f32_e32 v81, v81, v82
	v_add_f32_e32 v80, v80, v81
	v_add_f32_e32 v83, v100, v80
	v_cvt_pk_bf16_f32 v90, v90, v91
	v_cvt_pk_bf16_f32 v91, v98, v99
	ds_bpermute_b32 v98, v120, v83
	s_waitcnt lgkmcnt(1)
	v_lshlrev_b64 v[96:97], 11, v[202:203]
	v_lshl_add_u64 v[80:81], s[64:65], 0, v[96:97]
	v_lshl_add_u64 v[96:97], v[194:195], 1, v[80:81]
	global_store_dwordx4 v[96:97], v[88:91], off nt
	s_waitcnt lgkmcnt(0)
	v_add_f32_e32 v80, v83, v98
	ds_bpermute_b32 v81, v121, v80
	v_cvt_pk_bf16_f32 v82, v84, v85
	v_cvt_pk_bf16_f32 v83, v86, v87
	v_cvt_pk_bf16_f32 v84, v94, v95
	v_cvt_pk_bf16_f32 v85, v92, v93
	global_store_dwordx4 v[96:97], v[82:85], off offset:256 nt
	s_and_saveexec_b64 s[22:23], s[2:3]
	s_cbranch_execz .LBB0_371
	v_lshlrev_b64 v[82:83], 6, v[202:203]
	v_lshl_add_u64 v[82:83], s[74:75], 0, v[82:83]
	v_lshl_add_u64 v[82:83], s[20:21], 2, v[82:83]
	s_lshl_b32 s6, s40, 2
	v_lshl_add_u64 v[82:83], v[82:83], 0, s[6:7]
	s_waitcnt lgkmcnt(0)
	v_add_f32_e32 v80, v80, v81
	global_store_dword v[82:83], v80, off
.LBB0_371:
	s_or_b64 exec, exec, s[22:23]
	v_pk_add_f32 v[78:79], v[78:79], v[142:143]
	v_pk_add_f32 v[76:77], v[76:77], v[140:141]
	v_pk_add_f32 v[82:83], v[74:75], v[138:139]
	v_pk_add_f32 v[74:75], v[72:73], v[136:137]
	v_mul_f32_e32 v72, v77, v77
	v_mul_f32_e32 v73, v79, v79
	v_fmac_f32_e32 v72, v76, v76
	v_fmac_f32_e32 v73, v78, v78
	v_add_f32_e32 v72, v72, v73
	v_mul_f32_e32 v73, v75, v75
	v_mul_f32_e32 v84, v83, v83
	v_fmac_f32_e32 v73, v74, v74
	v_fmac_f32_e32 v84, v82, v82
	v_add_f32_e32 v73, v73, v84
	v_pk_add_f32 v[70:71], v[70:71], v[134:135]
	v_pk_add_f32 v[68:69], v[68:69], v[132:133]
	v_add_f32_e32 v84, v72, v73
	v_cvt_pk_bf16_f32 v72, v76, v77
	v_cvt_pk_bf16_f32 v73, v78, v79
	v_pk_add_f32 v[78:79], v[64:65], v[128:129]
	v_mul_f32_e32 v64, v69, v69
	v_mul_f32_e32 v65, v71, v71
	v_pk_add_f32 v[76:77], v[66:67], v[130:131]
	v_fmac_f32_e32 v64, v68, v68
	v_fmac_f32_e32 v65, v70, v70
	v_add_f32_e32 v64, v64, v65
	v_mul_f32_e32 v65, v79, v79
	v_mul_f32_e32 v66, v77, v77
	v_fmac_f32_e32 v65, v78, v78
	v_fmac_f32_e32 v66, v76, v76
	v_add_f32_e32 v65, v65, v66
	v_add_f32_e32 v64, v64, v65
	v_add_f32_e32 v67, v84, v64
	v_cvt_pk_bf16_f32 v74, v74, v75
	v_cvt_pk_bf16_f32 v75, v82, v83
	ds_bpermute_b32 v82, v120, v67
	s_waitcnt lgkmcnt(1)
	v_lshlrev_b64 v[80:81], 11, v[200:201]
	v_lshl_add_u64 v[64:65], s[64:65], 0, v[80:81]
	v_lshl_add_u64 v[80:81], v[194:195], 1, v[64:65]
	global_store_dwordx4 v[80:81], v[72:75], off nt
	s_waitcnt lgkmcnt(0)
	v_add_f32_e32 v64, v67, v82
	ds_bpermute_b32 v65, v121, v64
	v_cvt_pk_bf16_f32 v66, v68, v69
	v_cvt_pk_bf16_f32 v67, v70, v71
	v_cvt_pk_bf16_f32 v68, v78, v79
	v_cvt_pk_bf16_f32 v69, v76, v77
	global_store_dwordx4 v[80:81], v[66:69], off offset:256 nt
	s_and_saveexec_b64 s[22:23], s[2:3]
	s_cbranch_execz .LBB0_373
	v_lshlrev_b64 v[66:67], 6, v[200:201]
	v_lshl_add_u64 v[66:67], s[74:75], 0, v[66:67]
	v_lshl_add_u64 v[66:67], s[20:21], 2, v[66:67]
	s_lshl_b32 s6, s40, 2
	v_lshl_add_u64 v[66:67], v[66:67], 0, s[6:7]
	s_waitcnt lgkmcnt(0)
	v_add_f32_e32 v64, v64, v65
	global_store_dword v[66:67], v64, off
.LBB0_373:
	s_or_b64 exec, exec, s[22:23]
	v_add_u32_e32 v118, 0x80, v196
	v_ashrrev_i32_e32 v119, 31, v118
	s_waitcnt lgkmcnt(0)
	v_lshlrev_b64 v[64:65], 12, v[118:119]
	v_add_u32_e32 v116, 0x90, v196
	v_lshl_add_u64 v[64:65], v[198:199], 0, v[64:65]
	v_ashrrev_i32_e32 v117, 31, v116
	global_load_dwordx4 v[122:125], v[64:65], off offset:16 nt
	global_load_dwordx4 v[126:129], v[64:65], off nt
	global_load_dwordx4 v[130:133], v[64:65], off offset:528 nt
	global_load_dwordx4 v[134:137], v[64:65], off offset:512 nt
	v_lshlrev_b64 v[64:65], 12, v[116:117]
	v_add_u32_e32 v114, 0xa0, v196
	v_lshl_add_u64 v[64:65], v[198:199], 0, v[64:65]
	v_ashrrev_i32_e32 v115, 31, v114
	global_load_dwordx4 v[104:107], v[64:65], off offset:16 nt
	global_load_dwordx4 v[108:111], v[64:65], off nt
	global_load_dwordx4 v[96:99], v[64:65], off offset:528 nt
	global_load_dwordx4 v[100:103], v[64:65], off offset:512 nt
	v_lshlrev_b64 v[64:65], 12, v[114:115]
	v_add_u32_e32 v112, 0xb0, v196
	v_lshl_add_u64 v[64:65], v[198:199], 0, v[64:65]
	v_ashrrev_i32_e32 v113, 31, v112
	global_load_dwordx4 v[88:91], v[64:65], off offset:16 nt
	global_load_dwordx4 v[92:95], v[64:65], off nt
	global_load_dwordx4 v[80:83], v[64:65], off offset:528 nt
	global_load_dwordx4 v[84:87], v[64:65], off offset:512 nt
	v_lshlrev_b64 v[64:65], 12, v[112:113]
	v_lshl_add_u64 v[68:69], v[198:199], 0, v[64:65]
	global_load_dwordx4 v[72:75], v[68:69], off offset:16 nt
	global_load_dwordx4 v[76:79], v[68:69], off nt
	global_load_dwordx4 v[64:67], v[68:69], off offset:528 nt
	s_nop 0
	global_load_dwordx4 v[68:71], v[68:69], off offset:512 nt
	s_waitcnt vmcnt(14)
	v_pk_add_f32 v[62:63], v[62:63], v[128:129]
	v_pk_add_f32 v[60:61], v[60:61], v[126:127]
	v_pk_add_f32 v[124:125], v[58:59], v[124:125]
	v_pk_add_f32 v[58:59], v[56:57], v[122:123]
	v_mul_f32_e32 v56, v61, v61
	v_mul_f32_e32 v57, v63, v63
	v_fmac_f32_e32 v56, v60, v60
	v_fmac_f32_e32 v57, v62, v62
	v_add_f32_e32 v56, v56, v57
	v_mul_f32_e32 v57, v59, v59
	v_mul_f32_e32 v122, v125, v125
	v_fmac_f32_e32 v57, v58, v58
	v_fmac_f32_e32 v122, v124, v124
	v_add_f32_e32 v57, v57, v122
	s_waitcnt vmcnt(12)
	v_pk_add_f32 v[54:55], v[54:55], v[136:137]
	v_pk_add_f32 v[52:53], v[52:53], v[134:135]
	v_add_f32_e32 v122, v56, v57
	v_cvt_pk_bf16_f32 v56, v60, v61
	v_cvt_pk_bf16_f32 v57, v62, v63
	v_pk_add_f32 v[62:63], v[48:49], v[130:131]
	v_mul_f32_e32 v48, v53, v53
	v_mul_f32_e32 v49, v55, v55
	v_pk_add_f32 v[60:61], v[50:51], v[132:133]
	v_fmac_f32_e32 v48, v52, v52
	v_fmac_f32_e32 v49, v54, v54
	v_add_f32_e32 v48, v48, v49
	v_mul_f32_e32 v49, v63, v63
	v_mul_f32_e32 v50, v61, v61
	v_fmac_f32_e32 v49, v62, v62
	v_fmac_f32_e32 v50, v60, v60
	v_add_f32_e32 v49, v49, v50
	v_add_f32_e32 v48, v48, v49
	v_add_f32_e32 v51, v122, v48
	v_cvt_pk_bf16_f32 v58, v58, v59
	v_cvt_pk_bf16_f32 v59, v124, v125
	ds_bpermute_b32 v124, v120, v51
	v_lshlrev_b64 v[138:139], 11, v[118:119]
	v_lshl_add_u64 v[48:49], s[64:65], 0, v[138:139]
	v_lshl_add_u64 v[122:123], v[194:195], 1, v[48:49]
	global_store_dwordx4 v[122:123], v[56:59], off nt
	s_waitcnt lgkmcnt(0)
	v_add_f32_e32 v48, v51, v124
	ds_bpermute_b32 v49, v121, v48
	v_cvt_pk_bf16_f32 v50, v52, v53
	v_cvt_pk_bf16_f32 v51, v54, v55
	v_cvt_pk_bf16_f32 v52, v62, v63
	v_cvt_pk_bf16_f32 v53, v60, v61
	global_store_dwordx4 v[122:123], v[50:53], off offset:256 nt
	s_and_saveexec_b64 s[22:23], s[2:3]
	s_cbranch_execz .LBB0_375
	v_lshlrev_b64 v[50:51], 6, v[118:119]
	v_lshl_add_u64 v[50:51], s[74:75], 0, v[50:51]
	v_lshl_add_u64 v[50:51], s[20:21], 2, v[50:51]
	s_lshl_b32 s6, s40, 2
	v_lshl_add_u64 v[50:51], v[50:51], 0, s[6:7]
	s_waitcnt lgkmcnt(0)
	v_add_f32_e32 v48, v48, v49
	global_store_dword v[50:51], v48, off
.LBB0_375:
	s_or_b64 exec, exec, s[22:23]
	s_waitcnt vmcnt(12)
	v_pk_add_f32 v[46:47], v[46:47], v[110:111]
	v_pk_add_f32 v[44:45], v[44:45], v[108:109]
	v_pk_add_f32 v[50:51], v[42:43], v[106:107]
	v_pk_add_f32 v[42:43], v[40:41], v[104:105]
	v_mul_f32_e32 v40, v45, v45
	v_mul_f32_e32 v41, v47, v47
	v_fmac_f32_e32 v40, v44, v44
	v_fmac_f32_e32 v41, v46, v46
	v_add_f32_e32 v40, v40, v41
	v_mul_f32_e32 v41, v43, v43
	v_mul_f32_e32 v52, v51, v51
	v_fmac_f32_e32 v41, v42, v42
	v_fmac_f32_e32 v52, v50, v50
	v_add_f32_e32 v41, v41, v52
	s_waitcnt vmcnt(10)
	v_pk_add_f32 v[38:39], v[38:39], v[102:103]
	v_pk_add_f32 v[36:37], v[36:37], v[100:101]
	v_add_f32_e32 v52, v40, v41
	v_cvt_pk_bf16_f32 v40, v44, v45
	v_cvt_pk_bf16_f32 v41, v46, v47
	v_pk_add_f32 v[46:47], v[32:33], v[96:97]
	v_mul_f32_e32 v32, v37, v37
	v_mul_f32_e32 v33, v39, v39
	v_pk_add_f32 v[44:45], v[34:35], v[98:99]
	v_fmac_f32_e32 v32, v36, v36
	v_fmac_f32_e32 v33, v38, v38
	v_add_f32_e32 v32, v32, v33
	v_mul_f32_e32 v33, v47, v47
	v_mul_f32_e32 v34, v45, v45
	v_fmac_f32_e32 v33, v46, v46
	v_fmac_f32_e32 v34, v44, v44
	v_add_f32_e32 v33, v33, v34
	v_add_f32_e32 v32, v32, v33
	v_add_f32_e32 v35, v52, v32
	v_cvt_pk_bf16_f32 v42, v42, v43
	v_cvt_pk_bf16_f32 v43, v50, v51
	ds_bpermute_b32 v50, v120, v35
	s_waitcnt lgkmcnt(1)
	v_lshlrev_b64 v[48:49], 11, v[116:117]
	v_lshl_add_u64 v[32:33], s[64:65], 0, v[48:49]
	v_lshl_add_u64 v[48:49], v[194:195], 1, v[32:33]
	global_store_dwordx4 v[48:49], v[40:43], off nt
	s_waitcnt lgkmcnt(0)
	v_add_f32_e32 v32, v35, v50
	ds_bpermute_b32 v33, v121, v32
	v_cvt_pk_bf16_f32 v34, v36, v37
	v_cvt_pk_bf16_f32 v35, v38, v39
	v_cvt_pk_bf16_f32 v36, v46, v47
	v_cvt_pk_bf16_f32 v37, v44, v45
	global_store_dwordx4 v[48:49], v[34:37], off offset:256 nt
	s_and_saveexec_b64 s[22:23], s[2:3]
	s_cbranch_execz .LBB0_377
	v_lshlrev_b64 v[34:35], 6, v[116:117]
	v_lshl_add_u64 v[34:35], s[74:75], 0, v[34:35]
	v_lshl_add_u64 v[34:35], s[20:21], 2, v[34:35]
	s_lshl_b32 s6, s40, 2
	v_lshl_add_u64 v[34:35], v[34:35], 0, s[6:7]
	s_waitcnt lgkmcnt(0)
	v_add_f32_e32 v32, v32, v33
	global_store_dword v[34:35], v32, off
.LBB0_377:
	s_or_b64 exec, exec, s[22:23]
	s_waitcnt vmcnt(10)
	v_pk_add_f32 v[30:31], v[30:31], v[94:95]
	v_pk_add_f32 v[28:29], v[28:29], v[92:93]
	v_pk_add_f32 v[34:35], v[26:27], v[90:91]
	v_pk_add_f32 v[26:27], v[24:25], v[88:89]
	v_mul_f32_e32 v24, v29, v29
	v_mul_f32_e32 v25, v31, v31
	v_fmac_f32_e32 v24, v28, v28
	v_fmac_f32_e32 v25, v30, v30
	v_add_f32_e32 v24, v24, v25
	v_mul_f32_e32 v25, v27, v27
	v_mul_f32_e32 v36, v35, v35
	v_fmac_f32_e32 v25, v26, v26
	v_fmac_f32_e32 v36, v34, v34
	v_add_f32_e32 v25, v25, v36
	s_waitcnt vmcnt(8)
	v_pk_add_f32 v[22:23], v[22:23], v[86:87]
	v_pk_add_f32 v[20:21], v[20:21], v[84:85]
	v_add_f32_e32 v36, v24, v25
	v_cvt_pk_bf16_f32 v24, v28, v29
	v_cvt_pk_bf16_f32 v25, v30, v31
	v_pk_add_f32 v[30:31], v[16:17], v[80:81]
	v_mul_f32_e32 v16, v21, v21
	v_mul_f32_e32 v17, v23, v23
	v_pk_add_f32 v[28:29], v[18:19], v[82:83]
	v_fmac_f32_e32 v16, v20, v20
	v_fmac_f32_e32 v17, v22, v22
	v_add_f32_e32 v16, v16, v17
	v_mul_f32_e32 v17, v31, v31
	v_mul_f32_e32 v18, v29, v29
	v_fmac_f32_e32 v17, v30, v30
	v_fmac_f32_e32 v18, v28, v28
	v_add_f32_e32 v17, v17, v18
	v_add_f32_e32 v16, v16, v17
	v_add_f32_e32 v19, v36, v16
	v_cvt_pk_bf16_f32 v26, v26, v27
	v_cvt_pk_bf16_f32 v27, v34, v35
	ds_bpermute_b32 v34, v120, v19
	s_waitcnt lgkmcnt(1)
	v_lshlrev_b64 v[32:33], 11, v[114:115]
	v_lshl_add_u64 v[16:17], s[64:65], 0, v[32:33]
	v_lshl_add_u64 v[32:33], v[194:195], 1, v[16:17]
	global_store_dwordx4 v[32:33], v[24:27], off nt
	s_waitcnt lgkmcnt(0)
	v_add_f32_e32 v16, v19, v34
	ds_bpermute_b32 v17, v121, v16
	v_cvt_pk_bf16_f32 v18, v20, v21
	v_cvt_pk_bf16_f32 v19, v22, v23
	v_cvt_pk_bf16_f32 v20, v30, v31
	v_cvt_pk_bf16_f32 v21, v28, v29
	global_store_dwordx4 v[32:33], v[18:21], off offset:256 nt
	s_and_saveexec_b64 s[22:23], s[2:3]
	s_cbranch_execz .LBB0_379
	v_lshlrev_b64 v[18:19], 6, v[114:115]
	v_lshl_add_u64 v[18:19], s[74:75], 0, v[18:19]
	v_lshl_add_u64 v[18:19], s[20:21], 2, v[18:19]
	s_lshl_b32 s6, s40, 2
	v_lshl_add_u64 v[18:19], v[18:19], 0, s[6:7]
	s_waitcnt lgkmcnt(0)
	v_add_f32_e32 v16, v16, v17
	global_store_dword v[18:19], v16, off
.LBB0_379:
	s_or_b64 exec, exec, s[22:23]
	s_waitcnt vmcnt(8)
	v_pk_add_f32 v[14:15], v[14:15], v[78:79]
	v_pk_add_f32 v[12:13], v[12:13], v[76:77]
	v_pk_add_f32 v[18:19], v[10:11], v[74:75]
	v_pk_add_f32 v[10:11], v[8:9], v[72:73]
	v_mul_f32_e32 v8, v13, v13
	v_mul_f32_e32 v9, v15, v15
	v_fmac_f32_e32 v8, v12, v12
	v_fmac_f32_e32 v9, v14, v14
	v_add_f32_e32 v8, v8, v9
	v_mul_f32_e32 v9, v11, v11
	v_mul_f32_e32 v20, v19, v19
	v_fmac_f32_e32 v9, v10, v10
	v_fmac_f32_e32 v20, v18, v18
	v_add_f32_e32 v9, v9, v20
	s_waitcnt vmcnt(6)
	v_pk_add_f32 v[6:7], v[6:7], v[70:71]
	v_pk_add_f32 v[4:5], v[4:5], v[68:69]
	v_add_f32_e32 v20, v8, v9
	v_cvt_pk_bf16_f32 v8, v12, v13
	v_cvt_pk_bf16_f32 v9, v14, v15
	v_pk_add_f32 v[14:15], v[0:1], v[64:65]
	v_mul_f32_e32 v0, v5, v5
	v_mul_f32_e32 v1, v7, v7
	v_pk_add_f32 v[12:13], v[2:3], v[66:67]
	v_fmac_f32_e32 v0, v4, v4
	v_fmac_f32_e32 v1, v6, v6
	v_add_f32_e32 v0, v0, v1
	v_mul_f32_e32 v1, v15, v15
	v_mul_f32_e32 v2, v13, v13
	v_fmac_f32_e32 v1, v14, v14
	v_fmac_f32_e32 v2, v12, v12
	v_add_f32_e32 v1, v1, v2
	v_add_f32_e32 v0, v0, v1
	v_add_f32_e32 v3, v20, v0
	v_cvt_pk_bf16_f32 v10, v10, v11
	v_cvt_pk_bf16_f32 v11, v18, v19
	ds_bpermute_b32 v18, v120, v3
	s_waitcnt lgkmcnt(1)
	v_lshlrev_b64 v[16:17], 11, v[112:113]
	v_lshl_add_u64 v[0:1], s[64:65], 0, v[16:17]
	v_lshl_add_u64 v[16:17], v[194:195], 1, v[0:1]
	global_store_dwordx4 v[16:17], v[8:11], off nt
	s_waitcnt lgkmcnt(0)
	v_add_f32_e32 v0, v3, v18
	ds_bpermute_b32 v1, v121, v0
	v_cvt_pk_bf16_f32 v2, v4, v5
	v_cvt_pk_bf16_f32 v3, v6, v7
	v_cvt_pk_bf16_f32 v4, v14, v15
	v_cvt_pk_bf16_f32 v5, v12, v13
	global_store_dwordx4 v[16:17], v[2:5], off offset:256 nt
	s_and_saveexec_b64 s[22:23], s[2:3]
	s_cbranch_execz .LBB0_356
	v_lshlrev_b64 v[2:3], 6, v[112:113]
	v_lshl_add_u64 v[2:3], s[74:75], 0, v[2:3]
	v_lshl_add_u64 v[2:3], s[20:21], 2, v[2:3]
	s_lshl_b32 s6, s40, 2
	v_lshl_add_u64 v[2:3], v[2:3], 0, s[6:7]
	s_waitcnt lgkmcnt(0)
	v_add_f32_e32 v0, v0, v1
	global_store_dword v[2:3], v0, off
	s_branch .LBB0_356

.LBB0_554:
	ds_read_b128 v[128:131], v190
	ds_read_b128 v[132:135], v190 offset:1024
	ds_read_b128 v[136:139], v190 offset:2048
	ds_read_b128 v[140:143], v190 offset:3072
	s_add_u32 s18, s14, 0x100
	s_addc_u32 s19, s15, 0
	s_cmp_eq_u32 s51, 40
	s_cselect_b32 s23, s1, s19
	s_cselect_b32 s22, s0, s18
	s_cselect_b32 s21, s7, s50
	s_cselect_b32 s20, s6, s49
	v_lshl_add_u64 v[184:185], s[14:15], 0, v[160:161]
	s_add_i32 m0, s34, 0xc000
	ds_read_b128 v[144:147], v191
	ds_read_b128 v[148:151], v191 offset:1024
	ds_read_b128 v[168:171], v191 offset:2048
	ds_read_b128 v[172:175], v191 offset:3072
	ds_read_b128 v[176:179], v191 offset:4096
	ds_read_b128 v[180:183], v191 offset:5120
	ds_read_b128 v[194:197], v191 offset:6144
	ds_read_b128 v[198:201], v191 offset:7168
	global_load_lds_dwordx4 v[184:185], off
	v_lshl_add_u64 v[184:185], s[14:15], 0, v[162:163]
	s_add_i32 m0, s34, 0xe000
	s_nop 0
	global_load_lds_dwordx4 v[184:185], off
	s_waitcnt lgkmcnt(8)
	s_barrier
	s_waitcnt lgkmcnt(0)
	s_setprio 1
	s_waitcnt lgkmcnt(0)
	v_mfma_f32_16x16x32_bf16 v[124:127], v[128:131], v[144:147], v[124:127]
	v_mfma_f32_16x16x32_bf16 v[120:123], v[136:139], v[144:147], v[120:123]
	v_mfma_f32_16x16x32_bf16 v[108:111], v[128:131], v[168:171], v[108:111]
	v_mfma_f32_16x16x32_bf16 v[104:107], v[136:139], v[168:171], v[104:107]
	v_mfma_f32_16x16x32_bf16 v[92:95], v[128:131], v[176:179], v[92:95]
	v_mfma_f32_16x16x32_bf16 v[88:91], v[136:139], v[176:179], v[88:91]
	v_mfma_f32_16x16x32_bf16 v[76:79], v[128:131], v[194:197], v[76:79]
	v_mfma_f32_16x16x32_bf16 v[72:75], v[136:139], v[194:197], v[72:75]
	v_mfma_f32_16x16x32_bf16 v[124:127], v[132:135], v[148:151], v[124:127]
	v_mfma_f32_16x16x32_bf16 v[120:123], v[140:143], v[148:151], v[120:123]
	v_mfma_f32_16x16x32_bf16 v[108:111], v[132:135], v[172:175], v[108:111]
	v_mfma_f32_16x16x32_bf16 v[104:107], v[140:143], v[172:175], v[104:107]
	v_mfma_f32_16x16x32_bf16 v[92:95], v[132:135], v[180:183], v[92:95]
	v_mfma_f32_16x16x32_bf16 v[88:91], v[140:143], v[180:183], v[88:91]
	v_mfma_f32_16x16x32_bf16 v[76:79], v[132:135], v[198:201], v[76:79]
	v_mfma_f32_16x16x32_bf16 v[72:75], v[140:143], v[198:201], v[72:75]
	s_setprio 0
	s_barrier
	s_add_i32 s14, s43, s31
	v_lshl_add_u64 v[184:185], s[20:21], 0, v[154:155]
	s_mov_b32 m0, s14
	ds_read_b128 v[202:205], v192
	ds_read_b128 v[206:209], v192 offset:1024
	ds_read_b128 v[210:213], v192 offset:2048
	ds_read_b128 v[214:217], v192 offset:3072
	global_load_lds_dwordx4 v[184:185], off
	v_lshl_add_u64 v[218:219], s[20:21], 0, v[158:159]
	s_add_i32 m0, s14, 0x2000
	s_nop 0
	global_load_lds_dwordx4 v[218:219], off
	s_barrier
	s_waitcnt lgkmcnt(0)
	s_setprio 1
	s_waitcnt lgkmcnt(0)
	v_mfma_f32_16x16x32_bf16 v[116:119], v[202:205], v[144:147], v[116:119]
	v_mfma_f32_16x16x32_bf16 v[112:115], v[210:213], v[144:147], v[112:115]
	v_mfma_f32_16x16x32_bf16 v[100:103], v[202:205], v[168:171], v[100:103]
	v_mfma_f32_16x16x32_bf16 v[96:99], v[210:213], v[168:171], v[96:99]
	v_mfma_f32_16x16x32_bf16 v[84:87], v[202:205], v[176:179], v[84:87]
	v_mfma_f32_16x16x32_bf16 v[80:83], v[210:213], v[176:179], v[80:83]
	v_mfma_f32_16x16x32_bf16 v[68:71], v[202:205], v[194:197], v[68:71]
	v_mfma_f32_16x16x32_bf16 v[64:67], v[210:213], v[194:197], v[64:67]
	v_mfma_f32_16x16x32_bf16 v[116:119], v[206:209], v[148:151], v[116:119]
	v_mfma_f32_16x16x32_bf16 v[112:115], v[214:217], v[148:151], v[112:115]
	v_mfma_f32_16x16x32_bf16 v[100:103], v[206:209], v[172:175], v[100:103]
	v_mfma_f32_16x16x32_bf16 v[96:99], v[214:217], v[172:175], v[96:99]
	v_mfma_f32_16x16x32_bf16 v[84:87], v[206:209], v[180:183], v[84:87]
	v_mfma_f32_16x16x32_bf16 v[80:83], v[214:217], v[180:183], v[80:83]
	v_mfma_f32_16x16x32_bf16 v[68:71], v[206:209], v[198:201], v[68:71]
	v_mfma_f32_16x16x32_bf16 v[64:67], v[214:217], v[198:201], v[64:67]
	s_setprio 0
	s_mov_b32 m0, s34
	v_lshl_add_u64 v[220:221], s[22:23], 0, v[152:153]
	s_barrier
	ds_read_b128 v[144:147], v191 offset:16384
	ds_read_b128 v[148:151], v191 offset:17408
	ds_read_b128 v[168:171], v191 offset:18432
	ds_read_b128 v[172:175], v191 offset:19456
	ds_read_b128 v[176:179], v191 offset:20480
	ds_read_b128 v[180:183], v191 offset:21504
	ds_read_b128 v[194:197], v191 offset:22528
	ds_read_b128 v[198:201], v191 offset:23552
	global_load_lds_dwordx4 v[220:221], off
	v_lshl_add_u64 v[222:223], s[22:23], 0, v[156:157]
	s_mov_b32 m0, s35
	s_nop 0
	global_load_lds_dwordx4 v[222:223], off
	s_barrier
	s_waitcnt lgkmcnt(0)
	s_setprio 1
	s_waitcnt lgkmcnt(0)
	v_mfma_f32_16x16x32_bf16 v[60:63], v[128:131], v[144:147], v[60:63]
	v_mfma_f32_16x16x32_bf16 v[56:59], v[136:139], v[144:147], v[56:59]
	v_mfma_f32_16x16x32_bf16 v[44:47], v[128:131], v[168:171], v[44:47]
	v_mfma_f32_16x16x32_bf16 v[40:43], v[136:139], v[168:171], v[40:43]
	v_mfma_f32_16x16x32_bf16 v[28:31], v[128:131], v[176:179], v[28:31]
	v_mfma_f32_16x16x32_bf16 v[24:27], v[136:139], v[176:179], v[24:27]
	v_mfma_f32_16x16x32_bf16 v[12:15], v[128:131], v[194:197], v[12:15]
	v_mfma_f32_16x16x32_bf16 v[8:11], v[136:139], v[194:197], v[8:11]
	v_mfma_f32_16x16x32_bf16 v[60:63], v[132:135], v[148:151], v[60:63]
	v_mfma_f32_16x16x32_bf16 v[56:59], v[140:143], v[148:151], v[56:59]
	v_mfma_f32_16x16x32_bf16 v[44:47], v[132:135], v[172:175], v[44:47]
	v_mfma_f32_16x16x32_bf16 v[40:43], v[140:143], v[172:175], v[40:43]
	v_mfma_f32_16x16x32_bf16 v[28:31], v[132:135], v[180:183], v[28:31]
	v_mfma_f32_16x16x32_bf16 v[24:27], v[140:143], v[180:183], v[24:27]
	v_mfma_f32_16x16x32_bf16 v[12:15], v[132:135], v[198:201], v[12:15]
	v_mfma_f32_16x16x32_bf16 v[8:11], v[140:143], v[198:201], v[8:11]
	s_setprio 0
	s_barrier
	s_add_u32 s14, s20, 0xb0000
	s_addc_u32 s15, s21, 0
	s_add_i32 s52, s44, s31
	v_lshl_add_u64 v[128:129], s[14:15], 0, v[154:155]
	s_mov_b32 m0, s52
	s_nop 0
	global_load_lds_dwordx4 v[128:129], off
	v_lshl_add_u64 v[128:129], s[14:15], 0, v[158:159]
	s_add_i32 m0, s52, 0x2000
	s_nop 0
	global_load_lds_dwordx4 v[128:129], off
	s_waitcnt vmcnt(6)
	s_barrier
	s_setprio 1
	v_mfma_f32_16x16x32_bf16 v[52:55], v[202:205], v[144:147], v[52:55]
	v_mfma_f32_16x16x32_bf16 v[48:51], v[210:213], v[144:147], v[48:51]
	v_mfma_f32_16x16x32_bf16 v[36:39], v[202:205], v[168:171], v[36:39]
	v_mfma_f32_16x16x32_bf16 v[32:35], v[210:213], v[168:171], v[32:35]
	v_mfma_f32_16x16x32_bf16 v[20:23], v[202:205], v[176:179], v[20:23]
	v_mfma_f32_16x16x32_bf16 v[16:19], v[210:213], v[176:179], v[16:19]
	v_mfma_f32_16x16x32_bf16 v[4:7], v[202:205], v[194:197], v[4:7]
	v_mfma_f32_16x16x32_bf16 v[0:3], v[210:213], v[194:197], v[0:3]
	v_mfma_f32_16x16x32_bf16 v[52:55], v[206:209], v[148:151], v[52:55]
	v_mfma_f32_16x16x32_bf16 v[48:51], v[214:217], v[148:151], v[48:51]
	v_mfma_f32_16x16x32_bf16 v[36:39], v[206:209], v[172:175], v[36:39]
	v_mfma_f32_16x16x32_bf16 v[32:35], v[214:217], v[172:175], v[32:35]
	v_mfma_f32_16x16x32_bf16 v[20:23], v[206:209], v[180:183], v[20:23]
	v_mfma_f32_16x16x32_bf16 v[16:19], v[214:217], v[180:183], v[16:19]
	v_mfma_f32_16x16x32_bf16 v[4:7], v[206:209], v[198:201], v[4:7]
	v_mfma_f32_16x16x32_bf16 v[0:3], v[214:217], v[198:201], v[0:3]
	s_setprio 0
	s_add_i32 s52, 0, 0x18000
	v_add_u32_e32 v140, s52, v187
	s_barrier
	ds_read_b128 v[128:131], v140
	ds_read_b128 v[132:135], v140 offset:1024
	ds_read_b128 v[136:139], v140 offset:2048
	ds_read_b128 v[140:143], v140 offset:3072
	s_add_u32 s14, s22, 0xb0000
	s_addc_u32 s15, s23, 0
	s_mov_b32 m0, s36
	v_lshl_add_u64 v[202:203], s[14:15], 0, v[152:153]
	ds_read_b128 v[144:147], v191 offset:32768
	ds_read_b128 v[148:151], v191 offset:33792
	ds_read_b128 v[168:171], v191 offset:34816
	ds_read_b128 v[172:175], v191 offset:35840
	ds_read_b128 v[176:179], v191 offset:36864
	ds_read_b128 v[180:183], v191 offset:37888
	ds_read_b128 v[194:197], v191 offset:38912
	ds_read_b128 v[198:201], v191 offset:39936
	global_load_lds_dwordx4 v[202:203], off
	v_lshl_add_u64 v[202:203], s[14:15], 0, v[156:157]
	s_mov_b32 m0, s37
	s_nop 0
	global_load_lds_dwordx4 v[202:203], off
	s_waitcnt lgkmcnt(8)
	s_barrier
	s_waitcnt lgkmcnt(0)
	s_setprio 1
	s_waitcnt lgkmcnt(0)
	v_mfma_f32_16x16x32_bf16 v[124:127], v[128:131], v[144:147], v[124:127]
	v_mfma_f32_16x16x32_bf16 v[120:123], v[136:139], v[144:147], v[120:123]
	v_mfma_f32_16x16x32_bf16 v[108:111], v[128:131], v[168:171], v[108:111]
	v_mfma_f32_16x16x32_bf16 v[104:107], v[136:139], v[168:171], v[104:107]
	v_mfma_f32_16x16x32_bf16 v[92:95], v[128:131], v[176:179], v[92:95]
	v_mfma_f32_16x16x32_bf16 v[88:91], v[136:139], v[176:179], v[88:91]
	v_mfma_f32_16x16x32_bf16 v[76:79], v[128:131], v[194:197], v[76:79]
	v_mfma_f32_16x16x32_bf16 v[72:75], v[136:139], v[194:197], v[72:75]
	v_mfma_f32_16x16x32_bf16 v[124:127], v[132:135], v[148:151], v[124:127]
	v_mfma_f32_16x16x32_bf16 v[120:123], v[140:143], v[148:151], v[120:123]
	v_mfma_f32_16x16x32_bf16 v[108:111], v[132:135], v[172:175], v[108:111]
	v_mfma_f32_16x16x32_bf16 v[104:107], v[140:143], v[172:175], v[104:107]
	v_mfma_f32_16x16x32_bf16 v[92:95], v[132:135], v[180:183], v[92:95]
	v_mfma_f32_16x16x32_bf16 v[88:91], v[140:143], v[180:183], v[88:91]
	v_mfma_f32_16x16x32_bf16 v[76:79], v[132:135], v[198:201], v[76:79]
	v_mfma_f32_16x16x32_bf16 v[72:75], v[140:143], v[198:201], v[72:75]
	s_setprio 0
	s_barrier
	s_add_i32 s22, 0, 0x1c000
	s_add_i32 s14, s52, s31
	v_add_u32_e32 v214, s22, v187
	v_lshl_add_u64 v[184:185], v[184:185], 0, s[12:13]
	s_mov_b32 m0, s14
	ds_read_b128 v[202:205], v214
	ds_read_b128 v[206:209], v214 offset:1024
	ds_read_b128 v[210:213], v214 offset:2048
	ds_read_b128 v[214:217], v214 offset:3072
	global_load_lds_dwordx4 v[184:185], off
	v_lshl_add_u64 v[184:185], v[218:219], 0, s[12:13]
	s_add_i32 m0, s14, 0x2000
	s_nop 0
	global_load_lds_dwordx4 v[184:185], off
	s_barrier
	s_waitcnt lgkmcnt(0)
	s_setprio 1
	s_waitcnt lgkmcnt(0)
	v_mfma_f32_16x16x32_bf16 v[116:119], v[202:205], v[144:147], v[116:119]
	v_mfma_f32_16x16x32_bf16 v[112:115], v[210:213], v[144:147], v[112:115]
	v_mfma_f32_16x16x32_bf16 v[100:103], v[202:205], v[168:171], v[100:103]
	v_mfma_f32_16x16x32_bf16 v[96:99], v[210:213], v[168:171], v[96:99]
	v_mfma_f32_16x16x32_bf16 v[84:87], v[202:205], v[176:179], v[84:87]
	v_mfma_f32_16x16x32_bf16 v[80:83], v[210:213], v[176:179], v[80:83]
	v_mfma_f32_16x16x32_bf16 v[68:71], v[202:205], v[194:197], v[68:71]
	v_mfma_f32_16x16x32_bf16 v[64:67], v[210:213], v[194:197], v[64:67]
	v_mfma_f32_16x16x32_bf16 v[116:119], v[206:209], v[148:151], v[116:119]
	v_mfma_f32_16x16x32_bf16 v[112:115], v[214:217], v[148:151], v[112:115]
	v_mfma_f32_16x16x32_bf16 v[100:103], v[206:209], v[172:175], v[100:103]
	v_mfma_f32_16x16x32_bf16 v[96:99], v[214:217], v[172:175], v[96:99]
	v_mfma_f32_16x16x32_bf16 v[84:87], v[206:209], v[180:183], v[84:87]
	v_mfma_f32_16x16x32_bf16 v[80:83], v[214:217], v[180:183], v[80:83]
	v_mfma_f32_16x16x32_bf16 v[68:71], v[206:209], v[198:201], v[68:71]
	v_mfma_f32_16x16x32_bf16 v[64:67], v[214:217], v[198:201], v[64:67]
	s_setprio 0
	s_mov_b32 m0, s39
	v_lshl_add_u64 v[184:185], v[220:221], 0, s[12:13]
	s_barrier
	ds_read_b128 v[144:147], v191 offset:49152
	ds_read_b128 v[148:151], v191 offset:50176
	ds_read_b128 v[168:171], v191 offset:51200
	ds_read_b128 v[172:175], v191 offset:52224
	ds_read_b128 v[176:179], v191 offset:53248
	ds_read_b128 v[180:183], v191 offset:54272
	ds_read_b128 v[194:197], v191 offset:55296
	ds_read_b128 v[198:201], v191 offset:56320
	global_load_lds_dwordx4 v[184:185], off
	v_lshl_add_u64 v[184:185], v[222:223], 0, s[12:13]
	s_mov_b32 m0, s40
	s_nop 0
	global_load_lds_dwordx4 v[184:185], off
	s_barrier
	s_waitcnt lgkmcnt(0)
	s_setprio 1
	s_waitcnt lgkmcnt(0)
	v_mfma_f32_16x16x32_bf16 v[60:63], v[128:131], v[144:147], v[60:63]
	v_mfma_f32_16x16x32_bf16 v[56:59], v[136:139], v[144:147], v[56:59]
	v_mfma_f32_16x16x32_bf16 v[44:47], v[128:131], v[168:171], v[44:47]
	v_mfma_f32_16x16x32_bf16 v[40:43], v[136:139], v[168:171], v[40:43]
	v_mfma_f32_16x16x32_bf16 v[28:31], v[128:131], v[176:179], v[28:31]
	v_mfma_f32_16x16x32_bf16 v[24:27], v[136:139], v[176:179], v[24:27]
	v_mfma_f32_16x16x32_bf16 v[12:15], v[128:131], v[194:197], v[12:15]
	v_mfma_f32_16x16x32_bf16 v[8:11], v[136:139], v[194:197], v[8:11]
	v_mfma_f32_16x16x32_bf16 v[60:63], v[132:135], v[148:151], v[60:63]
	v_mfma_f32_16x16x32_bf16 v[56:59], v[140:143], v[148:151], v[56:59]
	v_mfma_f32_16x16x32_bf16 v[44:47], v[132:135], v[172:175], v[44:47]
	v_mfma_f32_16x16x32_bf16 v[40:43], v[140:143], v[172:175], v[40:43]
	v_mfma_f32_16x16x32_bf16 v[28:31], v[132:135], v[180:183], v[28:31]
	v_mfma_f32_16x16x32_bf16 v[24:27], v[140:143], v[180:183], v[24:27]
	v_mfma_f32_16x16x32_bf16 v[12:15], v[132:135], v[198:201], v[12:15]
	v_mfma_f32_16x16x32_bf16 v[8:11], v[140:143], v[198:201], v[8:11]
	s_setprio 0
	s_barrier
	s_add_u32 s14, s20, 0xb0080
	s_addc_u32 s15, s21, 0
	s_add_i32 s20, s22, s31
	v_lshl_add_u64 v[128:129], s[14:15], 0, v[154:155]
	s_mov_b32 m0, s20
	s_nop 0
	global_load_lds_dwordx4 v[128:129], off
	v_lshl_add_u64 v[128:129], s[14:15], 0, v[158:159]
	s_add_i32 m0, s20, 0x2000
	s_nop 0
	global_load_lds_dwordx4 v[128:129], off
	s_waitcnt vmcnt(6)
	s_barrier
	s_setprio 1
	v_mfma_f32_16x16x32_bf16 v[52:55], v[202:205], v[144:147], v[52:55]
	v_mfma_f32_16x16x32_bf16 v[48:51], v[210:213], v[144:147], v[48:51]
	v_mfma_f32_16x16x32_bf16 v[36:39], v[202:205], v[168:171], v[36:39]
	v_mfma_f32_16x16x32_bf16 v[32:35], v[210:213], v[168:171], v[32:35]
	v_mfma_f32_16x16x32_bf16 v[20:23], v[202:205], v[176:179], v[20:23]
	v_mfma_f32_16x16x32_bf16 v[16:19], v[210:213], v[176:179], v[16:19]
	v_mfma_f32_16x16x32_bf16 v[4:7], v[202:205], v[194:197], v[4:7]
	v_mfma_f32_16x16x32_bf16 v[0:3], v[210:213], v[194:197], v[0:3]
	v_mfma_f32_16x16x32_bf16 v[52:55], v[206:209], v[148:151], v[52:55]
	v_mfma_f32_16x16x32_bf16 v[48:51], v[214:217], v[148:151], v[48:51]
	v_mfma_f32_16x16x32_bf16 v[36:39], v[206:209], v[172:175], v[36:39]
	v_mfma_f32_16x16x32_bf16 v[32:35], v[214:217], v[172:175], v[32:35]
	v_mfma_f32_16x16x32_bf16 v[20:23], v[206:209], v[180:183], v[20:23]
	v_mfma_f32_16x16x32_bf16 v[16:19], v[214:217], v[180:183], v[16:19]
	v_mfma_f32_16x16x32_bf16 v[4:7], v[206:209], v[198:201], v[4:7]
	v_mfma_f32_16x16x32_bf16 v[0:3], v[214:217], v[198:201], v[0:3]
	s_setprio 0
	s_add_i32 s51, s51, 2
	s_add_u32 s49, s49, 0x100
	s_addc_u32 s50, s50, 0
	s_cmp_gt_u32 s51, 41
	s_mov_b64 s[14:15], s[18:19]
	s_barrier
	s_cbranch_scc0 .LBB0_554
	v_lshl_or_b32 v168, s10, 8, v189
	v_lshl_add_u32 v170, s48, 8, v186
	v_ashrrev_i32_e32 v169, 31, v168
	v_lshlrev_b64 v[202:203], 1, v[168:169]
	v_ashrrev_i32_e32 v171, 31, v170
	v_or_b32_e32 v182, 16, v170
	v_lshl_add_u64 v[172:173], s[64:65], 0, v[202:203]
	v_lshlrev_b64 v[204:205], 11, v[170:171]
	v_ashrrev_i32_e32 v183, 31, v182
	v_or_b32_e32 v178, 32, v170
	v_lshl_add_u64 v[128:129], v[172:173], 0, v[204:205]
	v_lshlrev_b64 v[184:185], 11, v[182:183]
	v_ashrrev_i32_e32 v179, 31, v178
	v_or_b32_e32 v174, 48, v170
	global_load_dwordx4 v[194:197], v[128:129], off
	global_load_dwordx4 v[198:201], v[128:129], off offset:256
	v_lshl_add_u64 v[128:129], v[172:173], 0, v[184:185]
	v_lshlrev_b64 v[180:181], 11, v[178:179]
	v_ashrrev_i32_e32 v175, 31, v174
	global_load_dwordx4 v[148:151], v[128:129], off
	global_load_dwordx4 v[144:147], v[128:129], off offset:256
	v_lshl_add_u64 v[128:129], v[172:173], 0, v[180:181]
	v_lshlrev_b64 v[176:177], 11, v[174:175]
	global_load_dwordx4 v[140:143], v[128:129], off
	global_load_dwordx4 v[136:139], v[128:129], off offset:256
	v_lshl_add_u64 v[128:129], v[172:173], 0, v[176:177]
	global_load_dwordx4 v[132:135], v[128:129], off
	s_nop 0
	global_load_dwordx4 v[128:131], v[128:129], off offset:256
	s_lshl_b32 s14, s10, 2
	s_ashr_i32 s15, s14, 31
	s_waitcnt vmcnt(0)
	v_lshlrev_b32_e32 v206, 16, v194
	v_and_b32_e32 v207, 0xffff0000, v194
	v_lshlrev_b32_e32 v194, 16, v195
	v_and_b32_e32 v195, 0xffff0000, v195
	v_lshlrev_b32_e32 v208, 16, v196
	v_and_b32_e32 v209, 0xffff0000, v196
	v_lshlrev_b32_e32 v196, 16, v197
	v_and_b32_e32 v197, 0xffff0000, v197
	v_pk_add_f32 v[126:127], v[126:127], v[194:195]
	v_pk_add_f32 v[124:125], v[124:125], v[206:207]
	v_pk_add_f32 v[194:195], v[122:123], v[196:197]
	v_pk_add_f32 v[122:123], v[120:121], v[208:209]
	v_mul_f32_e32 v120, v125, v125
	v_mul_f32_e32 v121, v127, v127
	v_fmac_f32_e32 v120, v124, v124
	v_fmac_f32_e32 v121, v126, v126
	v_add_f32_e32 v120, v120, v121
	v_mul_f32_e32 v121, v123, v123
	v_mul_f32_e32 v196, v195, v195
	v_fmac_f32_e32 v121, v122, v122
	v_fmac_f32_e32 v196, v194, v194
	v_add_f32_e32 v121, v121, v196
	v_add_f32_e32 v206, v120, v121
	v_cvt_pk_bf16_f32 v120, v124, v125
	v_cvt_pk_bf16_f32 v121, v126, v127
	v_lshlrev_b32_e32 v124, 16, v198
	v_and_b32_e32 v125, 0xffff0000, v198
	v_lshlrev_b32_e32 v126, 16, v199
	v_and_b32_e32 v127, 0xffff0000, v199
	v_cvt_pk_bf16_f32 v122, v122, v123
	v_cvt_pk_bf16_f32 v123, v194, v195
	v_lshlrev_b32_e32 v194, 16, v200
	v_and_b32_e32 v195, 0xffff0000, v200
	v_pk_add_f32 v[118:119], v[118:119], v[126:127]
	v_pk_add_f32 v[116:117], v[116:117], v[124:125]
	v_lshlrev_b32_e32 v196, 16, v201
	v_and_b32_e32 v197, 0xffff0000, v201
	v_pk_add_f32 v[126:127], v[112:113], v[194:195]
	v_mul_f32_e32 v112, v117, v117
	v_mul_f32_e32 v113, v119, v119
	v_pk_add_f32 v[124:125], v[114:115], v[196:197]
	v_fmac_f32_e32 v112, v116, v116
	v_fmac_f32_e32 v113, v118, v118
	v_add_f32_e32 v112, v112, v113
	v_mul_f32_e32 v113, v127, v127
	v_mul_f32_e32 v114, v125, v125
	v_fmac_f32_e32 v113, v126, v126
	v_fmac_f32_e32 v114, v124, v124
	v_add_f32_e32 v113, v113, v114
	v_add_f32_e32 v112, v112, v113
	v_and_b32_e32 v114, 64, v193
	v_add_f32_e32 v113, v206, v112
	v_xor_b32_e32 v112, 16, v193
	v_add_u32_e32 v196, 64, v114
	v_cmp_lt_i32_e32 vcc, v112, v196
	v_lshl_add_u64 v[114:115], s[64:65], 0, v[204:205]
	v_lshl_add_u64 v[194:195], v[114:115], 0, v[202:203]
	v_cndmask_b32_e32 v112, v193, v112, vcc
	v_lshlrev_b32_e32 v112, 2, v112
	ds_bpermute_b32 v197, v112, v113
	global_store_dwordx4 v[194:195], v[120:123], off nt
	v_cvt_pk_bf16_f32 v116, v116, v117
	v_cvt_pk_bf16_f32 v117, v118, v119
	v_cvt_pk_bf16_f32 v118, v126, v127
	s_waitcnt lgkmcnt(0)
	v_add_f32_e32 v114, v113, v197
	v_xor_b32_e32 v113, 32, v193
	v_cmp_lt_i32_e32 vcc, v113, v196
	v_cvt_pk_bf16_f32 v119, v124, v125
	global_store_dwordx4 v[194:195], v[116:119], off offset:256 nt
	s_nop 0
	v_cndmask_b32_e32 v113, v193, v113, vcc
	v_lshlrev_b32_e32 v113, 2, v113
	ds_bpermute_b32 v115, v113, v114
	s_and_saveexec_b64 s[18:19], s[2:3]
	s_cbranch_execz .LBB0_557
	s_waitcnt lgkmcnt(0)
	v_add_f32_e32 v116, v114, v115
	v_lshlrev_b64 v[114:115], 6, v[170:171]
	v_lshl_add_u64 v[114:115], s[74:75], 0, v[114:115]
	v_lshl_add_u64 v[114:115], s[14:15], 2, v[114:115]
	s_lshl_b32 s10, s38, 2
	v_lshl_add_u64 v[114:115], v[114:115], 0, s[10:11]
	global_store_dword v[114:115], v116, off
.LBB0_557:
	s_or_b64 exec, exec, s[18:19]
	v_lshlrev_b32_e32 v114, 16, v148
	s_waitcnt lgkmcnt(0)
	v_and_b32_e32 v115, 0xffff0000, v148
	v_lshlrev_b32_e32 v116, 16, v149
	v_and_b32_e32 v117, 0xffff0000, v149
	v_lshlrev_b32_e32 v118, 16, v150
	v_and_b32_e32 v119, 0xffff0000, v150
	v_lshlrev_b32_e32 v120, 16, v151
	v_and_b32_e32 v121, 0xffff0000, v151
	v_pk_add_f32 v[110:111], v[110:111], v[116:117]
	v_pk_add_f32 v[108:109], v[108:109], v[114:115]
	v_pk_add_f32 v[114:115], v[106:107], v[120:121]
	v_pk_add_f32 v[106:107], v[104:105], v[118:119]
	v_mul_f32_e32 v104, v109, v109
	v_mul_f32_e32 v105, v111, v111
	v_fmac_f32_e32 v104, v108, v108
	v_fmac_f32_e32 v105, v110, v110
	v_add_f32_e32 v104, v104, v105
	v_mul_f32_e32 v105, v107, v107
	v_mul_f32_e32 v116, v115, v115
	v_fmac_f32_e32 v105, v106, v106
	v_fmac_f32_e32 v116, v114, v114
	v_add_f32_e32 v105, v105, v116
	v_add_f32_e32 v118, v104, v105
	v_cvt_pk_bf16_f32 v104, v108, v109
	v_cvt_pk_bf16_f32 v105, v110, v111
	v_lshlrev_b32_e32 v108, 16, v144
	v_and_b32_e32 v109, 0xffff0000, v144
	v_lshlrev_b32_e32 v110, 16, v145
	v_and_b32_e32 v111, 0xffff0000, v145
	v_cvt_pk_bf16_f32 v106, v106, v107
	v_cvt_pk_bf16_f32 v107, v114, v115
	v_lshlrev_b32_e32 v114, 16, v146
	v_and_b32_e32 v115, 0xffff0000, v146
	v_pk_add_f32 v[102:103], v[102:103], v[110:111]
	v_pk_add_f32 v[100:101], v[100:101], v[108:109]
	v_lshlrev_b32_e32 v116, 16, v147
	v_and_b32_e32 v117, 0xffff0000, v147
	v_pk_add_f32 v[110:111], v[96:97], v[114:115]
	v_mul_f32_e32 v96, v101, v101
	v_mul_f32_e32 v97, v103, v103
	v_pk_add_f32 v[108:109], v[98:99], v[116:117]
	v_fmac_f32_e32 v96, v100, v100
	v_fmac_f32_e32 v97, v102, v102
	v_add_f32_e32 v96, v96, v97
	v_mul_f32_e32 v97, v111, v111
	v_mul_f32_e32 v98, v109, v109
	v_fmac_f32_e32 v97, v110, v110
	v_fmac_f32_e32 v98, v108, v108
	v_add_f32_e32 v97, v97, v98
	v_add_f32_e32 v96, v96, v97
	v_add_f32_e32 v99, v118, v96
	ds_bpermute_b32 v116, v112, v99
	v_lshl_add_u64 v[96:97], s[64:65], 0, v[184:185]
	v_lshl_add_u64 v[114:115], v[168:169], 1, v[96:97]
	global_store_dwordx4 v[114:115], v[104:107], off nt
	v_cvt_pk_bf16_f32 v98, v100, v101
	s_waitcnt lgkmcnt(0)
	v_add_f32_e32 v96, v99, v116
	ds_bpermute_b32 v97, v113, v96
	v_cvt_pk_bf16_f32 v99, v102, v103
	v_cvt_pk_bf16_f32 v100, v110, v111
	v_cvt_pk_bf16_f32 v101, v108, v109
	global_store_dwordx4 v[114:115], v[98:101], off offset:256 nt
	s_and_saveexec_b64 s[18:19], s[2:3]
	s_cbranch_execz .LBB0_559
	s_waitcnt lgkmcnt(0)
	v_add_f32_e32 v98, v96, v97
	v_lshlrev_b64 v[96:97], 6, v[182:183]
	v_lshl_add_u64 v[96:97], s[74:75], 0, v[96:97]
	v_lshl_add_u64 v[96:97], s[14:15], 2, v[96:97]
	s_lshl_b32 s10, s38, 2
	v_lshl_add_u64 v[96:97], v[96:97], 0, s[10:11]
	global_store_dword v[96:97], v98, off
.LBB0_559:
	s_or_b64 exec, exec, s[18:19]
	v_lshlrev_b32_e32 v96, 16, v140
	s_waitcnt lgkmcnt(0)
	v_and_b32_e32 v97, 0xffff0000, v140
	v_lshlrev_b32_e32 v98, 16, v141
	v_and_b32_e32 v99, 0xffff0000, v141
	v_lshlrev_b32_e32 v100, 16, v142
	v_and_b32_e32 v101, 0xffff0000, v142
	v_lshlrev_b32_e32 v102, 16, v143
	v_and_b32_e32 v103, 0xffff0000, v143
	v_pk_add_f32 v[94:95], v[94:95], v[98:99]
	v_pk_add_f32 v[92:93], v[92:93], v[96:97]
	v_pk_add_f32 v[96:97], v[90:91], v[102:103]
	v_pk_add_f32 v[90:91], v[88:89], v[100:101]
	v_mul_f32_e32 v88, v93, v93
	v_mul_f32_e32 v89, v95, v95
	v_fmac_f32_e32 v88, v92, v92
	v_fmac_f32_e32 v89, v94, v94
	v_add_f32_e32 v88, v88, v89
	v_mul_f32_e32 v89, v91, v91
	v_mul_f32_e32 v98, v97, v97
	v_fmac_f32_e32 v89, v90, v90
	v_fmac_f32_e32 v98, v96, v96
	v_add_f32_e32 v89, v89, v98
	v_add_f32_e32 v100, v88, v89
	v_cvt_pk_bf16_f32 v88, v92, v93
	v_cvt_pk_bf16_f32 v89, v94, v95
	v_lshlrev_b32_e32 v92, 16, v136
	v_and_b32_e32 v93, 0xffff0000, v136
	v_lshlrev_b32_e32 v94, 16, v137
	v_and_b32_e32 v95, 0xffff0000, v137
	v_cvt_pk_bf16_f32 v90, v90, v91
	v_cvt_pk_bf16_f32 v91, v96, v97
	v_lshlrev_b32_e32 v96, 16, v138
	v_and_b32_e32 v97, 0xffff0000, v138
	v_pk_add_f32 v[86:87], v[86:87], v[94:95]
	v_pk_add_f32 v[84:85], v[84:85], v[92:93]
	v_lshlrev_b32_e32 v98, 16, v139
	v_and_b32_e32 v99, 0xffff0000, v139
	v_pk_add_f32 v[94:95], v[80:81], v[96:97]
	v_mul_f32_e32 v80, v85, v85
	v_mul_f32_e32 v81, v87, v87
	v_pk_add_f32 v[92:93], v[82:83], v[98:99]
	v_fmac_f32_e32 v80, v84, v84
	v_fmac_f32_e32 v81, v86, v86
	v_add_f32_e32 v80, v80, v81
	v_mul_f32_e32 v81, v95, v95
	v_mul_f32_e32 v82, v93, v93
	v_fmac_f32_e32 v81, v94, v94
	v_fmac_f32_e32 v82, v92, v92
	v_add_f32_e32 v81, v81, v82
	v_add_f32_e32 v80, v80, v81
	v_add_f32_e32 v83, v100, v80
	ds_bpermute_b32 v98, v112, v83
	v_lshl_add_u64 v[80:81], s[64:65], 0, v[180:181]
	v_lshl_add_u64 v[96:97], v[168:169], 1, v[80:81]
	global_store_dwordx4 v[96:97], v[88:91], off nt
	v_cvt_pk_bf16_f32 v82, v84, v85
	s_waitcnt lgkmcnt(0)
	v_add_f32_e32 v80, v83, v98
	ds_bpermute_b32 v81, v113, v80
	v_cvt_pk_bf16_f32 v83, v86, v87
	v_cvt_pk_bf16_f32 v84, v94, v95
	v_cvt_pk_bf16_f32 v85, v92, v93
	global_store_dwordx4 v[96:97], v[82:85], off offset:256 nt
	s_and_saveexec_b64 s[18:19], s[2:3]
	s_cbranch_execz .LBB0_561
	s_waitcnt lgkmcnt(0)
	v_add_f32_e32 v82, v80, v81
	v_lshlrev_b64 v[80:81], 6, v[178:179]
	v_lshl_add_u64 v[80:81], s[74:75], 0, v[80:81]
	v_lshl_add_u64 v[80:81], s[14:15], 2, v[80:81]
	s_lshl_b32 s10, s38, 2
	v_lshl_add_u64 v[80:81], v[80:81], 0, s[10:11]
	global_store_dword v[80:81], v82, off
.LBB0_561:
	s_or_b64 exec, exec, s[18:19]
	v_lshlrev_b32_e32 v80, 16, v132
	s_waitcnt lgkmcnt(0)
	v_and_b32_e32 v81, 0xffff0000, v132
	v_lshlrev_b32_e32 v82, 16, v133
	v_and_b32_e32 v83, 0xffff0000, v133
	v_lshlrev_b32_e32 v84, 16, v134
	v_and_b32_e32 v85, 0xffff0000, v134
	v_lshlrev_b32_e32 v86, 16, v135
	v_and_b32_e32 v87, 0xffff0000, v135
	v_pk_add_f32 v[78:79], v[78:79], v[82:83]
	v_pk_add_f32 v[76:77], v[76:77], v[80:81]
	v_pk_add_f32 v[80:81], v[74:75], v[86:87]
	v_pk_add_f32 v[74:75], v[72:73], v[84:85]
	v_mul_f32_e32 v72, v77, v77
	v_mul_f32_e32 v73, v79, v79
	v_fmac_f32_e32 v72, v76, v76
	v_fmac_f32_e32 v73, v78, v78
	v_add_f32_e32 v72, v72, v73
	v_mul_f32_e32 v73, v75, v75
	v_mul_f32_e32 v82, v81, v81
	v_fmac_f32_e32 v73, v74, v74
	v_fmac_f32_e32 v82, v80, v80
	v_add_f32_e32 v73, v73, v82
	v_add_f32_e32 v84, v72, v73
	v_cvt_pk_bf16_f32 v72, v76, v77
	v_cvt_pk_bf16_f32 v73, v78, v79
	v_lshlrev_b32_e32 v76, 16, v128
	v_and_b32_e32 v77, 0xffff0000, v128
	v_lshlrev_b32_e32 v78, 16, v129
	v_and_b32_e32 v79, 0xffff0000, v129
	v_cvt_pk_bf16_f32 v74, v74, v75
	v_cvt_pk_bf16_f32 v75, v80, v81
	v_lshlrev_b32_e32 v80, 16, v130
	v_and_b32_e32 v81, 0xffff0000, v130
	v_pk_add_f32 v[70:71], v[70:71], v[78:79]
	v_pk_add_f32 v[68:69], v[68:69], v[76:77]
	v_lshlrev_b32_e32 v82, 16, v131
	v_and_b32_e32 v83, 0xffff0000, v131
	v_pk_add_f32 v[78:79], v[64:65], v[80:81]
	v_mul_f32_e32 v64, v69, v69
	v_mul_f32_e32 v65, v71, v71
	v_pk_add_f32 v[76:77], v[66:67], v[82:83]
	v_fmac_f32_e32 v64, v68, v68
	v_fmac_f32_e32 v65, v70, v70
	v_add_f32_e32 v64, v64, v65
	v_mul_f32_e32 v65, v79, v79
	v_mul_f32_e32 v66, v77, v77
	v_fmac_f32_e32 v65, v78, v78
	v_fmac_f32_e32 v66, v76, v76
	v_add_f32_e32 v65, v65, v66
	v_add_f32_e32 v64, v64, v65
	v_add_f32_e32 v67, v84, v64
	ds_bpermute_b32 v82, v112, v67
	v_lshl_add_u64 v[64:65], s[64:65], 0, v[176:177]
	v_lshl_add_u64 v[80:81], v[168:169], 1, v[64:65]
	global_store_dwordx4 v[80:81], v[72:75], off nt
	v_cvt_pk_bf16_f32 v66, v68, v69
	s_waitcnt lgkmcnt(0)
	v_add_f32_e32 v64, v67, v82
	ds_bpermute_b32 v65, v113, v64
	v_cvt_pk_bf16_f32 v67, v70, v71
	v_cvt_pk_bf16_f32 v68, v78, v79
	v_cvt_pk_bf16_f32 v69, v76, v77
	global_store_dwordx4 v[80:81], v[66:69], off offset:256 nt
	s_and_saveexec_b64 s[18:19], s[2:3]
	s_cbranch_execz .LBB0_563
	s_waitcnt lgkmcnt(0)
	v_add_f32_e32 v66, v64, v65
	v_lshlrev_b64 v[64:65], 6, v[174:175]
	v_lshl_add_u64 v[64:65], s[74:75], 0, v[64:65]
	v_lshl_add_u64 v[64:65], s[14:15], 2, v[64:65]
	s_lshl_b32 s10, s38, 2
	v_lshl_add_u64 v[64:65], v[64:65], 0, s[10:11]
	global_store_dword v[64:65], v66, off
.LBB0_563:
	s_or_b64 exec, exec, s[18:19]
	v_add_u32_e32 v100, 0x80, v170
	v_ashrrev_i32_e32 v101, 31, v100
	v_add_u32_e32 v96, 0x90, v170
	v_lshlrev_b64 v[110:111], 11, v[100:101]
	v_ashrrev_i32_e32 v97, 31, v96
	v_add_u32_e32 v92, 0xa0, v170
	s_waitcnt lgkmcnt(0)
	v_lshl_add_u64 v[64:65], v[172:173], 0, v[110:111]
	v_lshlrev_b64 v[98:99], 11, v[96:97]
	v_ashrrev_i32_e32 v93, 31, v92
	v_add_u32_e32 v88, 0xb0, v170
	global_load_dwordx4 v[102:105], v[64:65], off
	global_load_dwordx4 v[106:109], v[64:65], off offset:256
	v_lshl_add_u64 v[64:65], v[172:173], 0, v[98:99]
	v_lshlrev_b64 v[94:95], 11, v[92:93]
	v_ashrrev_i32_e32 v89, 31, v88
	global_load_dwordx4 v[84:87], v[64:65], off
	global_load_dwordx4 v[80:83], v[64:65], off offset:256
	v_lshl_add_u64 v[64:65], v[172:173], 0, v[94:95]
	v_lshlrev_b64 v[90:91], 11, v[88:89]
	global_load_dwordx4 v[76:79], v[64:65], off
	global_load_dwordx4 v[72:75], v[64:65], off offset:256
	v_lshl_add_u64 v[64:65], v[172:173], 0, v[90:91]
	global_load_dwordx4 v[68:71], v[64:65], off
	s_nop 0
	global_load_dwordx4 v[64:67], v[64:65], off offset:256
	s_waitcnt vmcnt(7)
	v_lshlrev_b32_e32 v114, 16, v102
	v_and_b32_e32 v115, 0xffff0000, v102
	v_lshlrev_b32_e32 v102, 16, v103
	v_and_b32_e32 v103, 0xffff0000, v103
	v_lshlrev_b32_e32 v116, 16, v104
	v_and_b32_e32 v117, 0xffff0000, v104
	v_lshlrev_b32_e32 v104, 16, v105
	v_and_b32_e32 v105, 0xffff0000, v105
	v_pk_add_f32 v[62:63], v[62:63], v[102:103]
	v_pk_add_f32 v[60:61], v[60:61], v[114:115]
	v_pk_add_f32 v[102:103], v[58:59], v[104:105]
	v_pk_add_f32 v[58:59], v[56:57], v[116:117]
	v_mul_f32_e32 v56, v61, v61
	v_mul_f32_e32 v57, v63, v63
	v_fmac_f32_e32 v56, v60, v60
	v_fmac_f32_e32 v57, v62, v62
	v_add_f32_e32 v56, v56, v57
	v_mul_f32_e32 v57, v59, v59
	v_mul_f32_e32 v104, v103, v103
	v_fmac_f32_e32 v57, v58, v58
	v_fmac_f32_e32 v104, v102, v102
	v_add_f32_e32 v57, v57, v104
	v_add_f32_e32 v114, v56, v57
	v_cvt_pk_bf16_f32 v56, v60, v61
	v_cvt_pk_bf16_f32 v57, v62, v63
	s_waitcnt vmcnt(6)
	v_lshlrev_b32_e32 v60, 16, v106
	v_and_b32_e32 v61, 0xffff0000, v106
	v_lshlrev_b32_e32 v62, 16, v107
	v_and_b32_e32 v63, 0xffff0000, v107
	v_cvt_pk_bf16_f32 v58, v58, v59
	v_cvt_pk_bf16_f32 v59, v102, v103
	v_lshlrev_b32_e32 v102, 16, v108
	v_and_b32_e32 v103, 0xffff0000, v108
	v_pk_add_f32 v[54:55], v[54:55], v[62:63]
	v_pk_add_f32 v[52:53], v[52:53], v[60:61]
	v_lshlrev_b32_e32 v104, 16, v109
	v_and_b32_e32 v105, 0xffff0000, v109
	v_pk_add_f32 v[62:63], v[48:49], v[102:103]
	v_mul_f32_e32 v48, v53, v53
	v_mul_f32_e32 v49, v55, v55
	v_pk_add_f32 v[60:61], v[50:51], v[104:105]
	v_fmac_f32_e32 v48, v52, v52
	v_fmac_f32_e32 v49, v54, v54
	v_add_f32_e32 v48, v48, v49
	v_mul_f32_e32 v49, v63, v63
	v_mul_f32_e32 v50, v61, v61
	v_fmac_f32_e32 v49, v62, v62
	v_fmac_f32_e32 v50, v60, v60
	v_add_f32_e32 v49, v49, v50
	v_add_f32_e32 v48, v48, v49
	v_add_f32_e32 v51, v114, v48
	ds_bpermute_b32 v104, v112, v51
	v_lshl_add_u64 v[48:49], s[64:65], 0, v[110:111]
	v_lshl_add_u64 v[102:103], v[168:169], 1, v[48:49]
	global_store_dwordx4 v[102:103], v[56:59], off nt
	v_cvt_pk_bf16_f32 v50, v52, v53
	s_waitcnt lgkmcnt(0)
	v_add_f32_e32 v48, v51, v104
	ds_bpermute_b32 v49, v113, v48
	v_cvt_pk_bf16_f32 v51, v54, v55
	v_cvt_pk_bf16_f32 v52, v62, v63
	v_cvt_pk_bf16_f32 v53, v60, v61
	global_store_dwordx4 v[102:103], v[50:53], off offset:256 nt
	s_and_saveexec_b64 s[18:19], s[2:3]
	s_cbranch_execz .LBB0_565
	s_waitcnt lgkmcnt(0)
	v_add_f32_e32 v50, v48, v49
	v_lshlrev_b64 v[48:49], 6, v[100:101]
	v_lshl_add_u64 v[48:49], s[74:75], 0, v[48:49]
	v_lshl_add_u64 v[48:49], s[14:15], 2, v[48:49]
	s_lshl_b32 s10, s38, 2
	v_lshl_add_u64 v[48:49], v[48:49], 0, s[10:11]
	global_store_dword v[48:49], v50, off
.LBB0_565:
	s_or_b64 exec, exec, s[18:19]
	s_waitcnt vmcnt(7)
	v_lshlrev_b32_e32 v48, 16, v84
	s_waitcnt lgkmcnt(0)
	v_and_b32_e32 v49, 0xffff0000, v84
	v_lshlrev_b32_e32 v50, 16, v85
	v_and_b32_e32 v51, 0xffff0000, v85
	v_lshlrev_b32_e32 v52, 16, v86
	v_and_b32_e32 v53, 0xffff0000, v86
	v_lshlrev_b32_e32 v54, 16, v87
	v_and_b32_e32 v55, 0xffff0000, v87
	v_pk_add_f32 v[46:47], v[46:47], v[50:51]
	v_pk_add_f32 v[44:45], v[44:45], v[48:49]
	v_pk_add_f32 v[48:49], v[42:43], v[54:55]
	v_pk_add_f32 v[42:43], v[40:41], v[52:53]
	v_mul_f32_e32 v40, v45, v45
	v_mul_f32_e32 v41, v47, v47
	v_fmac_f32_e32 v40, v44, v44
	v_fmac_f32_e32 v41, v46, v46
	v_add_f32_e32 v40, v40, v41
	v_mul_f32_e32 v41, v43, v43
	v_mul_f32_e32 v50, v49, v49
	v_fmac_f32_e32 v41, v42, v42
	v_fmac_f32_e32 v50, v48, v48
	v_add_f32_e32 v41, v41, v50
	v_add_f32_e32 v52, v40, v41
	v_cvt_pk_bf16_f32 v40, v44, v45
	v_cvt_pk_bf16_f32 v41, v46, v47
	s_waitcnt vmcnt(6)
	v_lshlrev_b32_e32 v44, 16, v80
	v_and_b32_e32 v45, 0xffff0000, v80
	v_lshlrev_b32_e32 v46, 16, v81
	v_and_b32_e32 v47, 0xffff0000, v81
	v_cvt_pk_bf16_f32 v42, v42, v43
	v_cvt_pk_bf16_f32 v43, v48, v49
	v_lshlrev_b32_e32 v48, 16, v82
	v_and_b32_e32 v49, 0xffff0000, v82
	v_pk_add_f32 v[38:39], v[38:39], v[46:47]
	v_pk_add_f32 v[36:37], v[36:37], v[44:45]
	v_lshlrev_b32_e32 v50, 16, v83
	v_and_b32_e32 v51, 0xffff0000, v83
	v_pk_add_f32 v[46:47], v[32:33], v[48:49]
	v_mul_f32_e32 v32, v37, v37
	v_mul_f32_e32 v33, v39, v39
	v_pk_add_f32 v[44:45], v[34:35], v[50:51]
	v_fmac_f32_e32 v32, v36, v36
	v_fmac_f32_e32 v33, v38, v38
	v_add_f32_e32 v32, v32, v33
	v_mul_f32_e32 v33, v47, v47
	v_mul_f32_e32 v34, v45, v45
	v_fmac_f32_e32 v33, v46, v46
	v_fmac_f32_e32 v34, v44, v44
	v_add_f32_e32 v33, v33, v34
	v_add_f32_e32 v32, v32, v33
	v_add_f32_e32 v35, v52, v32
	ds_bpermute_b32 v50, v112, v35
	v_lshl_add_u64 v[32:33], s[64:65], 0, v[98:99]
	v_lshl_add_u64 v[48:49], v[168:169], 1, v[32:33]
	global_store_dwordx4 v[48:49], v[40:43], off nt
	v_cvt_pk_bf16_f32 v34, v36, v37
	s_waitcnt lgkmcnt(0)
	v_add_f32_e32 v32, v35, v50
	ds_bpermute_b32 v33, v113, v32
	v_cvt_pk_bf16_f32 v35, v38, v39
	v_cvt_pk_bf16_f32 v36, v46, v47
	v_cvt_pk_bf16_f32 v37, v44, v45
	global_store_dwordx4 v[48:49], v[34:37], off offset:256 nt
	s_and_saveexec_b64 s[18:19], s[2:3]
	s_cbranch_execz .LBB0_567
	s_waitcnt lgkmcnt(0)
	v_add_f32_e32 v34, v32, v33
	v_lshlrev_b64 v[32:33], 6, v[96:97]
	v_lshl_add_u64 v[32:33], s[74:75], 0, v[32:33]
	v_lshl_add_u64 v[32:33], s[14:15], 2, v[32:33]
	s_lshl_b32 s10, s38, 2
	v_lshl_add_u64 v[32:33], v[32:33], 0, s[10:11]
	global_store_dword v[32:33], v34, off
.LBB0_567:
	s_or_b64 exec, exec, s[18:19]
	s_waitcnt vmcnt(7)
	v_lshlrev_b32_e32 v32, 16, v76
	s_waitcnt lgkmcnt(0)
	v_and_b32_e32 v33, 0xffff0000, v76
	v_lshlrev_b32_e32 v34, 16, v77
	v_and_b32_e32 v35, 0xffff0000, v77
	v_lshlrev_b32_e32 v36, 16, v78
	v_and_b32_e32 v37, 0xffff0000, v78
	v_lshlrev_b32_e32 v38, 16, v79
	v_and_b32_e32 v39, 0xffff0000, v79
	v_pk_add_f32 v[30:31], v[30:31], v[34:35]
	v_pk_add_f32 v[28:29], v[28:29], v[32:33]
	v_pk_add_f32 v[32:33], v[26:27], v[38:39]
	v_pk_add_f32 v[26:27], v[24:25], v[36:37]
	v_mul_f32_e32 v24, v29, v29
	v_mul_f32_e32 v25, v31, v31
	v_fmac_f32_e32 v24, v28, v28
	v_fmac_f32_e32 v25, v30, v30
	v_add_f32_e32 v24, v24, v25
	v_mul_f32_e32 v25, v27, v27
	v_mul_f32_e32 v34, v33, v33
	v_fmac_f32_e32 v25, v26, v26
	v_fmac_f32_e32 v34, v32, v32
	v_add_f32_e32 v25, v25, v34
	v_add_f32_e32 v36, v24, v25
	v_cvt_pk_bf16_f32 v24, v28, v29
	v_cvt_pk_bf16_f32 v25, v30, v31
	s_waitcnt vmcnt(6)
	v_lshlrev_b32_e32 v28, 16, v72
	v_and_b32_e32 v29, 0xffff0000, v72
	v_lshlrev_b32_e32 v30, 16, v73
	v_and_b32_e32 v31, 0xffff0000, v73
	v_cvt_pk_bf16_f32 v26, v26, v27
	v_cvt_pk_bf16_f32 v27, v32, v33
	v_lshlrev_b32_e32 v32, 16, v74
	v_and_b32_e32 v33, 0xffff0000, v74
	v_pk_add_f32 v[22:23], v[22:23], v[30:31]
	v_pk_add_f32 v[20:21], v[20:21], v[28:29]
	v_lshlrev_b32_e32 v34, 16, v75
	v_and_b32_e32 v35, 0xffff0000, v75
	v_pk_add_f32 v[30:31], v[16:17], v[32:33]
	v_mul_f32_e32 v16, v21, v21
	v_mul_f32_e32 v17, v23, v23
	v_pk_add_f32 v[28:29], v[18:19], v[34:35]
	v_fmac_f32_e32 v16, v20, v20
	v_fmac_f32_e32 v17, v22, v22
	v_add_f32_e32 v16, v16, v17
	v_mul_f32_e32 v17, v31, v31
	v_mul_f32_e32 v18, v29, v29
	v_fmac_f32_e32 v17, v30, v30
	v_fmac_f32_e32 v18, v28, v28
	v_add_f32_e32 v17, v17, v18
	v_add_f32_e32 v16, v16, v17
	v_add_f32_e32 v19, v36, v16
	ds_bpermute_b32 v34, v112, v19
	v_lshl_add_u64 v[16:17], s[64:65], 0, v[94:95]
	v_lshl_add_u64 v[32:33], v[168:169], 1, v[16:17]
	global_store_dwordx4 v[32:33], v[24:27], off nt
	v_cvt_pk_bf16_f32 v18, v20, v21
	s_waitcnt lgkmcnt(0)
	v_add_f32_e32 v16, v19, v34
	ds_bpermute_b32 v17, v113, v16
	v_cvt_pk_bf16_f32 v19, v22, v23
	v_cvt_pk_bf16_f32 v20, v30, v31
	v_cvt_pk_bf16_f32 v21, v28, v29
	global_store_dwordx4 v[32:33], v[18:21], off offset:256 nt
	s_and_saveexec_b64 s[18:19], s[2:3]
	s_cbranch_execz .LBB0_569
	s_waitcnt lgkmcnt(0)
	v_add_f32_e32 v18, v16, v17
	v_lshlrev_b64 v[16:17], 6, v[92:93]
	v_lshl_add_u64 v[16:17], s[74:75], 0, v[16:17]
	v_lshl_add_u64 v[16:17], s[14:15], 2, v[16:17]
	s_lshl_b32 s10, s38, 2
	v_lshl_add_u64 v[16:17], v[16:17], 0, s[10:11]
	global_store_dword v[16:17], v18, off
.LBB0_569:
	s_or_b64 exec, exec, s[18:19]
	s_waitcnt vmcnt(7)
	v_lshlrev_b32_e32 v16, 16, v68
	s_waitcnt lgkmcnt(0)
	v_and_b32_e32 v17, 0xffff0000, v68
	v_lshlrev_b32_e32 v18, 16, v69
	v_and_b32_e32 v19, 0xffff0000, v69
	v_lshlrev_b32_e32 v20, 16, v70
	v_and_b32_e32 v21, 0xffff0000, v70
	v_lshlrev_b32_e32 v22, 16, v71
	v_and_b32_e32 v23, 0xffff0000, v71
	v_pk_add_f32 v[14:15], v[14:15], v[18:19]
	v_pk_add_f32 v[12:13], v[12:13], v[16:17]
	v_pk_add_f32 v[16:17], v[10:11], v[22:23]
	v_pk_add_f32 v[10:11], v[8:9], v[20:21]
	v_mul_f32_e32 v8, v13, v13
	v_mul_f32_e32 v9, v15, v15
	v_fmac_f32_e32 v8, v12, v12
	v_fmac_f32_e32 v9, v14, v14
	v_add_f32_e32 v8, v8, v9
	v_mul_f32_e32 v9, v11, v11
	v_mul_f32_e32 v18, v17, v17
	v_fmac_f32_e32 v9, v10, v10
	v_fmac_f32_e32 v18, v16, v16
	v_add_f32_e32 v9, v9, v18
	v_add_f32_e32 v20, v8, v9
	v_cvt_pk_bf16_f32 v8, v12, v13
	v_cvt_pk_bf16_f32 v9, v14, v15
	s_waitcnt vmcnt(6)
	v_lshlrev_b32_e32 v12, 16, v64
	v_and_b32_e32 v13, 0xffff0000, v64
	v_lshlrev_b32_e32 v14, 16, v65
	v_and_b32_e32 v15, 0xffff0000, v65
	v_cvt_pk_bf16_f32 v10, v10, v11
	v_cvt_pk_bf16_f32 v11, v16, v17
	v_lshlrev_b32_e32 v16, 16, v66
	v_and_b32_e32 v17, 0xffff0000, v66
	v_pk_add_f32 v[6:7], v[6:7], v[14:15]
	v_pk_add_f32 v[4:5], v[4:5], v[12:13]
	v_lshlrev_b32_e32 v18, 16, v67
	v_and_b32_e32 v19, 0xffff0000, v67
	v_pk_add_f32 v[14:15], v[0:1], v[16:17]
	v_mul_f32_e32 v0, v5, v5
	v_mul_f32_e32 v1, v7, v7
	v_pk_add_f32 v[12:13], v[2:3], v[18:19]
	v_fmac_f32_e32 v0, v4, v4
	v_fmac_f32_e32 v1, v6, v6
	v_add_f32_e32 v0, v0, v1
	v_mul_f32_e32 v1, v15, v15
	v_mul_f32_e32 v2, v13, v13
	v_fmac_f32_e32 v1, v14, v14
	v_fmac_f32_e32 v2, v12, v12
	v_add_f32_e32 v1, v1, v2
	v_add_f32_e32 v0, v0, v1
	v_add_f32_e32 v3, v20, v0
	ds_bpermute_b32 v18, v112, v3
	v_lshl_add_u64 v[0:1], s[64:65], 0, v[90:91]
	v_lshl_add_u64 v[16:17], v[168:169], 1, v[0:1]
	global_store_dwordx4 v[16:17], v[8:11], off nt
	v_cvt_pk_bf16_f32 v2, v4, v5
	s_waitcnt lgkmcnt(0)
	v_add_f32_e32 v0, v3, v18
	ds_bpermute_b32 v1, v113, v0
	v_cvt_pk_bf16_f32 v3, v6, v7
	v_cvt_pk_bf16_f32 v4, v14, v15
	v_cvt_pk_bf16_f32 v5, v12, v13
	global_store_dwordx4 v[16:17], v[2:5], off offset:256 nt
	s_and_saveexec_b64 s[18:19], s[2:3]
	s_cbranch_execz .LBB0_542
	s_waitcnt lgkmcnt(0)
	v_add_f32_e32 v2, v0, v1
	v_lshlrev_b64 v[0:1], 6, v[88:89]
	v_lshl_add_u64 v[0:1], s[74:75], 0, v[0:1]
	v_lshl_add_u64 v[0:1], s[14:15], 2, v[0:1]
	s_lshl_b32 s10, s38, 2
	v_lshl_add_u64 v[0:1], v[0:1], 0, s[10:11]
	global_store_dword v[0:1], v2, off
	s_branch .LBB0_542

.LBB0_860:
	s_or_b64 exec, exec, s[30:31]
	v_bfi_b32 v11, s68, v11, v10
	v_bfi_b32 v10, s68, v9, v8
	v_bfi_b32 v15, s68, v15, v14
	v_bfi_b32 v14, s68, v13, v12
	v_pk_mul_f32 v[0:1], v[0:1], 0.5 op_sel_hi:[1,0]
	v_pk_add_f32 v[8:9], v[10:11], 1.0 op_sel_hi:[1,0]
	v_pk_mul_f32 v[4:5], v[4:5], 0.5 op_sel_hi:[1,0]
	v_pk_add_f32 v[12:13], v[14:15], 1.0 op_sel_hi:[1,0]
	v_pk_mul_f32 v[0:1], v[0:1], v[8:9]
	v_lshlrev_b64 v[8:9], 9, v[64:65]
	v_pk_mul_f32 v[4:5], v[4:5], v[12:13]
	v_bfi_b32 v13, s68, v23, v22
	v_bfi_b32 v12, s68, v19, v18
	v_lshl_add_u64 v[8:9], s[0:1], 0, v[8:9]
	v_pk_mul_f32 v[2:3], v[2:3], 0.5 op_sel_hi:[1,0]
	v_pk_add_f32 v[10:11], v[12:13], 1.0 op_sel_hi:[1,0]
	v_lshl_add_u64 v[8:9], v[8:9], 0, v[80:81]
	v_bfi_b32 v21, s68, v21, v20
	v_bfi_b32 v20, s68, v17, v16
	v_pk_mul_f32 v[2:3], v[2:3], v[10:11]
	v_lshl_add_u64 v[10:11], v[8:9], 0, s[18:19]
	v_add_co_u32_e32 v8, vcc, 0x16000, v8
	v_pk_mul_f32 v[6:7], v[6:7], 0.5 op_sel_hi:[1,0]
	v_pk_add_f32 v[14:15], v[20:21], 1.0 op_sel_hi:[1,0]
	v_addc_co_u32_e32 v9, vcc, 0, v9, vcc
	v_pk_mul_f32 v[6:7], v[6:7], v[14:15]
	s_and_b64 vcc, exec, s[2:3]
	s_mov_b32 s30, s20
	s_mov_b32 s70, s69
	s_mov_b64 s[36:37], s[28:29]
	s_mov_b64 s[34:35], s[22:23]
	global_store_dwordx4 v[8:9], v[4:7], off nt
	global_store_dwordx4 v[10:11], v[0:3], off offset:16 nt
	s_cbranch_vccnz .LBB0_1131

.LBB0_905:
	s_andn2_saveexec_b64 s[0:1], s[0:1]
	v_mul_f32_e32 v112, v111, v111
	v_fmamk_f32 v113, v112, 0xbbbac73d, v96
	v_fmaak_f32 v113, v112, v113, 0xbd5c1c4e
	v_fmaak_f32 v113, v112, v113, 0x3e088382
	v_fmaak_f32 v113, v112, v113, 0xbeaaaa99
	v_mul_f32_e64 v113, |v111|, v113
	v_fma_f32 v112, v112, v113, |v111|
	s_or_b64 exec, exec, s[0:1]
	v_bfi_b32 v80, s68, v98, v80
	v_mul_f32_e32 v68, 0.5, v68
	v_add_f32_e32 v80, 1.0, v80
	v_mul_f32_e32 v68, v68, v80
	v_bfi_b32 v80, s68, v102, v101
	v_mul_f32_e32 v69, 0.5, v69
	v_add_f32_e32 v80, 1.0, v80
	v_mul_f32_e32 v69, v69, v80
	v_bfi_b32 v80, s68, v106, v105
	v_mul_f32_e32 v70, 0.5, v70
	v_add_f32_e32 v80, 1.0, v80
	v_mul_f32_e32 v70, v70, v80
	v_bfi_b32 v80, s68, v110, v109
	v_mul_f32_e32 v71, 0.5, v71
	v_add_f32_e32 v80, 1.0, v80
	v_mul_f32_e32 v71, v71, v80
	v_bfi_b32 v80, s68, v100, v99
	v_mul_f32_e32 v64, 0.5, v64
	v_add_f32_e32 v80, 1.0, v80
	v_mul_f32_e32 v98, v64, v80
	v_mul_f32_e32 v64, 0.5, v65
	v_bfi_b32 v65, s68, v104, v103
	v_add_f32_e32 v65, 1.0, v65
	v_mul_f32_e32 v99, v64, v65
	v_bfi_b32 v65, s68, v108, v107
	v_mul_f32_e32 v64, 0.5, v66
	v_add_f32_e32 v65, 1.0, v65
	s_ashr_i32 s31, s30, 31
	v_bfi_b32 v66, s68, v112, v111
	v_mul_f32_e32 v100, v64, v65
	v_lshl_add_u32 v64, s70, 8, v83
	s_lshl_b64 s[0:1], s[30:31], 23
	v_mul_f32_e32 v65, 0.5, v67
	v_add_f32_e32 v66, 1.0, v66
	v_mul_f32_e32 v101, v65, v66
	v_ashrrev_i32_e32 v65, 31, v64
	s_add_u32 s0, s52, s0
	s_addc_u32 s1, s53, s1
	v_lshlrev_b64 v[66:67], 9, v[64:65]
	v_lshl_add_u64 v[66:67], s[0:1], 0, v[66:67]
	v_lshlrev_b32_e32 v80, 2, v82
	v_lshl_add_u64 v[66:67], v[66:67], 0, v[80:81]
	v_pk_add_f32 v[60:61], v[60:61], v[16:17]
	global_store_dwordx4 v[66:67], v[68:71], off nt
	global_store_dwordx4 v[66:67], v[98:101], off offset:16 nt
	v_mul_f32_e32 v66, 0x3d372713, v60
	v_mul_f32_e32 v66, v60, v66
	v_fma_f32 v66, v60, v66, v60
	v_mul_f32_e32 v66, 0x3f4c422a, v66
	v_cmp_nlt_f32_e64 s[30:31], |v66|, s61
	s_and_saveexec_b64 s[34:35], s[30:31]
	s_xor_b64 s[30:31], exec, s[34:35]
	s_cbranch_execz .LBB0_909
	v_add_f32_e64 v67, |v66|, |v66|
	v_mul_f32_e32 v68, 0x3fb8aa3b, v67
	v_rndne_f32_e32 v69, v68
	v_sub_f32_e32 v70, v68, v69
	v_fma_f32 v68, v67, s62, -v68
	v_fmac_f32_e32 v68, 0x32a5705f, v67
	v_add_f32_e32 v68, v70, v68
	v_cvt_i32_f32_e32 v69, v69
	v_exp_f32_e32 v68, v68
	v_cmp_ngt_f32_e32 vcc, s63, v67
	v_ldexp_f32 v68, v68, v69
	s_nop 0
	v_cndmask_b32_e32 v68, 0, v68, vcc
	v_cmp_nlt_f32_e32 vcc, s67, v67
	s_nop 1
	v_cndmask_b32_e32 v67, v97, v68, vcc
	v_add_f32_e32 v67, 1.0, v67
	v_rcp_f32_e32 v67, v67
	s_nop 0
	v_fma_f32 v67, v67, -2.0, 1.0

.LBB0_937:
	s_andn2_saveexec_b64 s[30:31], s[30:31]
	v_mul_f32_e32 v107, v106, v106
	v_fmamk_f32 v108, v107, 0xbbbac73d, v96
	v_fmaak_f32 v108, v107, v108, 0xbd5c1c4e
	v_fmaak_f32 v108, v107, v108, 0x3e088382
	v_fmaak_f32 v108, v107, v108, 0xbeaaaa99
	v_mul_f32_e64 v108, |v106|, v108
	v_fma_f32 v107, v107, v108, |v106|
	s_or_b64 exec, exec, s[30:31]
	v_bfi_b32 v66, s68, v67, v66
	v_mul_f32_e32 v60, 0.5, v60
	v_add_f32_e32 v66, 1.0, v66
	v_mul_f32_e32 v60, v60, v66
	v_bfi_b32 v66, s68, v71, v70
	v_mul_f32_e32 v61, 0.5, v61
	v_add_f32_e32 v66, 1.0, v66
	v_mul_f32_e32 v61, v61, v66
	v_bfi_b32 v66, s68, v101, v100
	v_mul_f32_e32 v62, 0.5, v62
	v_add_f32_e32 v66, 1.0, v66
	v_mul_f32_e32 v62, v62, v66
	v_bfi_b32 v66, s68, v105, v104
	v_mul_f32_e32 v63, 0.5, v63
	v_add_f32_e32 v66, 1.0, v66
	v_mul_f32_e32 v63, v63, v66
	v_bfi_b32 v66, s68, v69, v68
	v_mul_f32_e32 v56, 0.5, v56
	v_add_f32_e32 v66, 1.0, v66
	v_mul_f32_e32 v56, v56, v66
	v_bfi_b32 v66, s68, v99, v98
	v_mul_f32_e32 v57, 0.5, v57
	v_add_f32_e32 v66, 1.0, v66
	v_mul_f32_e32 v57, v57, v66
	v_bfi_b32 v66, s68, v103, v102
	v_mul_f32_e32 v58, 0.5, v58
	v_add_f32_e32 v66, 1.0, v66
	v_mul_f32_e32 v58, v58, v66
	v_bfi_b32 v66, s68, v107, v106
	v_mul_f32_e32 v59, 0.5, v59
	v_add_f32_e32 v66, 1.0, v66
	v_mul_f32_e32 v59, v59, v66
	v_or_b32_e32 v66, 16, v64
	v_ashrrev_i32_e32 v67, 31, v66
	v_lshlrev_b64 v[66:67], 9, v[66:67]
	v_lshl_add_u64 v[66:67], s[0:1], 0, v[66:67]
	v_lshl_add_u64 v[66:67], v[66:67], 0, v[80:81]
	v_pk_add_f32 v[52:53], v[52:53], v[16:17]
	global_store_dwordx4 v[66:67], v[60:63], off nt
	global_store_dwordx4 v[66:67], v[56:59], off offset:16 nt
	s_nop 1
	v_mul_f32_e32 v56, 0x3d372713, v52
	v_mul_f32_e32 v56, v52, v56
	v_fma_f32 v56, v52, v56, v52
	v_mul_f32_e32 v56, 0x3f4c422a, v56
	v_cmp_nlt_f32_e64 s[30:31], |v56|, s61
	s_and_saveexec_b64 s[34:35], s[30:31]
	s_xor_b64 s[30:31], exec, s[34:35]
	s_cbranch_execz .LBB0_941
	v_add_f32_e64 v57, |v56|, |v56|
	v_mul_f32_e32 v58, 0x3fb8aa3b, v57
	v_rndne_f32_e32 v59, v58
	v_sub_f32_e32 v60, v58, v59
	v_fma_f32 v58, v57, s62, -v58
	v_fmac_f32_e32 v58, 0x32a5705f, v57
	v_add_f32_e32 v58, v60, v58
	v_cvt_i32_f32_e32 v59, v59
	v_exp_f32_e32 v58, v58
	v_cmp_ngt_f32_e32 vcc, s63, v57
	v_ldexp_f32 v58, v58, v59
	s_nop 0
	v_cndmask_b32_e32 v58, 0, v58, vcc
	v_cmp_nlt_f32_e32 vcc, s67, v57
	s_nop 1
	v_cndmask_b32_e32 v57, v97, v58, vcc
	v_add_f32_e32 v57, 1.0, v57
	v_rcp_f32_e32 v57, v57
	s_nop 0
	v_fma_f32 v57, v57, -2.0, 1.0

.LBB0_969:
	s_andn2_saveexec_b64 s[30:31], s[30:31]
	v_mul_f32_e32 v99, v98, v98
	v_fmamk_f32 v100, v99, 0xbbbac73d, v96
	v_fmaak_f32 v100, v99, v100, 0xbd5c1c4e
	v_fmaak_f32 v100, v99, v100, 0x3e088382
	v_fmaak_f32 v100, v99, v100, 0xbeaaaa99
	v_mul_f32_e64 v100, |v98|, v100
	v_fma_f32 v99, v99, v100, |v98|
	s_or_b64 exec, exec, s[30:31]
	v_bfi_b32 v56, s68, v57, v56
	v_mul_f32_e32 v52, 0.5, v52
	v_add_f32_e32 v56, 1.0, v56
	v_mul_f32_e32 v52, v52, v56
	v_bfi_b32 v56, s68, v61, v60
	v_mul_f32_e32 v53, 0.5, v53
	v_add_f32_e32 v56, 1.0, v56
	v_mul_f32_e32 v53, v53, v56
	v_bfi_b32 v56, s68, v67, v66
	v_mul_f32_e32 v54, 0.5, v54
	v_add_f32_e32 v56, 1.0, v56
	v_mul_f32_e32 v54, v54, v56
	v_bfi_b32 v56, s68, v71, v70
	v_mul_f32_e32 v55, 0.5, v55
	v_add_f32_e32 v56, 1.0, v56
	v_mul_f32_e32 v55, v55, v56
	v_bfi_b32 v56, s68, v59, v58
	v_mul_f32_e32 v48, 0.5, v48
	v_add_f32_e32 v56, 1.0, v56
	v_mul_f32_e32 v48, v48, v56
	v_bfi_b32 v56, s68, v63, v62
	v_mul_f32_e32 v49, 0.5, v49
	v_add_f32_e32 v56, 1.0, v56
	v_mul_f32_e32 v49, v49, v56
	v_bfi_b32 v56, s68, v69, v68
	v_mul_f32_e32 v50, 0.5, v50
	v_add_f32_e32 v56, 1.0, v56
	v_mul_f32_e32 v50, v50, v56
	v_bfi_b32 v56, s68, v99, v98
	v_mul_f32_e32 v51, 0.5, v51
	v_add_f32_e32 v56, 1.0, v56
	v_mul_f32_e32 v51, v51, v56
	v_or_b32_e32 v56, 32, v64
	v_ashrrev_i32_e32 v57, 31, v56
	v_lshlrev_b64 v[56:57], 9, v[56:57]
	v_lshl_add_u64 v[56:57], s[0:1], 0, v[56:57]
	v_lshl_add_u64 v[56:57], v[56:57], 0, v[80:81]
	v_pk_add_f32 v[44:45], v[44:45], v[16:17]
	global_store_dwordx4 v[56:57], v[52:55], off nt
	global_store_dwordx4 v[56:57], v[48:51], off offset:16 nt
	s_nop 1
	v_mul_f32_e32 v48, 0x3d372713, v44
	v_mul_f32_e32 v48, v44, v48
	v_fma_f32 v48, v44, v48, v44
	v_mul_f32_e32 v48, 0x3f4c422a, v48
	v_cmp_nlt_f32_e64 s[30:31], |v48|, s61
	s_and_saveexec_b64 s[34:35], s[30:31]
	s_xor_b64 s[30:31], exec, s[34:35]
	s_cbranch_execz .LBB0_973
	v_add_f32_e64 v49, |v48|, |v48|
	v_mul_f32_e32 v50, 0x3fb8aa3b, v49
	v_rndne_f32_e32 v51, v50
	v_sub_f32_e32 v52, v50, v51
	v_fma_f32 v50, v49, s62, -v50
	v_fmac_f32_e32 v50, 0x32a5705f, v49
	v_add_f32_e32 v50, v52, v50
	v_cvt_i32_f32_e32 v51, v51
	v_exp_f32_e32 v50, v50
	v_cmp_ngt_f32_e32 vcc, s63, v49
	v_ldexp_f32 v50, v50, v51
	s_nop 0
	v_cndmask_b32_e32 v50, 0, v50, vcc
	v_cmp_nlt_f32_e32 vcc, s67, v49
	s_nop 1
	v_cndmask_b32_e32 v49, v97, v50, vcc
	v_add_f32_e32 v49, 1.0, v49
	v_rcp_f32_e32 v49, v49
	s_nop 0
	v_fma_f32 v49, v49, -2.0, 1.0

.LBB0_1001:
	s_andn2_saveexec_b64 s[30:31], s[30:31]
	v_mul_f32_e32 v63, v62, v62
	v_fmamk_f32 v66, v63, 0xbbbac73d, v96
	v_fmaak_f32 v66, v63, v66, 0xbd5c1c4e
	v_fmaak_f32 v66, v63, v66, 0x3e088382
	v_fmaak_f32 v66, v63, v66, 0xbeaaaa99
	v_mul_f32_e64 v66, |v62|, v66
	v_fma_f32 v63, v63, v66, |v62|
	s_or_b64 exec, exec, s[30:31]
	v_bfi_b32 v48, s68, v49, v48
	v_mul_f32_e32 v44, 0.5, v44
	v_add_f32_e32 v48, 1.0, v48
	v_mul_f32_e32 v44, v44, v48
	v_bfi_b32 v48, s68, v53, v52
	v_mul_f32_e32 v45, 0.5, v45
	v_add_f32_e32 v48, 1.0, v48
	v_mul_f32_e32 v45, v45, v48
	v_bfi_b32 v48, s68, v57, v56
	v_mul_f32_e32 v46, 0.5, v46
	v_add_f32_e32 v48, 1.0, v48
	v_mul_f32_e32 v46, v46, v48
	v_bfi_b32 v48, s68, v61, v60
	v_mul_f32_e32 v47, 0.5, v47
	v_add_f32_e32 v48, 1.0, v48
	v_mul_f32_e32 v47, v47, v48
	v_bfi_b32 v48, s68, v51, v50
	v_mul_f32_e32 v40, 0.5, v40
	v_add_f32_e32 v48, 1.0, v48
	v_mul_f32_e32 v40, v40, v48
	v_bfi_b32 v48, s68, v55, v54
	v_mul_f32_e32 v41, 0.5, v41
	v_add_f32_e32 v48, 1.0, v48
	v_mul_f32_e32 v41, v41, v48
	v_bfi_b32 v48, s68, v59, v58
	v_mul_f32_e32 v42, 0.5, v42
	v_add_f32_e32 v48, 1.0, v48
	v_mul_f32_e32 v42, v42, v48
	v_bfi_b32 v48, s68, v63, v62
	v_mul_f32_e32 v43, 0.5, v43
	v_add_f32_e32 v48, 1.0, v48
	v_mul_f32_e32 v43, v43, v48
	v_or_b32_e32 v48, 48, v64
	v_ashrrev_i32_e32 v49, 31, v48
	v_lshlrev_b64 v[48:49], 9, v[48:49]
	v_lshl_add_u64 v[48:49], s[0:1], 0, v[48:49]
	v_lshl_add_u64 v[48:49], v[48:49], 0, v[80:81]
	v_pk_add_f32 v[36:37], v[36:37], v[16:17]
	global_store_dwordx4 v[48:49], v[44:47], off nt
	global_store_dwordx4 v[48:49], v[40:43], off offset:16 nt
	s_nop 1
	v_mul_f32_e32 v40, 0x3d372713, v36
	v_mul_f32_e32 v40, v36, v40
	v_fma_f32 v40, v36, v40, v36
	v_mul_f32_e32 v40, 0x3f4c422a, v40
	v_cmp_nlt_f32_e64 s[30:31], |v40|, s61
	s_and_saveexec_b64 s[34:35], s[30:31]
	s_xor_b64 s[30:31], exec, s[34:35]
	s_cbranch_execz .LBB0_1005
	v_add_f32_e64 v41, |v40|, |v40|
	v_mul_f32_e32 v42, 0x3fb8aa3b, v41
	v_rndne_f32_e32 v43, v42
	v_sub_f32_e32 v44, v42, v43
	v_fma_f32 v42, v41, s62, -v42
	v_fmac_f32_e32 v42, 0x32a5705f, v41
	v_add_f32_e32 v42, v44, v42
	v_cvt_i32_f32_e32 v43, v43
	v_exp_f32_e32 v42, v42
	v_cmp_ngt_f32_e32 vcc, s63, v41
	v_ldexp_f32 v42, v42, v43
	s_nop 0
	v_cndmask_b32_e32 v42, 0, v42, vcc
	v_cmp_nlt_f32_e32 vcc, s67, v41
	s_nop 1
	v_cndmask_b32_e32 v41, v97, v42, vcc
	v_add_f32_e32 v41, 1.0, v41
	v_rcp_f32_e32 v41, v41
	s_nop 0
	v_fma_f32 v41, v41, -2.0, 1.0

.LBB0_1033:
	s_andn2_saveexec_b64 s[30:31], s[30:31]
	v_mul_f32_e32 v55, v54, v54
	v_fmamk_f32 v56, v55, 0xbbbac73d, v96
	v_fmaak_f32 v56, v55, v56, 0xbd5c1c4e
	v_fmaak_f32 v56, v55, v56, 0x3e088382
	v_fmaak_f32 v56, v55, v56, 0xbeaaaa99
	v_mul_f32_e64 v56, |v54|, v56
	v_fma_f32 v55, v55, v56, |v54|
	s_or_b64 exec, exec, s[30:31]
	v_bfi_b32 v40, s68, v41, v40
	v_mul_f32_e32 v36, 0.5, v36
	v_add_f32_e32 v40, 1.0, v40
	v_mul_f32_e32 v36, v36, v40
	v_bfi_b32 v40, s68, v45, v44
	v_mul_f32_e32 v37, 0.5, v37
	v_add_f32_e32 v40, 1.0, v40
	v_mul_f32_e32 v37, v37, v40
	v_bfi_b32 v40, s68, v49, v48
	v_mul_f32_e32 v38, 0.5, v38
	v_add_f32_e32 v40, 1.0, v40
	v_mul_f32_e32 v38, v38, v40
	v_bfi_b32 v40, s68, v53, v52
	v_mul_f32_e32 v39, 0.5, v39
	v_add_f32_e32 v40, 1.0, v40
	v_mul_f32_e32 v39, v39, v40
	v_bfi_b32 v40, s68, v43, v42
	v_mul_f32_e32 v32, 0.5, v32
	v_add_f32_e32 v40, 1.0, v40
	v_mul_f32_e32 v32, v32, v40
	v_bfi_b32 v40, s68, v47, v46
	v_mul_f32_e32 v33, 0.5, v33
	v_add_f32_e32 v40, 1.0, v40
	v_mul_f32_e32 v33, v33, v40
	v_bfi_b32 v40, s68, v51, v50
	v_mul_f32_e32 v34, 0.5, v34
	v_add_f32_e32 v40, 1.0, v40
	v_mul_f32_e32 v34, v34, v40
	v_bfi_b32 v40, s68, v55, v54
	v_mul_f32_e32 v35, 0.5, v35
	v_add_f32_e32 v40, 1.0, v40
	v_mul_f32_e32 v35, v35, v40
	v_lshlrev_b64 v[40:41], 9, v[64:65]
	v_lshl_add_u64 v[40:41], s[0:1], 0, v[40:41]
	v_lshl_add_u64 v[40:41], v[40:41], 0, v[80:81]
	v_lshl_add_u64 v[42:43], v[40:41], 0, s[10:11]
	v_add_co_u32_e32 v40, vcc, s49, v40
	v_pk_add_f32 v[28:29], v[28:29], v[16:17]
	s_nop 0
	v_addc_co_u32_e32 v41, vcc, 0, v41, vcc
	global_store_dwordx4 v[40:41], v[36:39], off nt
	global_store_dwordx4 v[42:43], v[32:35], off offset:16 nt
	s_nop 1
	v_mul_f32_e32 v32, 0x3d372713, v28
	v_mul_f32_e32 v32, v28, v32
	v_fma_f32 v32, v28, v32, v28
	v_mul_f32_e32 v32, 0x3f4c422a, v32
	v_cmp_nlt_f32_e64 s[30:31], |v32|, s61
	s_and_saveexec_b64 s[34:35], s[30:31]
	s_xor_b64 s[30:31], exec, s[34:35]
	s_cbranch_execz .LBB0_1037
	v_add_f32_e64 v33, |v32|, |v32|
	v_mul_f32_e32 v34, 0x3fb8aa3b, v33
	v_rndne_f32_e32 v35, v34
	v_sub_f32_e32 v36, v34, v35
	v_fma_f32 v34, v33, s62, -v34
	v_fmac_f32_e32 v34, 0x32a5705f, v33
	v_add_f32_e32 v34, v36, v34
	v_cvt_i32_f32_e32 v35, v35
	v_exp_f32_e32 v34, v34
	v_cmp_ngt_f32_e32 vcc, s63, v33
	v_ldexp_f32 v34, v34, v35
	s_nop 0
	v_cndmask_b32_e32 v34, 0, v34, vcc
	v_cmp_nlt_f32_e32 vcc, s67, v33
	s_nop 1
	v_cndmask_b32_e32 v33, v97, v34, vcc
	v_add_f32_e32 v33, 1.0, v33
	v_rcp_f32_e32 v33, v33
	s_nop 0
	v_fma_f32 v33, v33, -2.0, 1.0

.LBB0_1065:
	s_andn2_saveexec_b64 s[30:31], s[30:31]
	v_mul_f32_e32 v47, v46, v46
	v_fmamk_f32 v48, v47, 0xbbbac73d, v96
	v_fmaak_f32 v48, v47, v48, 0xbd5c1c4e
	v_fmaak_f32 v48, v47, v48, 0x3e088382
	v_fmaak_f32 v48, v47, v48, 0xbeaaaa99
	v_mul_f32_e64 v48, |v46|, v48
	v_fma_f32 v47, v47, v48, |v46|
	s_or_b64 exec, exec, s[30:31]
	v_bfi_b32 v32, s68, v33, v32
	v_mul_f32_e32 v28, 0.5, v28
	v_add_f32_e32 v32, 1.0, v32
	v_mul_f32_e32 v28, v28, v32
	v_bfi_b32 v32, s68, v37, v36
	v_mul_f32_e32 v29, 0.5, v29
	v_add_f32_e32 v32, 1.0, v32
	v_mul_f32_e32 v29, v29, v32
	v_bfi_b32 v32, s68, v41, v40
	v_mul_f32_e32 v30, 0.5, v30
	v_add_f32_e32 v32, 1.0, v32
	v_mul_f32_e32 v30, v30, v32
	v_bfi_b32 v32, s68, v45, v44
	v_mul_f32_e32 v31, 0.5, v31
	v_add_f32_e32 v32, 1.0, v32
	v_mul_f32_e32 v31, v31, v32
	v_bfi_b32 v32, s68, v35, v34
	v_mul_f32_e32 v24, 0.5, v24
	v_add_f32_e32 v32, 1.0, v32
	v_mul_f32_e32 v24, v24, v32
	v_bfi_b32 v32, s68, v39, v38
	v_mul_f32_e32 v25, 0.5, v25
	v_add_f32_e32 v32, 1.0, v32
	v_mul_f32_e32 v25, v25, v32
	v_bfi_b32 v32, s68, v43, v42
	v_mul_f32_e32 v26, 0.5, v26
	v_add_f32_e32 v32, 1.0, v32
	v_mul_f32_e32 v26, v26, v32
	v_bfi_b32 v32, s68, v47, v46
	v_mul_f32_e32 v27, 0.5, v27
	v_add_f32_e32 v32, 1.0, v32
	v_mul_f32_e32 v27, v27, v32
	v_lshlrev_b64 v[32:33], 9, v[64:65]
	v_lshl_add_u64 v[32:33], s[0:1], 0, v[32:33]
	v_lshl_add_u64 v[32:33], v[32:33], 0, v[80:81]
	v_lshl_add_u64 v[34:35], v[32:33], 0, s[12:13]
	v_add_co_u32_e32 v32, vcc, s50, v32
	v_pk_add_f32 v[20:21], v[20:21], v[16:17]
	s_nop 0
	v_addc_co_u32_e32 v33, vcc, 0, v33, vcc
	global_store_dwordx4 v[32:33], v[28:31], off nt
	global_store_dwordx4 v[34:35], v[24:27], off offset:16 nt
	s_nop 1
	v_mul_f32_e32 v24, 0x3d372713, v20
	v_mul_f32_e32 v24, v20, v24
	v_fma_f32 v24, v20, v24, v20
	v_mul_f32_e32 v24, 0x3f4c422a, v24
	v_cmp_nlt_f32_e64 s[30:31], |v24|, s61
	s_and_saveexec_b64 s[34:35], s[30:31]
	s_xor_b64 s[30:31], exec, s[34:35]
	s_cbranch_execz .LBB0_1069
	v_add_f32_e64 v25, |v24|, |v24|
	v_mul_f32_e32 v26, 0x3fb8aa3b, v25
	v_rndne_f32_e32 v27, v26
	v_sub_f32_e32 v28, v26, v27
	v_fma_f32 v26, v25, s62, -v26
	v_fmac_f32_e32 v26, 0x32a5705f, v25
	v_add_f32_e32 v26, v28, v26
	v_cvt_i32_f32_e32 v27, v27
	v_exp_f32_e32 v26, v26
	v_cmp_ngt_f32_e32 vcc, s63, v25
	v_ldexp_f32 v26, v26, v27
	s_nop 0
	v_cndmask_b32_e32 v26, 0, v26, vcc
	v_cmp_nlt_f32_e32 vcc, s67, v25
	s_nop 1
	v_cndmask_b32_e32 v25, v97, v26, vcc
	v_add_f32_e32 v25, 1.0, v25
	v_rcp_f32_e32 v25, v25
	s_nop 0
	v_fma_f32 v25, v25, -2.0, 1.0

.LBB0_1097:
	s_andn2_saveexec_b64 s[30:31], s[30:31]
	v_mul_f32_e32 v39, v38, v38
	v_fmamk_f32 v40, v39, 0xbbbac73d, v96
	v_fmaak_f32 v40, v39, v40, 0xbd5c1c4e
	v_fmaak_f32 v40, v39, v40, 0x3e088382
	v_fmaak_f32 v40, v39, v40, 0xbeaaaa99
	v_mul_f32_e64 v40, |v38|, v40
	v_fma_f32 v39, v39, v40, |v38|
	s_or_b64 exec, exec, s[30:31]
	v_bfi_b32 v24, s68, v25, v24
	v_mul_f32_e32 v20, 0.5, v20
	v_add_f32_e32 v24, 1.0, v24
	v_mul_f32_e32 v20, v20, v24
	v_bfi_b32 v24, s68, v29, v28
	v_mul_f32_e32 v21, 0.5, v21
	v_add_f32_e32 v24, 1.0, v24
	v_mul_f32_e32 v21, v21, v24
	v_bfi_b32 v24, s68, v33, v32
	v_mul_f32_e32 v22, 0.5, v22
	v_add_f32_e32 v24, 1.0, v24
	v_mul_f32_e32 v22, v22, v24
	v_bfi_b32 v24, s68, v37, v36
	v_mul_f32_e32 v23, 0.5, v23
	v_add_f32_e32 v24, 1.0, v24
	v_mul_f32_e32 v23, v23, v24
	v_bfi_b32 v24, s68, v27, v26
	v_mul_f32_e32 v12, 0.5, v12
	v_add_f32_e32 v24, 1.0, v24
	v_mul_f32_e32 v12, v12, v24
	v_bfi_b32 v24, s68, v31, v30
	v_mul_f32_e32 v13, 0.5, v13
	v_add_f32_e32 v24, 1.0, v24
	v_mul_f32_e32 v13, v13, v24
	v_bfi_b32 v24, s68, v35, v34
	v_mul_f32_e32 v14, 0.5, v14
	v_add_f32_e32 v24, 1.0, v24
	v_mul_f32_e32 v14, v14, v24
	v_bfi_b32 v24, s68, v39, v38
	v_mul_f32_e32 v15, 0.5, v15
	v_add_f32_e32 v24, 1.0, v24
	v_mul_f32_e32 v15, v15, v24
	v_lshlrev_b64 v[24:25], 9, v[64:65]
	v_lshl_add_u64 v[24:25], s[0:1], 0, v[24:25]
	v_lshl_add_u64 v[24:25], v[24:25], 0, v[80:81]
	v_lshl_add_u64 v[26:27], v[24:25], 0, s[14:15]
	v_add_co_u32_e32 v24, vcc, s51, v24
	v_pk_add_f32 v[4:5], v[4:5], v[16:17]
	s_nop 0
	v_addc_co_u32_e32 v25, vcc, 0, v25, vcc
	global_store_dwordx4 v[24:25], v[20:23], off nt
	global_store_dwordx4 v[26:27], v[12:15], off offset:16 nt
	s_nop 1
	v_mul_f32_e32 v12, 0x3d372713, v4
	v_mul_f32_e32 v12, v4, v12
	v_fma_f32 v12, v4, v12, v4
	v_mul_f32_e32 v12, 0x3f4c422a, v12
	v_cmp_nlt_f32_e64 s[30:31], |v12|, s61
	s_and_saveexec_b64 s[34:35], s[30:31]
	s_xor_b64 s[30:31], exec, s[34:35]
	s_cbranch_execz .LBB0_1101
	v_add_f32_e64 v13, |v12|, |v12|
	v_mul_f32_e32 v14, 0x3fb8aa3b, v13
	v_rndne_f32_e32 v15, v14
	v_sub_f32_e32 v16, v14, v15
	v_fma_f32 v14, v13, s62, -v14
	v_fmac_f32_e32 v14, 0x32a5705f, v13
	v_add_f32_e32 v14, v16, v14
	v_cvt_i32_f32_e32 v15, v15
	v_exp_f32_e32 v14, v14
	v_cmp_ngt_f32_e32 vcc, s63, v13
	v_ldexp_f32 v14, v14, v15
	s_nop 0
	v_cndmask_b32_e32 v14, 0, v14, vcc
	v_cmp_nlt_f32_e32 vcc, s67, v13
	s_nop 1
	v_cndmask_b32_e32 v13, v97, v14, vcc
	v_add_f32_e32 v13, 1.0, v13
	v_rcp_f32_e32 v13, v13
	s_nop 0
	v_fma_f32 v13, v13, -2.0, 1.0

.LBB0_1551:
	ds_read_b128 v[128:131], v190
	ds_read_b128 v[132:135], v190 offset:1024
	ds_read_b128 v[136:139], v190 offset:2048
	ds_read_b128 v[140:143], v190 offset:3072
	s_add_u32 s22, s20, 0xfffc0080
	s_addc_u32 s23, s21, -1
	s_cmp_eq_u32 s51, 12
	s_cselect_b32 s29, s13, s23
	s_cselect_b32 s28, s19, s22
	s_cselect_b32 s23, s11, s50
	s_cselect_b32 s22, s48, s49
	v_lshl_add_u64 v[184:185], s[20:21], 0, v[160:161]
	s_add_i32 m0, s36, 0xc000
	ds_read_b128 v[144:147], v191
	ds_read_b128 v[148:151], v191 offset:1024
	ds_read_b128 v[168:171], v191 offset:2048
	ds_read_b128 v[172:175], v191 offset:3072
	ds_read_b128 v[176:179], v191 offset:4096
	ds_read_b128 v[180:183], v191 offset:5120
	ds_read_b128 v[194:197], v191 offset:6144
	ds_read_b128 v[198:201], v191 offset:7168
	global_load_lds_dwordx4 v[184:185], off
	v_lshl_add_u64 v[184:185], s[20:21], 0, v[162:163]
	s_add_i32 m0, s36, 0xe000
	s_nop 0
	global_load_lds_dwordx4 v[184:185], off
	s_waitcnt lgkmcnt(8)
	s_barrier
	s_waitcnt lgkmcnt(0)
	s_setprio 1
	s_waitcnt lgkmcnt(0)
	v_mfma_f32_16x16x32_bf16 v[124:127], v[128:131], v[144:147], v[124:127]
	v_mfma_f32_16x16x32_bf16 v[120:123], v[136:139], v[144:147], v[120:123]
	v_mfma_f32_16x16x32_bf16 v[108:111], v[128:131], v[168:171], v[108:111]
	v_mfma_f32_16x16x32_bf16 v[104:107], v[136:139], v[168:171], v[104:107]
	v_mfma_f32_16x16x32_bf16 v[92:95], v[128:131], v[176:179], v[92:95]
	v_mfma_f32_16x16x32_bf16 v[88:91], v[136:139], v[176:179], v[88:91]
	v_mfma_f32_16x16x32_bf16 v[76:79], v[128:131], v[194:197], v[76:79]
	v_mfma_f32_16x16x32_bf16 v[72:75], v[136:139], v[194:197], v[72:75]
	v_mfma_f32_16x16x32_bf16 v[124:127], v[132:135], v[148:151], v[124:127]
	v_mfma_f32_16x16x32_bf16 v[120:123], v[140:143], v[148:151], v[120:123]
	v_mfma_f32_16x16x32_bf16 v[108:111], v[132:135], v[172:175], v[108:111]
	v_mfma_f32_16x16x32_bf16 v[104:107], v[140:143], v[172:175], v[104:107]
	v_mfma_f32_16x16x32_bf16 v[92:95], v[132:135], v[180:183], v[92:95]
	v_mfma_f32_16x16x32_bf16 v[88:91], v[140:143], v[180:183], v[88:91]
	v_mfma_f32_16x16x32_bf16 v[76:79], v[132:135], v[198:201], v[76:79]
	v_mfma_f32_16x16x32_bf16 v[72:75], v[140:143], v[198:201], v[72:75]
	s_setprio 0
	s_barrier
	s_add_i32 s52, s45, s35
	v_lshl_add_u64 v[184:185], s[22:23], 0, v[154:155]
	s_mov_b32 m0, s52
	ds_read_b128 v[202:205], v192
	ds_read_b128 v[206:209], v192 offset:1024
	ds_read_b128 v[210:213], v192 offset:2048
	ds_read_b128 v[214:217], v192 offset:3072
	global_load_lds_dwordx4 v[184:185], off
	v_lshl_add_u64 v[218:219], s[22:23], 0, v[158:159]
	s_add_i32 m0, s52, 0x2000
	s_nop 0
	global_load_lds_dwordx4 v[218:219], off
	s_barrier
	s_waitcnt lgkmcnt(0)
	s_setprio 1
	s_waitcnt lgkmcnt(0)
	v_mfma_f32_16x16x32_bf16 v[116:119], v[202:205], v[144:147], v[116:119]
	v_mfma_f32_16x16x32_bf16 v[112:115], v[210:213], v[144:147], v[112:115]
	v_mfma_f32_16x16x32_bf16 v[100:103], v[202:205], v[168:171], v[100:103]
	v_mfma_f32_16x16x32_bf16 v[96:99], v[210:213], v[168:171], v[96:99]
	v_mfma_f32_16x16x32_bf16 v[84:87], v[202:205], v[176:179], v[84:87]
	v_mfma_f32_16x16x32_bf16 v[80:83], v[210:213], v[176:179], v[80:83]
	v_mfma_f32_16x16x32_bf16 v[68:71], v[202:205], v[194:197], v[68:71]
	v_mfma_f32_16x16x32_bf16 v[64:67], v[210:213], v[194:197], v[64:67]
	v_mfma_f32_16x16x32_bf16 v[116:119], v[206:209], v[148:151], v[116:119]
	v_mfma_f32_16x16x32_bf16 v[112:115], v[214:217], v[148:151], v[112:115]
	v_mfma_f32_16x16x32_bf16 v[100:103], v[206:209], v[172:175], v[100:103]
	v_mfma_f32_16x16x32_bf16 v[96:99], v[214:217], v[172:175], v[96:99]
	v_mfma_f32_16x16x32_bf16 v[84:87], v[206:209], v[180:183], v[84:87]
	v_mfma_f32_16x16x32_bf16 v[80:83], v[214:217], v[180:183], v[80:83]
	v_mfma_f32_16x16x32_bf16 v[68:71], v[206:209], v[198:201], v[68:71]
	v_mfma_f32_16x16x32_bf16 v[64:67], v[214:217], v[198:201], v[64:67]
	s_setprio 0
	s_mov_b32 m0, s36
	v_lshl_add_u64 v[220:221], s[28:29], 0, v[152:153]
	s_barrier
	ds_read_b128 v[144:147], v191 offset:16384
	ds_read_b128 v[148:151], v191 offset:17408
	ds_read_b128 v[168:171], v191 offset:18432
	ds_read_b128 v[172:175], v191 offset:19456
	ds_read_b128 v[176:179], v191 offset:20480
	ds_read_b128 v[180:183], v191 offset:21504
	ds_read_b128 v[194:197], v191 offset:22528
	ds_read_b128 v[198:201], v191 offset:23552
	global_load_lds_dwordx4 v[220:221], off
	v_lshl_add_u64 v[222:223], s[28:29], 0, v[156:157]
	s_mov_b32 m0, s37
	s_nop 0
	global_load_lds_dwordx4 v[222:223], off
	s_barrier
	s_waitcnt lgkmcnt(0)
	s_setprio 1
	s_waitcnt lgkmcnt(0)
	v_mfma_f32_16x16x32_bf16 v[60:63], v[128:131], v[144:147], v[60:63]
	v_mfma_f32_16x16x32_bf16 v[56:59], v[136:139], v[144:147], v[56:59]
	v_mfma_f32_16x16x32_bf16 v[44:47], v[128:131], v[168:171], v[44:47]
	v_mfma_f32_16x16x32_bf16 v[40:43], v[136:139], v[168:171], v[40:43]
	v_mfma_f32_16x16x32_bf16 v[28:31], v[128:131], v[176:179], v[28:31]
	v_mfma_f32_16x16x32_bf16 v[24:27], v[136:139], v[176:179], v[24:27]
	v_mfma_f32_16x16x32_bf16 v[12:15], v[128:131], v[194:197], v[12:15]
	v_mfma_f32_16x16x32_bf16 v[8:11], v[136:139], v[194:197], v[8:11]
	v_mfma_f32_16x16x32_bf16 v[60:63], v[132:135], v[148:151], v[60:63]
	v_mfma_f32_16x16x32_bf16 v[56:59], v[140:143], v[148:151], v[56:59]
	v_mfma_f32_16x16x32_bf16 v[44:47], v[132:135], v[172:175], v[44:47]
	v_mfma_f32_16x16x32_bf16 v[40:43], v[140:143], v[172:175], v[40:43]
	v_mfma_f32_16x16x32_bf16 v[28:31], v[132:135], v[180:183], v[28:31]
	v_mfma_f32_16x16x32_bf16 v[24:27], v[140:143], v[180:183], v[24:27]
	v_mfma_f32_16x16x32_bf16 v[12:15], v[132:135], v[198:201], v[12:15]
	v_mfma_f32_16x16x32_bf16 v[8:11], v[140:143], v[198:201], v[8:11]
	s_setprio 0
	s_barrier
	s_add_u32 s52, s22, 0x40000
	s_addc_u32 s53, s23, 0
	s_add_i32 s54, s46, s35
	v_lshl_add_u64 v[128:129], s[52:53], 0, v[154:155]
	s_mov_b32 m0, s54
	s_nop 0
	global_load_lds_dwordx4 v[128:129], off
	v_lshl_add_u64 v[128:129], s[52:53], 0, v[158:159]
	s_add_i32 m0, s54, 0x2000
	s_nop 0
	global_load_lds_dwordx4 v[128:129], off
	s_waitcnt vmcnt(6)
	s_barrier
	s_setprio 1
	v_mfma_f32_16x16x32_bf16 v[52:55], v[202:205], v[144:147], v[52:55]
	v_mfma_f32_16x16x32_bf16 v[48:51], v[210:213], v[144:147], v[48:51]
	v_mfma_f32_16x16x32_bf16 v[36:39], v[202:205], v[168:171], v[36:39]
	v_mfma_f32_16x16x32_bf16 v[32:35], v[210:213], v[168:171], v[32:35]
	v_mfma_f32_16x16x32_bf16 v[20:23], v[202:205], v[176:179], v[20:23]
	v_mfma_f32_16x16x32_bf16 v[16:19], v[210:213], v[176:179], v[16:19]
	v_mfma_f32_16x16x32_bf16 v[4:7], v[202:205], v[194:197], v[4:7]
	v_mfma_f32_16x16x32_bf16 v[0:3], v[210:213], v[194:197], v[0:3]
	v_mfma_f32_16x16x32_bf16 v[52:55], v[206:209], v[148:151], v[52:55]
	v_mfma_f32_16x16x32_bf16 v[48:51], v[214:217], v[148:151], v[48:51]
	v_mfma_f32_16x16x32_bf16 v[36:39], v[206:209], v[172:175], v[36:39]
	v_mfma_f32_16x16x32_bf16 v[32:35], v[214:217], v[172:175], v[32:35]
	v_mfma_f32_16x16x32_bf16 v[20:23], v[206:209], v[180:183], v[20:23]
	v_mfma_f32_16x16x32_bf16 v[16:19], v[214:217], v[180:183], v[16:19]
	v_mfma_f32_16x16x32_bf16 v[4:7], v[206:209], v[198:201], v[4:7]
	v_mfma_f32_16x16x32_bf16 v[0:3], v[214:217], v[198:201], v[0:3]
	s_setprio 0
	s_add_i32 s52, 0, 0x18000
	v_add_u32_e32 v140, s52, v187
	s_barrier
	ds_read_b128 v[128:131], v140
	ds_read_b128 v[132:135], v140 offset:1024
	ds_read_b128 v[136:139], v140 offset:2048
	ds_read_b128 v[140:143], v140 offset:3072
	s_add_u32 s28, s28, 0x40000
	s_addc_u32 s29, s29, 0
	s_mov_b32 m0, s38
	v_lshl_add_u64 v[202:203], s[28:29], 0, v[152:153]
	ds_read_b128 v[144:147], v191 offset:32768
	ds_read_b128 v[148:151], v191 offset:33792
	ds_read_b128 v[168:171], v191 offset:34816
	ds_read_b128 v[172:175], v191 offset:35840
	ds_read_b128 v[176:179], v191 offset:36864
	ds_read_b128 v[180:183], v191 offset:37888
	ds_read_b128 v[194:197], v191 offset:38912
	ds_read_b128 v[198:201], v191 offset:39936
	global_load_lds_dwordx4 v[202:203], off
	v_lshl_add_u64 v[202:203], s[28:29], 0, v[156:157]
	s_mov_b32 m0, s39
	s_nop 0
	global_load_lds_dwordx4 v[202:203], off
	s_waitcnt lgkmcnt(8)
	s_barrier
	s_waitcnt lgkmcnt(0)
	s_setprio 1
	s_waitcnt lgkmcnt(0)
	v_mfma_f32_16x16x32_bf16 v[124:127], v[128:131], v[144:147], v[124:127]
	v_mfma_f32_16x16x32_bf16 v[120:123], v[136:139], v[144:147], v[120:123]
	v_mfma_f32_16x16x32_bf16 v[108:111], v[128:131], v[168:171], v[108:111]
	v_mfma_f32_16x16x32_bf16 v[104:107], v[136:139], v[168:171], v[104:107]
	v_mfma_f32_16x16x32_bf16 v[92:95], v[128:131], v[176:179], v[92:95]
	v_mfma_f32_16x16x32_bf16 v[88:91], v[136:139], v[176:179], v[88:91]
	v_mfma_f32_16x16x32_bf16 v[76:79], v[128:131], v[194:197], v[76:79]
	v_mfma_f32_16x16x32_bf16 v[72:75], v[136:139], v[194:197], v[72:75]
	v_mfma_f32_16x16x32_bf16 v[124:127], v[132:135], v[148:151], v[124:127]
	v_mfma_f32_16x16x32_bf16 v[120:123], v[140:143], v[148:151], v[120:123]
	v_mfma_f32_16x16x32_bf16 v[108:111], v[132:135], v[172:175], v[108:111]
	v_mfma_f32_16x16x32_bf16 v[104:107], v[140:143], v[172:175], v[104:107]
	v_mfma_f32_16x16x32_bf16 v[92:95], v[132:135], v[180:183], v[92:95]
	v_mfma_f32_16x16x32_bf16 v[88:91], v[140:143], v[180:183], v[88:91]
	v_mfma_f32_16x16x32_bf16 v[76:79], v[132:135], v[198:201], v[76:79]
	v_mfma_f32_16x16x32_bf16 v[72:75], v[140:143], v[198:201], v[72:75]
	s_setprio 0
	s_barrier
	s_add_i32 s28, 0, 0x1c000
	s_add_i32 s29, s52, s35
	v_add_u32_e32 v214, s28, v187
	v_lshl_add_u64 v[184:185], v[184:185], 0, s[8:9]
	s_mov_b32 m0, s29
	ds_read_b128 v[202:205], v214
	ds_read_b128 v[206:209], v214 offset:1024
	ds_read_b128 v[210:213], v214 offset:2048
	ds_read_b128 v[214:217], v214 offset:3072
	global_load_lds_dwordx4 v[184:185], off
	v_lshl_add_u64 v[184:185], v[218:219], 0, s[8:9]
	s_add_i32 m0, s29, 0x2000
	s_nop 0
	global_load_lds_dwordx4 v[184:185], off
	s_barrier
	s_waitcnt lgkmcnt(0)
	s_setprio 1
	s_waitcnt lgkmcnt(0)
	v_mfma_f32_16x16x32_bf16 v[116:119], v[202:205], v[144:147], v[116:119]
	v_mfma_f32_16x16x32_bf16 v[112:115], v[210:213], v[144:147], v[112:115]
	v_mfma_f32_16x16x32_bf16 v[100:103], v[202:205], v[168:171], v[100:103]
	v_mfma_f32_16x16x32_bf16 v[96:99], v[210:213], v[168:171], v[96:99]
	v_mfma_f32_16x16x32_bf16 v[84:87], v[202:205], v[176:179], v[84:87]
	v_mfma_f32_16x16x32_bf16 v[80:83], v[210:213], v[176:179], v[80:83]
	v_mfma_f32_16x16x32_bf16 v[68:71], v[202:205], v[194:197], v[68:71]
	v_mfma_f32_16x16x32_bf16 v[64:67], v[210:213], v[194:197], v[64:67]
	v_mfma_f32_16x16x32_bf16 v[116:119], v[206:209], v[148:151], v[116:119]
	v_mfma_f32_16x16x32_bf16 v[112:115], v[214:217], v[148:151], v[112:115]
	v_mfma_f32_16x16x32_bf16 v[100:103], v[206:209], v[172:175], v[100:103]
	v_mfma_f32_16x16x32_bf16 v[96:99], v[214:217], v[172:175], v[96:99]
	v_mfma_f32_16x16x32_bf16 v[84:87], v[206:209], v[180:183], v[84:87]
	v_mfma_f32_16x16x32_bf16 v[80:83], v[214:217], v[180:183], v[80:83]
	v_mfma_f32_16x16x32_bf16 v[68:71], v[206:209], v[198:201], v[68:71]
	v_mfma_f32_16x16x32_bf16 v[64:67], v[214:217], v[198:201], v[64:67]
	s_setprio 0
	s_mov_b32 m0, s41
	v_lshl_add_u64 v[184:185], v[220:221], 0, s[8:9]
	s_barrier
	ds_read_b128 v[144:147], v191 offset:49152
	ds_read_b128 v[148:151], v191 offset:50176
	ds_read_b128 v[168:171], v191 offset:51200
	ds_read_b128 v[172:175], v191 offset:52224
	ds_read_b128 v[176:179], v191 offset:53248
	ds_read_b128 v[180:183], v191 offset:54272
	ds_read_b128 v[194:197], v191 offset:55296
	ds_read_b128 v[198:201], v191 offset:56320
	global_load_lds_dwordx4 v[184:185], off
	v_lshl_add_u64 v[184:185], v[222:223], 0, s[8:9]
	s_mov_b32 m0, s42
	s_nop 0
	global_load_lds_dwordx4 v[184:185], off
	s_barrier
	s_waitcnt lgkmcnt(0)
	s_setprio 1
	s_waitcnt lgkmcnt(0)
	v_mfma_f32_16x16x32_bf16 v[60:63], v[128:131], v[144:147], v[60:63]
	v_mfma_f32_16x16x32_bf16 v[56:59], v[136:139], v[144:147], v[56:59]
	v_mfma_f32_16x16x32_bf16 v[44:47], v[128:131], v[168:171], v[44:47]
	v_mfma_f32_16x16x32_bf16 v[40:43], v[136:139], v[168:171], v[40:43]
	v_mfma_f32_16x16x32_bf16 v[28:31], v[128:131], v[176:179], v[28:31]
	v_mfma_f32_16x16x32_bf16 v[24:27], v[136:139], v[176:179], v[24:27]
	v_mfma_f32_16x16x32_bf16 v[12:15], v[128:131], v[194:197], v[12:15]
	v_mfma_f32_16x16x32_bf16 v[8:11], v[136:139], v[194:197], v[8:11]
	v_mfma_f32_16x16x32_bf16 v[60:63], v[132:135], v[148:151], v[60:63]
	v_mfma_f32_16x16x32_bf16 v[56:59], v[140:143], v[148:151], v[56:59]
	v_mfma_f32_16x16x32_bf16 v[44:47], v[132:135], v[172:175], v[44:47]
	v_mfma_f32_16x16x32_bf16 v[40:43], v[140:143], v[172:175], v[40:43]
	v_mfma_f32_16x16x32_bf16 v[28:31], v[132:135], v[180:183], v[28:31]
	v_mfma_f32_16x16x32_bf16 v[24:27], v[140:143], v[180:183], v[24:27]
	v_mfma_f32_16x16x32_bf16 v[12:15], v[132:135], v[198:201], v[12:15]
	v_mfma_f32_16x16x32_bf16 v[8:11], v[140:143], v[198:201], v[8:11]
	s_setprio 0
	s_barrier
	s_add_u32 s22, s22, 0x40080
	s_addc_u32 s23, s23, 0
	s_add_i32 s28, s28, s35
	v_lshl_add_u64 v[128:129], s[22:23], 0, v[154:155]
	s_mov_b32 m0, s28
	s_nop 0
	global_load_lds_dwordx4 v[128:129], off
	v_lshl_add_u64 v[128:129], s[22:23], 0, v[158:159]
	s_add_i32 m0, s28, 0x2000
	s_nop 0
	global_load_lds_dwordx4 v[128:129], off
	s_waitcnt vmcnt(6)
	s_barrier
	s_setprio 1
	v_mfma_f32_16x16x32_bf16 v[52:55], v[202:205], v[144:147], v[52:55]
	v_mfma_f32_16x16x32_bf16 v[48:51], v[210:213], v[144:147], v[48:51]
	v_mfma_f32_16x16x32_bf16 v[36:39], v[202:205], v[168:171], v[36:39]
	v_mfma_f32_16x16x32_bf16 v[32:35], v[210:213], v[168:171], v[32:35]
	v_mfma_f32_16x16x32_bf16 v[20:23], v[202:205], v[176:179], v[20:23]
	v_mfma_f32_16x16x32_bf16 v[16:19], v[210:213], v[176:179], v[16:19]
	v_mfma_f32_16x16x32_bf16 v[4:7], v[202:205], v[194:197], v[4:7]
	v_mfma_f32_16x16x32_bf16 v[0:3], v[210:213], v[194:197], v[0:3]
	v_mfma_f32_16x16x32_bf16 v[52:55], v[206:209], v[148:151], v[52:55]
	v_mfma_f32_16x16x32_bf16 v[48:51], v[214:217], v[148:151], v[48:51]
	v_mfma_f32_16x16x32_bf16 v[36:39], v[206:209], v[172:175], v[36:39]
	v_mfma_f32_16x16x32_bf16 v[32:35], v[214:217], v[172:175], v[32:35]
	v_mfma_f32_16x16x32_bf16 v[20:23], v[206:209], v[180:183], v[20:23]
	v_mfma_f32_16x16x32_bf16 v[16:19], v[214:217], v[180:183], v[16:19]
	v_mfma_f32_16x16x32_bf16 v[4:7], v[206:209], v[198:201], v[4:7]
	v_mfma_f32_16x16x32_bf16 v[0:3], v[214:217], v[198:201], v[0:3]
	s_setprio 0
	s_add_i32 s51, s51, 2
	s_add_u32 s20, s20, 0x100
	s_addc_u32 s21, s21, 0
	s_add_u32 s49, s49, 0x100
	s_addc_u32 s50, s50, 0
	s_cmp_gt_u32 s51, 13
	s_barrier
	s_cbranch_scc0 .LBB0_1551
	v_lshl_or_b32 v168, s6, 8, v189
	v_lshl_add_u32 v170, s18, 8, v186
	v_ashrrev_i32_e32 v169, 31, v168
	v_lshlrev_b64 v[202:203], 1, v[168:169]
	v_ashrrev_i32_e32 v171, 31, v170
	v_or_b32_e32 v182, 16, v170
	v_lshl_add_u64 v[172:173], s[64:65], 0, v[202:203]
	v_lshlrev_b64 v[204:205], 11, v[170:171]
	v_ashrrev_i32_e32 v183, 31, v182
	v_or_b32_e32 v178, 32, v170
	v_lshl_add_u64 v[128:129], v[172:173], 0, v[204:205]
	v_lshlrev_b64 v[184:185], 11, v[182:183]
	v_ashrrev_i32_e32 v179, 31, v178
	v_or_b32_e32 v174, 48, v170
	global_load_dwordx4 v[194:197], v[128:129], off
	global_load_dwordx4 v[198:201], v[128:129], off offset:256
	v_lshl_add_u64 v[128:129], v[172:173], 0, v[184:185]
	v_lshlrev_b64 v[180:181], 11, v[178:179]
	v_ashrrev_i32_e32 v175, 31, v174
	global_load_dwordx4 v[148:151], v[128:129], off
	global_load_dwordx4 v[144:147], v[128:129], off offset:256
	v_lshl_add_u64 v[128:129], v[172:173], 0, v[180:181]
	v_lshlrev_b64 v[176:177], 11, v[174:175]
	global_load_dwordx4 v[140:143], v[128:129], off
	global_load_dwordx4 v[136:139], v[128:129], off offset:256
	v_lshl_add_u64 v[128:129], v[172:173], 0, v[176:177]
	global_load_dwordx4 v[132:135], v[128:129], off
	s_nop 0
	global_load_dwordx4 v[128:131], v[128:129], off offset:256
	s_lshl_b32 s18, s6, 2
	s_ashr_i32 s19, s18, 31
	s_waitcnt vmcnt(0)
	v_lshlrev_b32_e32 v206, 16, v194
	v_and_b32_e32 v207, 0xffff0000, v194
	v_lshlrev_b32_e32 v194, 16, v195
	v_and_b32_e32 v195, 0xffff0000, v195
	v_lshlrev_b32_e32 v208, 16, v196
	v_and_b32_e32 v209, 0xffff0000, v196
	v_lshlrev_b32_e32 v196, 16, v197
	v_and_b32_e32 v197, 0xffff0000, v197
	v_pk_add_f32 v[126:127], v[126:127], v[194:195]
	v_pk_add_f32 v[124:125], v[124:125], v[206:207]
	v_pk_add_f32 v[194:195], v[122:123], v[196:197]
	v_pk_add_f32 v[122:123], v[120:121], v[208:209]
	v_mul_f32_e32 v120, v125, v125
	v_mul_f32_e32 v121, v127, v127
	v_fmac_f32_e32 v120, v124, v124
	v_fmac_f32_e32 v121, v126, v126
	v_add_f32_e32 v120, v120, v121
	v_mul_f32_e32 v121, v123, v123
	v_mul_f32_e32 v196, v195, v195
	v_fmac_f32_e32 v121, v122, v122
	v_fmac_f32_e32 v196, v194, v194
	v_add_f32_e32 v121, v121, v196
	v_add_f32_e32 v206, v120, v121
	v_cvt_pk_bf16_f32 v120, v124, v125
	v_cvt_pk_bf16_f32 v121, v126, v127
	v_lshlrev_b32_e32 v124, 16, v198
	v_and_b32_e32 v125, 0xffff0000, v198
	v_lshlrev_b32_e32 v126, 16, v199
	v_and_b32_e32 v127, 0xffff0000, v199
	v_cvt_pk_bf16_f32 v122, v122, v123
	v_cvt_pk_bf16_f32 v123, v194, v195
	v_lshlrev_b32_e32 v194, 16, v200
	v_and_b32_e32 v195, 0xffff0000, v200
	v_pk_add_f32 v[118:119], v[118:119], v[126:127]
	v_pk_add_f32 v[116:117], v[116:117], v[124:125]
	v_lshlrev_b32_e32 v196, 16, v201
	v_and_b32_e32 v197, 0xffff0000, v201
	v_pk_add_f32 v[126:127], v[112:113], v[194:195]
	v_mul_f32_e32 v112, v117, v117
	v_mul_f32_e32 v113, v119, v119
	v_pk_add_f32 v[124:125], v[114:115], v[196:197]
	v_fmac_f32_e32 v112, v116, v116
	v_fmac_f32_e32 v113, v118, v118
	v_add_f32_e32 v112, v112, v113
	v_mul_f32_e32 v113, v127, v127
	v_mul_f32_e32 v114, v125, v125
	v_fmac_f32_e32 v113, v126, v126
	v_fmac_f32_e32 v114, v124, v124
	v_add_f32_e32 v113, v113, v114
	v_add_f32_e32 v112, v112, v113
	v_and_b32_e32 v114, 64, v193
	v_add_f32_e32 v113, v206, v112
	v_xor_b32_e32 v112, 16, v193
	v_add_u32_e32 v196, 64, v114
	v_cmp_lt_i32_e32 vcc, v112, v196
	v_lshl_add_u64 v[114:115], s[64:65], 0, v[204:205]
	v_lshl_add_u64 v[194:195], v[114:115], 0, v[202:203]
	v_cndmask_b32_e32 v112, v193, v112, vcc
	v_lshlrev_b32_e32 v112, 2, v112
	ds_bpermute_b32 v197, v112, v113
	global_store_dwordx4 v[194:195], v[120:123], off nt
	v_cvt_pk_bf16_f32 v116, v116, v117
	v_cvt_pk_bf16_f32 v117, v118, v119
	v_cvt_pk_bf16_f32 v118, v126, v127
	s_waitcnt lgkmcnt(0)
	v_add_f32_e32 v114, v113, v197
	v_xor_b32_e32 v113, 32, v193
	v_cmp_lt_i32_e32 vcc, v113, v196
	v_cvt_pk_bf16_f32 v119, v124, v125
	global_store_dwordx4 v[194:195], v[116:119], off offset:256 nt
	s_nop 0
	v_cndmask_b32_e32 v113, v193, v113, vcc
	v_lshlrev_b32_e32 v113, 2, v113
	ds_bpermute_b32 v115, v113, v114
	s_and_saveexec_b64 s[20:21], s[2:3]
	s_cbranch_execz .LBB0_1554
	s_waitcnt lgkmcnt(0)
	v_add_f32_e32 v116, v114, v115
	v_lshlrev_b64 v[114:115], 6, v[170:171]
	v_lshl_add_u64 v[114:115], s[74:75], 0, v[114:115]
	v_lshl_add_u64 v[114:115], s[18:19], 2, v[114:115]
	s_lshl_b32 s6, s40, 2
	v_lshl_add_u64 v[114:115], v[114:115], 0, s[6:7]
	global_store_dword v[114:115], v116, off
.LBB0_1554:
	s_or_b64 exec, exec, s[20:21]
	v_lshlrev_b32_e32 v114, 16, v148
	s_waitcnt lgkmcnt(0)
	v_and_b32_e32 v115, 0xffff0000, v148
	v_lshlrev_b32_e32 v116, 16, v149
	v_and_b32_e32 v117, 0xffff0000, v149
	v_lshlrev_b32_e32 v118, 16, v150
	v_and_b32_e32 v119, 0xffff0000, v150
	v_lshlrev_b32_e32 v120, 16, v151
	v_and_b32_e32 v121, 0xffff0000, v151
	v_pk_add_f32 v[110:111], v[110:111], v[116:117]
	v_pk_add_f32 v[108:109], v[108:109], v[114:115]
	v_pk_add_f32 v[114:115], v[106:107], v[120:121]
	v_pk_add_f32 v[106:107], v[104:105], v[118:119]
	v_mul_f32_e32 v104, v109, v109
	v_mul_f32_e32 v105, v111, v111
	v_fmac_f32_e32 v104, v108, v108
	v_fmac_f32_e32 v105, v110, v110
	v_add_f32_e32 v104, v104, v105
	v_mul_f32_e32 v105, v107, v107
	v_mul_f32_e32 v116, v115, v115
	v_fmac_f32_e32 v105, v106, v106
	v_fmac_f32_e32 v116, v114, v114
	v_add_f32_e32 v105, v105, v116
	v_add_f32_e32 v118, v104, v105
	v_cvt_pk_bf16_f32 v104, v108, v109
	v_cvt_pk_bf16_f32 v105, v110, v111
	v_lshlrev_b32_e32 v108, 16, v144
	v_and_b32_e32 v109, 0xffff0000, v144
	v_lshlrev_b32_e32 v110, 16, v145
	v_and_b32_e32 v111, 0xffff0000, v145
	v_cvt_pk_bf16_f32 v106, v106, v107
	v_cvt_pk_bf16_f32 v107, v114, v115
	v_lshlrev_b32_e32 v114, 16, v146
	v_and_b32_e32 v115, 0xffff0000, v146
	v_pk_add_f32 v[102:103], v[102:103], v[110:111]
	v_pk_add_f32 v[100:101], v[100:101], v[108:109]
	v_lshlrev_b32_e32 v116, 16, v147
	v_and_b32_e32 v117, 0xffff0000, v147
	v_pk_add_f32 v[110:111], v[96:97], v[114:115]
	v_mul_f32_e32 v96, v101, v101
	v_mul_f32_e32 v97, v103, v103
	v_pk_add_f32 v[108:109], v[98:99], v[116:117]
	v_fmac_f32_e32 v96, v100, v100
	v_fmac_f32_e32 v97, v102, v102
	v_add_f32_e32 v96, v96, v97
	v_mul_f32_e32 v97, v111, v111
	v_mul_f32_e32 v98, v109, v109
	v_fmac_f32_e32 v97, v110, v110
	v_fmac_f32_e32 v98, v108, v108
	v_add_f32_e32 v97, v97, v98
	v_add_f32_e32 v96, v96, v97
	v_add_f32_e32 v99, v118, v96
	ds_bpermute_b32 v116, v112, v99
	v_lshl_add_u64 v[96:97], s[64:65], 0, v[184:185]
	v_lshl_add_u64 v[114:115], v[168:169], 1, v[96:97]
	global_store_dwordx4 v[114:115], v[104:107], off nt
	v_cvt_pk_bf16_f32 v98, v100, v101
	s_waitcnt lgkmcnt(0)
	v_add_f32_e32 v96, v99, v116
	ds_bpermute_b32 v97, v113, v96
	v_cvt_pk_bf16_f32 v99, v102, v103
	v_cvt_pk_bf16_f32 v100, v110, v111
	v_cvt_pk_bf16_f32 v101, v108, v109
	global_store_dwordx4 v[114:115], v[98:101], off offset:256 nt
	s_and_saveexec_b64 s[20:21], s[2:3]
	s_cbranch_execz .LBB0_1556
	s_waitcnt lgkmcnt(0)
	v_add_f32_e32 v98, v96, v97
	v_lshlrev_b64 v[96:97], 6, v[182:183]
	v_lshl_add_u64 v[96:97], s[74:75], 0, v[96:97]
	v_lshl_add_u64 v[96:97], s[18:19], 2, v[96:97]
	s_lshl_b32 s6, s40, 2
	v_lshl_add_u64 v[96:97], v[96:97], 0, s[6:7]
	global_store_dword v[96:97], v98, off
.LBB0_1556:
	s_or_b64 exec, exec, s[20:21]
	v_lshlrev_b32_e32 v96, 16, v140
	s_waitcnt lgkmcnt(0)
	v_and_b32_e32 v97, 0xffff0000, v140
	v_lshlrev_b32_e32 v98, 16, v141
	v_and_b32_e32 v99, 0xffff0000, v141
	v_lshlrev_b32_e32 v100, 16, v142
	v_and_b32_e32 v101, 0xffff0000, v142
	v_lshlrev_b32_e32 v102, 16, v143
	v_and_b32_e32 v103, 0xffff0000, v143
	v_pk_add_f32 v[94:95], v[94:95], v[98:99]
	v_pk_add_f32 v[92:93], v[92:93], v[96:97]
	v_pk_add_f32 v[96:97], v[90:91], v[102:103]
	v_pk_add_f32 v[90:91], v[88:89], v[100:101]
	v_mul_f32_e32 v88, v93, v93
	v_mul_f32_e32 v89, v95, v95
	v_fmac_f32_e32 v88, v92, v92
	v_fmac_f32_e32 v89, v94, v94
	v_add_f32_e32 v88, v88, v89
	v_mul_f32_e32 v89, v91, v91
	v_mul_f32_e32 v98, v97, v97
	v_fmac_f32_e32 v89, v90, v90
	v_fmac_f32_e32 v98, v96, v96
	v_add_f32_e32 v89, v89, v98
	v_add_f32_e32 v100, v88, v89
	v_cvt_pk_bf16_f32 v88, v92, v93
	v_cvt_pk_bf16_f32 v89, v94, v95
	v_lshlrev_b32_e32 v92, 16, v136
	v_and_b32_e32 v93, 0xffff0000, v136
	v_lshlrev_b32_e32 v94, 16, v137
	v_and_b32_e32 v95, 0xffff0000, v137
	v_cvt_pk_bf16_f32 v90, v90, v91
	v_cvt_pk_bf16_f32 v91, v96, v97
	v_lshlrev_b32_e32 v96, 16, v138
	v_and_b32_e32 v97, 0xffff0000, v138
	v_pk_add_f32 v[86:87], v[86:87], v[94:95]
	v_pk_add_f32 v[84:85], v[84:85], v[92:93]
	v_lshlrev_b32_e32 v98, 16, v139
	v_and_b32_e32 v99, 0xffff0000, v139
	v_pk_add_f32 v[94:95], v[80:81], v[96:97]
	v_mul_f32_e32 v80, v85, v85
	v_mul_f32_e32 v81, v87, v87
	v_pk_add_f32 v[92:93], v[82:83], v[98:99]
	v_fmac_f32_e32 v80, v84, v84
	v_fmac_f32_e32 v81, v86, v86
	v_add_f32_e32 v80, v80, v81
	v_mul_f32_e32 v81, v95, v95
	v_mul_f32_e32 v82, v93, v93
	v_fmac_f32_e32 v81, v94, v94
	v_fmac_f32_e32 v82, v92, v92
	v_add_f32_e32 v81, v81, v82
	v_add_f32_e32 v80, v80, v81
	v_add_f32_e32 v83, v100, v80
	ds_bpermute_b32 v98, v112, v83
	v_lshl_add_u64 v[80:81], s[64:65], 0, v[180:181]
	v_lshl_add_u64 v[96:97], v[168:169], 1, v[80:81]
	global_store_dwordx4 v[96:97], v[88:91], off nt
	v_cvt_pk_bf16_f32 v82, v84, v85
	s_waitcnt lgkmcnt(0)
	v_add_f32_e32 v80, v83, v98
	ds_bpermute_b32 v81, v113, v80
	v_cvt_pk_bf16_f32 v83, v86, v87
	v_cvt_pk_bf16_f32 v84, v94, v95
	v_cvt_pk_bf16_f32 v85, v92, v93
	global_store_dwordx4 v[96:97], v[82:85], off offset:256 nt
	s_and_saveexec_b64 s[20:21], s[2:3]
	s_cbranch_execz .LBB0_1558
	s_waitcnt lgkmcnt(0)
	v_add_f32_e32 v82, v80, v81
	v_lshlrev_b64 v[80:81], 6, v[178:179]
	v_lshl_add_u64 v[80:81], s[74:75], 0, v[80:81]
	v_lshl_add_u64 v[80:81], s[18:19], 2, v[80:81]
	s_lshl_b32 s6, s40, 2
	v_lshl_add_u64 v[80:81], v[80:81], 0, s[6:7]
	global_store_dword v[80:81], v82, off
.LBB0_1558:
	s_or_b64 exec, exec, s[20:21]
	v_lshlrev_b32_e32 v80, 16, v132
	s_waitcnt lgkmcnt(0)
	v_and_b32_e32 v81, 0xffff0000, v132
	v_lshlrev_b32_e32 v82, 16, v133
	v_and_b32_e32 v83, 0xffff0000, v133
	v_lshlrev_b32_e32 v84, 16, v134
	v_and_b32_e32 v85, 0xffff0000, v134
	v_lshlrev_b32_e32 v86, 16, v135
	v_and_b32_e32 v87, 0xffff0000, v135
	v_pk_add_f32 v[78:79], v[78:79], v[82:83]
	v_pk_add_f32 v[76:77], v[76:77], v[80:81]
	v_pk_add_f32 v[80:81], v[74:75], v[86:87]
	v_pk_add_f32 v[74:75], v[72:73], v[84:85]
	v_mul_f32_e32 v72, v77, v77
	v_mul_f32_e32 v73, v79, v79
	v_fmac_f32_e32 v72, v76, v76
	v_fmac_f32_e32 v73, v78, v78
	v_add_f32_e32 v72, v72, v73
	v_mul_f32_e32 v73, v75, v75
	v_mul_f32_e32 v82, v81, v81
	v_fmac_f32_e32 v73, v74, v74
	v_fmac_f32_e32 v82, v80, v80
	v_add_f32_e32 v73, v73, v82
	v_add_f32_e32 v84, v72, v73
	v_cvt_pk_bf16_f32 v72, v76, v77
	v_cvt_pk_bf16_f32 v73, v78, v79
	v_lshlrev_b32_e32 v76, 16, v128
	v_and_b32_e32 v77, 0xffff0000, v128
	v_lshlrev_b32_e32 v78, 16, v129
	v_and_b32_e32 v79, 0xffff0000, v129
	v_cvt_pk_bf16_f32 v74, v74, v75
	v_cvt_pk_bf16_f32 v75, v80, v81
	v_lshlrev_b32_e32 v80, 16, v130
	v_and_b32_e32 v81, 0xffff0000, v130
	v_pk_add_f32 v[70:71], v[70:71], v[78:79]
	v_pk_add_f32 v[68:69], v[68:69], v[76:77]
	v_lshlrev_b32_e32 v82, 16, v131
	v_and_b32_e32 v83, 0xffff0000, v131
	v_pk_add_f32 v[78:79], v[64:65], v[80:81]
	v_mul_f32_e32 v64, v69, v69
	v_mul_f32_e32 v65, v71, v71
	v_pk_add_f32 v[76:77], v[66:67], v[82:83]
	v_fmac_f32_e32 v64, v68, v68
	v_fmac_f32_e32 v65, v70, v70
	v_add_f32_e32 v64, v64, v65
	v_mul_f32_e32 v65, v79, v79
	v_mul_f32_e32 v66, v77, v77
	v_fmac_f32_e32 v65, v78, v78
	v_fmac_f32_e32 v66, v76, v76
	v_add_f32_e32 v65, v65, v66
	v_add_f32_e32 v64, v64, v65
	v_add_f32_e32 v67, v84, v64
	ds_bpermute_b32 v82, v112, v67
	v_lshl_add_u64 v[64:65], s[64:65], 0, v[176:177]
	v_lshl_add_u64 v[80:81], v[168:169], 1, v[64:65]
	global_store_dwordx4 v[80:81], v[72:75], off nt
	v_cvt_pk_bf16_f32 v66, v68, v69
	s_waitcnt lgkmcnt(0)
	v_add_f32_e32 v64, v67, v82
	ds_bpermute_b32 v65, v113, v64
	v_cvt_pk_bf16_f32 v67, v70, v71
	v_cvt_pk_bf16_f32 v68, v78, v79
	v_cvt_pk_bf16_f32 v69, v76, v77
	global_store_dwordx4 v[80:81], v[66:69], off offset:256 nt
	s_and_saveexec_b64 s[20:21], s[2:3]
	s_cbranch_execz .LBB0_1560
	s_waitcnt lgkmcnt(0)
	v_add_f32_e32 v66, v64, v65
	v_lshlrev_b64 v[64:65], 6, v[174:175]
	v_lshl_add_u64 v[64:65], s[74:75], 0, v[64:65]
	v_lshl_add_u64 v[64:65], s[18:19], 2, v[64:65]
	s_lshl_b32 s6, s40, 2
	v_lshl_add_u64 v[64:65], v[64:65], 0, s[6:7]
	global_store_dword v[64:65], v66, off
.LBB0_1560:
	s_or_b64 exec, exec, s[20:21]
	v_add_u32_e32 v100, 0x80, v170
	v_ashrrev_i32_e32 v101, 31, v100
	v_add_u32_e32 v96, 0x90, v170
	v_lshlrev_b64 v[110:111], 11, v[100:101]
	v_ashrrev_i32_e32 v97, 31, v96
	v_add_u32_e32 v92, 0xa0, v170
	s_waitcnt lgkmcnt(0)
	v_lshl_add_u64 v[64:65], v[172:173], 0, v[110:111]
	v_lshlrev_b64 v[98:99], 11, v[96:97]
	v_ashrrev_i32_e32 v93, 31, v92
	v_add_u32_e32 v88, 0xb0, v170
	global_load_dwordx4 v[102:105], v[64:65], off
	global_load_dwordx4 v[106:109], v[64:65], off offset:256
	v_lshl_add_u64 v[64:65], v[172:173], 0, v[98:99]
	v_lshlrev_b64 v[94:95], 11, v[92:93]
	v_ashrrev_i32_e32 v89, 31, v88
	global_load_dwordx4 v[84:87], v[64:65], off
	global_load_dwordx4 v[80:83], v[64:65], off offset:256
	v_lshl_add_u64 v[64:65], v[172:173], 0, v[94:95]
	v_lshlrev_b64 v[90:91], 11, v[88:89]
	global_load_dwordx4 v[76:79], v[64:65], off
	global_load_dwordx4 v[72:75], v[64:65], off offset:256
	v_lshl_add_u64 v[64:65], v[172:173], 0, v[90:91]
	global_load_dwordx4 v[68:71], v[64:65], off
	s_nop 0
	global_load_dwordx4 v[64:67], v[64:65], off offset:256
	s_waitcnt vmcnt(7)
	v_lshlrev_b32_e32 v114, 16, v102
	v_and_b32_e32 v115, 0xffff0000, v102
	v_lshlrev_b32_e32 v102, 16, v103
	v_and_b32_e32 v103, 0xffff0000, v103
	v_lshlrev_b32_e32 v116, 16, v104
	v_and_b32_e32 v117, 0xffff0000, v104
	v_lshlrev_b32_e32 v104, 16, v105
	v_and_b32_e32 v105, 0xffff0000, v105
	v_pk_add_f32 v[62:63], v[62:63], v[102:103]
	v_pk_add_f32 v[60:61], v[60:61], v[114:115]
	v_pk_add_f32 v[102:103], v[58:59], v[104:105]
	v_pk_add_f32 v[58:59], v[56:57], v[116:117]
	v_mul_f32_e32 v56, v61, v61
	v_mul_f32_e32 v57, v63, v63
	v_fmac_f32_e32 v56, v60, v60
	v_fmac_f32_e32 v57, v62, v62
	v_add_f32_e32 v56, v56, v57
	v_mul_f32_e32 v57, v59, v59
	v_mul_f32_e32 v104, v103, v103
	v_fmac_f32_e32 v57, v58, v58
	v_fmac_f32_e32 v104, v102, v102
	v_add_f32_e32 v57, v57, v104
	v_add_f32_e32 v114, v56, v57
	v_cvt_pk_bf16_f32 v56, v60, v61
	v_cvt_pk_bf16_f32 v57, v62, v63
	s_waitcnt vmcnt(6)
	v_lshlrev_b32_e32 v60, 16, v106
	v_and_b32_e32 v61, 0xffff0000, v106
	v_lshlrev_b32_e32 v62, 16, v107
	v_and_b32_e32 v63, 0xffff0000, v107
	v_cvt_pk_bf16_f32 v58, v58, v59
	v_cvt_pk_bf16_f32 v59, v102, v103
	v_lshlrev_b32_e32 v102, 16, v108
	v_and_b32_e32 v103, 0xffff0000, v108
	v_pk_add_f32 v[54:55], v[54:55], v[62:63]
	v_pk_add_f32 v[52:53], v[52:53], v[60:61]
	v_lshlrev_b32_e32 v104, 16, v109
	v_and_b32_e32 v105, 0xffff0000, v109
	v_pk_add_f32 v[62:63], v[48:49], v[102:103]
	v_mul_f32_e32 v48, v53, v53
	v_mul_f32_e32 v49, v55, v55
	v_pk_add_f32 v[60:61], v[50:51], v[104:105]
	v_fmac_f32_e32 v48, v52, v52
	v_fmac_f32_e32 v49, v54, v54
	v_add_f32_e32 v48, v48, v49
	v_mul_f32_e32 v49, v63, v63
	v_mul_f32_e32 v50, v61, v61
	v_fmac_f32_e32 v49, v62, v62
	v_fmac_f32_e32 v50, v60, v60
	v_add_f32_e32 v49, v49, v50
	v_add_f32_e32 v48, v48, v49
	v_add_f32_e32 v51, v114, v48
	ds_bpermute_b32 v104, v112, v51
	v_lshl_add_u64 v[48:49], s[64:65], 0, v[110:111]
	v_lshl_add_u64 v[102:103], v[168:169], 1, v[48:49]
	global_store_dwordx4 v[102:103], v[56:59], off nt
	v_cvt_pk_bf16_f32 v50, v52, v53
	s_waitcnt lgkmcnt(0)
	v_add_f32_e32 v48, v51, v104
	ds_bpermute_b32 v49, v113, v48
	v_cvt_pk_bf16_f32 v51, v54, v55
	v_cvt_pk_bf16_f32 v52, v62, v63
	v_cvt_pk_bf16_f32 v53, v60, v61
	global_store_dwordx4 v[102:103], v[50:53], off offset:256 nt
	s_and_saveexec_b64 s[20:21], s[2:3]
	s_cbranch_execz .LBB0_1562
	s_waitcnt lgkmcnt(0)
	v_add_f32_e32 v50, v48, v49
	v_lshlrev_b64 v[48:49], 6, v[100:101]
	v_lshl_add_u64 v[48:49], s[74:75], 0, v[48:49]
	v_lshl_add_u64 v[48:49], s[18:19], 2, v[48:49]
	s_lshl_b32 s6, s40, 2
	v_lshl_add_u64 v[48:49], v[48:49], 0, s[6:7]
	global_store_dword v[48:49], v50, off
.LBB0_1562:
	s_or_b64 exec, exec, s[20:21]
	s_waitcnt vmcnt(7)
	v_lshlrev_b32_e32 v48, 16, v84
	s_waitcnt lgkmcnt(0)
	v_and_b32_e32 v49, 0xffff0000, v84
	v_lshlrev_b32_e32 v50, 16, v85
	v_and_b32_e32 v51, 0xffff0000, v85
	v_lshlrev_b32_e32 v52, 16, v86
	v_and_b32_e32 v53, 0xffff0000, v86
	v_lshlrev_b32_e32 v54, 16, v87
	v_and_b32_e32 v55, 0xffff0000, v87
	v_pk_add_f32 v[46:47], v[46:47], v[50:51]
	v_pk_add_f32 v[44:45], v[44:45], v[48:49]
	v_pk_add_f32 v[48:49], v[42:43], v[54:55]
	v_pk_add_f32 v[42:43], v[40:41], v[52:53]
	v_mul_f32_e32 v40, v45, v45
	v_mul_f32_e32 v41, v47, v47
	v_fmac_f32_e32 v40, v44, v44
	v_fmac_f32_e32 v41, v46, v46
	v_add_f32_e32 v40, v40, v41
	v_mul_f32_e32 v41, v43, v43
	v_mul_f32_e32 v50, v49, v49
	v_fmac_f32_e32 v41, v42, v42
	v_fmac_f32_e32 v50, v48, v48
	v_add_f32_e32 v41, v41, v50
	v_add_f32_e32 v52, v40, v41
	v_cvt_pk_bf16_f32 v40, v44, v45
	v_cvt_pk_bf16_f32 v41, v46, v47
	s_waitcnt vmcnt(6)
	v_lshlrev_b32_e32 v44, 16, v80
	v_and_b32_e32 v45, 0xffff0000, v80
	v_lshlrev_b32_e32 v46, 16, v81
	v_and_b32_e32 v47, 0xffff0000, v81
	v_cvt_pk_bf16_f32 v42, v42, v43
	v_cvt_pk_bf16_f32 v43, v48, v49
	v_lshlrev_b32_e32 v48, 16, v82
	v_and_b32_e32 v49, 0xffff0000, v82
	v_pk_add_f32 v[38:39], v[38:39], v[46:47]
	v_pk_add_f32 v[36:37], v[36:37], v[44:45]
	v_lshlrev_b32_e32 v50, 16, v83
	v_and_b32_e32 v51, 0xffff0000, v83
	v_pk_add_f32 v[46:47], v[32:33], v[48:49]
	v_mul_f32_e32 v32, v37, v37
	v_mul_f32_e32 v33, v39, v39
	v_pk_add_f32 v[44:45], v[34:35], v[50:51]
	v_fmac_f32_e32 v32, v36, v36
	v_fmac_f32_e32 v33, v38, v38
	v_add_f32_e32 v32, v32, v33
	v_mul_f32_e32 v33, v47, v47
	v_mul_f32_e32 v34, v45, v45
	v_fmac_f32_e32 v33, v46, v46
	v_fmac_f32_e32 v34, v44, v44
	v_add_f32_e32 v33, v33, v34
	v_add_f32_e32 v32, v32, v33
	v_add_f32_e32 v35, v52, v32
	ds_bpermute_b32 v50, v112, v35
	v_lshl_add_u64 v[32:33], s[64:65], 0, v[98:99]
	v_lshl_add_u64 v[48:49], v[168:169], 1, v[32:33]
	global_store_dwordx4 v[48:49], v[40:43], off nt
	v_cvt_pk_bf16_f32 v34, v36, v37
	s_waitcnt lgkmcnt(0)
	v_add_f32_e32 v32, v35, v50
	ds_bpermute_b32 v33, v113, v32
	v_cvt_pk_bf16_f32 v35, v38, v39
	v_cvt_pk_bf16_f32 v36, v46, v47
	v_cvt_pk_bf16_f32 v37, v44, v45
	global_store_dwordx4 v[48:49], v[34:37], off offset:256 nt
	s_and_saveexec_b64 s[20:21], s[2:3]
	s_cbranch_execz .LBB0_1564
	s_waitcnt lgkmcnt(0)
	v_add_f32_e32 v34, v32, v33
	v_lshlrev_b64 v[32:33], 6, v[96:97]
	v_lshl_add_u64 v[32:33], s[74:75], 0, v[32:33]
	v_lshl_add_u64 v[32:33], s[18:19], 2, v[32:33]
	s_lshl_b32 s6, s40, 2
	v_lshl_add_u64 v[32:33], v[32:33], 0, s[6:7]
	global_store_dword v[32:33], v34, off
.LBB0_1564:
	s_or_b64 exec, exec, s[20:21]
	s_waitcnt vmcnt(7)
	v_lshlrev_b32_e32 v32, 16, v76
	s_waitcnt lgkmcnt(0)
	v_and_b32_e32 v33, 0xffff0000, v76
	v_lshlrev_b32_e32 v34, 16, v77
	v_and_b32_e32 v35, 0xffff0000, v77
	v_lshlrev_b32_e32 v36, 16, v78
	v_and_b32_e32 v37, 0xffff0000, v78
	v_lshlrev_b32_e32 v38, 16, v79
	v_and_b32_e32 v39, 0xffff0000, v79
	v_pk_add_f32 v[30:31], v[30:31], v[34:35]
	v_pk_add_f32 v[28:29], v[28:29], v[32:33]
	v_pk_add_f32 v[32:33], v[26:27], v[38:39]
	v_pk_add_f32 v[26:27], v[24:25], v[36:37]
	v_mul_f32_e32 v24, v29, v29
	v_mul_f32_e32 v25, v31, v31
	v_fmac_f32_e32 v24, v28, v28
	v_fmac_f32_e32 v25, v30, v30
	v_add_f32_e32 v24, v24, v25
	v_mul_f32_e32 v25, v27, v27
	v_mul_f32_e32 v34, v33, v33
	v_fmac_f32_e32 v25, v26, v26
	v_fmac_f32_e32 v34, v32, v32
	v_add_f32_e32 v25, v25, v34
	v_add_f32_e32 v36, v24, v25
	v_cvt_pk_bf16_f32 v24, v28, v29
	v_cvt_pk_bf16_f32 v25, v30, v31
	s_waitcnt vmcnt(6)
	v_lshlrev_b32_e32 v28, 16, v72
	v_and_b32_e32 v29, 0xffff0000, v72
	v_lshlrev_b32_e32 v30, 16, v73
	v_and_b32_e32 v31, 0xffff0000, v73
	v_cvt_pk_bf16_f32 v26, v26, v27
	v_cvt_pk_bf16_f32 v27, v32, v33
	v_lshlrev_b32_e32 v32, 16, v74
	v_and_b32_e32 v33, 0xffff0000, v74
	v_pk_add_f32 v[22:23], v[22:23], v[30:31]
	v_pk_add_f32 v[20:21], v[20:21], v[28:29]
	v_lshlrev_b32_e32 v34, 16, v75
	v_and_b32_e32 v35, 0xffff0000, v75
	v_pk_add_f32 v[30:31], v[16:17], v[32:33]
	v_mul_f32_e32 v16, v21, v21
	v_mul_f32_e32 v17, v23, v23
	v_pk_add_f32 v[28:29], v[18:19], v[34:35]
	v_fmac_f32_e32 v16, v20, v20
	v_fmac_f32_e32 v17, v22, v22
	v_add_f32_e32 v16, v16, v17
	v_mul_f32_e32 v17, v31, v31
	v_mul_f32_e32 v18, v29, v29
	v_fmac_f32_e32 v17, v30, v30
	v_fmac_f32_e32 v18, v28, v28
	v_add_f32_e32 v17, v17, v18
	v_add_f32_e32 v16, v16, v17
	v_add_f32_e32 v19, v36, v16
	ds_bpermute_b32 v34, v112, v19
	v_lshl_add_u64 v[16:17], s[64:65], 0, v[94:95]
	v_lshl_add_u64 v[32:33], v[168:169], 1, v[16:17]
	global_store_dwordx4 v[32:33], v[24:27], off nt
	v_cvt_pk_bf16_f32 v18, v20, v21
	s_waitcnt lgkmcnt(0)
	v_add_f32_e32 v16, v19, v34
	ds_bpermute_b32 v17, v113, v16
	v_cvt_pk_bf16_f32 v19, v22, v23
	v_cvt_pk_bf16_f32 v20, v30, v31
	v_cvt_pk_bf16_f32 v21, v28, v29
	global_store_dwordx4 v[32:33], v[18:21], off offset:256 nt
	s_and_saveexec_b64 s[20:21], s[2:3]
	s_cbranch_execz .LBB0_1566
	s_waitcnt lgkmcnt(0)
	v_add_f32_e32 v18, v16, v17
	v_lshlrev_b64 v[16:17], 6, v[92:93]
	v_lshl_add_u64 v[16:17], s[74:75], 0, v[16:17]
	v_lshl_add_u64 v[16:17], s[18:19], 2, v[16:17]
	s_lshl_b32 s6, s40, 2
	v_lshl_add_u64 v[16:17], v[16:17], 0, s[6:7]
	global_store_dword v[16:17], v18, off
.LBB0_1566:
	s_or_b64 exec, exec, s[20:21]
	s_waitcnt vmcnt(7)
	v_lshlrev_b32_e32 v16, 16, v68
	s_waitcnt lgkmcnt(0)
	v_and_b32_e32 v17, 0xffff0000, v68
	v_lshlrev_b32_e32 v18, 16, v69
	v_and_b32_e32 v19, 0xffff0000, v69
	v_lshlrev_b32_e32 v20, 16, v70
	v_and_b32_e32 v21, 0xffff0000, v70
	v_lshlrev_b32_e32 v22, 16, v71
	v_and_b32_e32 v23, 0xffff0000, v71
	v_pk_add_f32 v[14:15], v[14:15], v[18:19]
	v_pk_add_f32 v[12:13], v[12:13], v[16:17]
	v_pk_add_f32 v[16:17], v[10:11], v[22:23]
	v_pk_add_f32 v[10:11], v[8:9], v[20:21]
	v_mul_f32_e32 v8, v13, v13
	v_mul_f32_e32 v9, v15, v15
	v_fmac_f32_e32 v8, v12, v12
	v_fmac_f32_e32 v9, v14, v14
	v_add_f32_e32 v8, v8, v9
	v_mul_f32_e32 v9, v11, v11
	v_mul_f32_e32 v18, v17, v17
	v_fmac_f32_e32 v9, v10, v10
	v_fmac_f32_e32 v18, v16, v16
	v_add_f32_e32 v9, v9, v18
	v_add_f32_e32 v20, v8, v9
	v_cvt_pk_bf16_f32 v8, v12, v13
	v_cvt_pk_bf16_f32 v9, v14, v15
	s_waitcnt vmcnt(6)
	v_lshlrev_b32_e32 v12, 16, v64
	v_and_b32_e32 v13, 0xffff0000, v64
	v_lshlrev_b32_e32 v14, 16, v65
	v_and_b32_e32 v15, 0xffff0000, v65
	v_cvt_pk_bf16_f32 v10, v10, v11
	v_cvt_pk_bf16_f32 v11, v16, v17
	v_lshlrev_b32_e32 v16, 16, v66
	v_and_b32_e32 v17, 0xffff0000, v66
	v_pk_add_f32 v[6:7], v[6:7], v[14:15]
	v_pk_add_f32 v[4:5], v[4:5], v[12:13]
	v_lshlrev_b32_e32 v18, 16, v67
	v_and_b32_e32 v19, 0xffff0000, v67
	v_pk_add_f32 v[14:15], v[0:1], v[16:17]
	v_mul_f32_e32 v0, v5, v5
	v_mul_f32_e32 v1, v7, v7
	v_pk_add_f32 v[12:13], v[2:3], v[18:19]
	v_fmac_f32_e32 v0, v4, v4
	v_fmac_f32_e32 v1, v6, v6
	v_add_f32_e32 v0, v0, v1
	v_mul_f32_e32 v1, v15, v15
	v_mul_f32_e32 v2, v13, v13
	v_fmac_f32_e32 v1, v14, v14
	v_fmac_f32_e32 v2, v12, v12
	v_add_f32_e32 v1, v1, v2
	v_add_f32_e32 v0, v0, v1
	v_add_f32_e32 v3, v20, v0
	ds_bpermute_b32 v18, v112, v3
	v_lshl_add_u64 v[0:1], s[64:65], 0, v[90:91]
	v_lshl_add_u64 v[16:17], v[168:169], 1, v[0:1]
	global_store_dwordx4 v[16:17], v[8:11], off nt
	v_cvt_pk_bf16_f32 v2, v4, v5
	s_waitcnt lgkmcnt(0)
	v_add_f32_e32 v0, v3, v18
	ds_bpermute_b32 v1, v113, v0
	v_cvt_pk_bf16_f32 v3, v6, v7
	v_cvt_pk_bf16_f32 v4, v14, v15
	v_cvt_pk_bf16_f32 v5, v12, v13
	global_store_dwordx4 v[16:17], v[2:5], off offset:256 nt
	s_and_saveexec_b64 s[20:21], s[2:3]
	s_cbranch_execz .LBB0_1543
	s_waitcnt lgkmcnt(0)
	v_add_f32_e32 v2, v0, v1
	v_lshlrev_b64 v[0:1], 6, v[88:89]
	v_lshl_add_u64 v[0:1], s[74:75], 0, v[0:1]
	v_lshl_add_u64 v[0:1], s[18:19], 2, v[0:1]
	s_lshl_b32 s6, s40, 2
	v_lshl_add_u64 v[0:1], v[0:1], 0, s[6:7]
	global_store_dword v[0:1], v2, off
	s_branch .LBB0_1543

.LBB0_1741:
	ds_read_b128 v[128:131], v190
	ds_read_b128 v[132:135], v190 offset:1024
	ds_read_b128 v[136:139], v190 offset:2048
	ds_read_b128 v[140:143], v190 offset:3072
	s_add_u32 s16, s14, 0x100
	s_addc_u32 s17, s15, 0
	s_cmp_eq_u32 s47, 40
	s_cselect_b32 s21, s1, s17
	s_cselect_b32 s20, s0, s16
	s_cselect_b32 s19, s7, s46
	s_cselect_b32 s18, s6, s45
	v_lshl_add_u64 v[184:185], s[14:15], 0, v[160:161]
	s_add_i32 m0, s28, 0xc000
	ds_read_b128 v[144:147], v191
	ds_read_b128 v[148:151], v191 offset:1024
	ds_read_b128 v[168:171], v191 offset:2048
	ds_read_b128 v[172:175], v191 offset:3072
	ds_read_b128 v[176:179], v191 offset:4096
	ds_read_b128 v[180:183], v191 offset:5120
	ds_read_b128 v[194:197], v191 offset:6144
	ds_read_b128 v[198:201], v191 offset:7168
	global_load_lds_dwordx4 v[184:185], off
	v_lshl_add_u64 v[184:185], s[14:15], 0, v[162:163]
	s_add_i32 m0, s28, 0xe000
	s_nop 0
	global_load_lds_dwordx4 v[184:185], off
	s_waitcnt lgkmcnt(8)
	s_barrier
	s_waitcnt lgkmcnt(0)
	s_setprio 1
	s_waitcnt lgkmcnt(0)
	v_mfma_f32_16x16x32_bf16 v[124:127], v[128:131], v[144:147], v[124:127]
	v_mfma_f32_16x16x32_bf16 v[120:123], v[136:139], v[144:147], v[120:123]
	v_mfma_f32_16x16x32_bf16 v[108:111], v[128:131], v[168:171], v[108:111]
	v_mfma_f32_16x16x32_bf16 v[104:107], v[136:139], v[168:171], v[104:107]
	v_mfma_f32_16x16x32_bf16 v[92:95], v[128:131], v[176:179], v[92:95]
	v_mfma_f32_16x16x32_bf16 v[88:91], v[136:139], v[176:179], v[88:91]
	v_mfma_f32_16x16x32_bf16 v[76:79], v[128:131], v[194:197], v[76:79]
	v_mfma_f32_16x16x32_bf16 v[72:75], v[136:139], v[194:197], v[72:75]
	v_mfma_f32_16x16x32_bf16 v[124:127], v[132:135], v[148:151], v[124:127]
	v_mfma_f32_16x16x32_bf16 v[120:123], v[140:143], v[148:151], v[120:123]
	v_mfma_f32_16x16x32_bf16 v[108:111], v[132:135], v[172:175], v[108:111]
	v_mfma_f32_16x16x32_bf16 v[104:107], v[140:143], v[172:175], v[104:107]
	v_mfma_f32_16x16x32_bf16 v[92:95], v[132:135], v[180:183], v[92:95]
	v_mfma_f32_16x16x32_bf16 v[88:91], v[140:143], v[180:183], v[88:91]
	v_mfma_f32_16x16x32_bf16 v[76:79], v[132:135], v[198:201], v[76:79]
	v_mfma_f32_16x16x32_bf16 v[72:75], v[140:143], v[198:201], v[72:75]
	s_setprio 0
	s_barrier
	s_add_i32 s14, s39, s27
	v_lshl_add_u64 v[184:185], s[18:19], 0, v[154:155]
	s_mov_b32 m0, s14
	ds_read_b128 v[202:205], v192
	ds_read_b128 v[206:209], v192 offset:1024
	ds_read_b128 v[210:213], v192 offset:2048
	ds_read_b128 v[214:217], v192 offset:3072
	global_load_lds_dwordx4 v[184:185], off
	v_lshl_add_u64 v[218:219], s[18:19], 0, v[158:159]
	s_add_i32 m0, s14, 0x2000
	s_nop 0
	global_load_lds_dwordx4 v[218:219], off
	s_barrier
	s_waitcnt lgkmcnt(0)
	s_setprio 1
	s_waitcnt lgkmcnt(0)
	v_mfma_f32_16x16x32_bf16 v[116:119], v[202:205], v[144:147], v[116:119]
	v_mfma_f32_16x16x32_bf16 v[112:115], v[210:213], v[144:147], v[112:115]
	v_mfma_f32_16x16x32_bf16 v[100:103], v[202:205], v[168:171], v[100:103]
	v_mfma_f32_16x16x32_bf16 v[96:99], v[210:213], v[168:171], v[96:99]
	v_mfma_f32_16x16x32_bf16 v[84:87], v[202:205], v[176:179], v[84:87]
	v_mfma_f32_16x16x32_bf16 v[80:83], v[210:213], v[176:179], v[80:83]
	v_mfma_f32_16x16x32_bf16 v[68:71], v[202:205], v[194:197], v[68:71]
	v_mfma_f32_16x16x32_bf16 v[64:67], v[210:213], v[194:197], v[64:67]
	v_mfma_f32_16x16x32_bf16 v[116:119], v[206:209], v[148:151], v[116:119]
	v_mfma_f32_16x16x32_bf16 v[112:115], v[214:217], v[148:151], v[112:115]
	v_mfma_f32_16x16x32_bf16 v[100:103], v[206:209], v[172:175], v[100:103]
	v_mfma_f32_16x16x32_bf16 v[96:99], v[214:217], v[172:175], v[96:99]
	v_mfma_f32_16x16x32_bf16 v[84:87], v[206:209], v[180:183], v[84:87]
	v_mfma_f32_16x16x32_bf16 v[80:83], v[214:217], v[180:183], v[80:83]
	v_mfma_f32_16x16x32_bf16 v[68:71], v[206:209], v[198:201], v[68:71]
	v_mfma_f32_16x16x32_bf16 v[64:67], v[214:217], v[198:201], v[64:67]
	s_setprio 0
	s_mov_b32 m0, s28
	v_lshl_add_u64 v[220:221], s[20:21], 0, v[152:153]
	s_barrier
	ds_read_b128 v[144:147], v191 offset:16384
	ds_read_b128 v[148:151], v191 offset:17408
	ds_read_b128 v[168:171], v191 offset:18432
	ds_read_b128 v[172:175], v191 offset:19456
	ds_read_b128 v[176:179], v191 offset:20480
	ds_read_b128 v[180:183], v191 offset:21504
	ds_read_b128 v[194:197], v191 offset:22528
	ds_read_b128 v[198:201], v191 offset:23552
	global_load_lds_dwordx4 v[220:221], off
	v_lshl_add_u64 v[222:223], s[20:21], 0, v[156:157]
	s_mov_b32 m0, s29
	s_nop 0
	global_load_lds_dwordx4 v[222:223], off
	s_barrier
	s_waitcnt lgkmcnt(0)
	s_setprio 1
	s_waitcnt lgkmcnt(0)
	v_mfma_f32_16x16x32_bf16 v[60:63], v[128:131], v[144:147], v[60:63]
	v_mfma_f32_16x16x32_bf16 v[56:59], v[136:139], v[144:147], v[56:59]
	v_mfma_f32_16x16x32_bf16 v[44:47], v[128:131], v[168:171], v[44:47]
	v_mfma_f32_16x16x32_bf16 v[40:43], v[136:139], v[168:171], v[40:43]
	v_mfma_f32_16x16x32_bf16 v[28:31], v[128:131], v[176:179], v[28:31]
	v_mfma_f32_16x16x32_bf16 v[24:27], v[136:139], v[176:179], v[24:27]
	v_mfma_f32_16x16x32_bf16 v[12:15], v[128:131], v[194:197], v[12:15]
	v_mfma_f32_16x16x32_bf16 v[8:11], v[136:139], v[194:197], v[8:11]
	v_mfma_f32_16x16x32_bf16 v[60:63], v[132:135], v[148:151], v[60:63]
	v_mfma_f32_16x16x32_bf16 v[56:59], v[140:143], v[148:151], v[56:59]
	v_mfma_f32_16x16x32_bf16 v[44:47], v[132:135], v[172:175], v[44:47]
	v_mfma_f32_16x16x32_bf16 v[40:43], v[140:143], v[172:175], v[40:43]
	v_mfma_f32_16x16x32_bf16 v[28:31], v[132:135], v[180:183], v[28:31]
	v_mfma_f32_16x16x32_bf16 v[24:27], v[140:143], v[180:183], v[24:27]
	v_mfma_f32_16x16x32_bf16 v[12:15], v[132:135], v[198:201], v[12:15]
	v_mfma_f32_16x16x32_bf16 v[8:11], v[140:143], v[198:201], v[8:11]
	s_setprio 0
	s_barrier
	s_add_u32 s14, s18, 0xb0000
	s_addc_u32 s15, s19, 0
	s_add_i32 s48, s40, s27
	v_lshl_add_u64 v[128:129], s[14:15], 0, v[154:155]
	s_mov_b32 m0, s48
	s_nop 0
	global_load_lds_dwordx4 v[128:129], off
	v_lshl_add_u64 v[128:129], s[14:15], 0, v[158:159]
	s_add_i32 m0, s48, 0x2000
	s_nop 0
	global_load_lds_dwordx4 v[128:129], off
	s_waitcnt vmcnt(6)
	s_barrier
	s_setprio 1
	v_mfma_f32_16x16x32_bf16 v[52:55], v[202:205], v[144:147], v[52:55]
	v_mfma_f32_16x16x32_bf16 v[48:51], v[210:213], v[144:147], v[48:51]
	v_mfma_f32_16x16x32_bf16 v[36:39], v[202:205], v[168:171], v[36:39]
	v_mfma_f32_16x16x32_bf16 v[32:35], v[210:213], v[168:171], v[32:35]
	v_mfma_f32_16x16x32_bf16 v[20:23], v[202:205], v[176:179], v[20:23]
	v_mfma_f32_16x16x32_bf16 v[16:19], v[210:213], v[176:179], v[16:19]
	v_mfma_f32_16x16x32_bf16 v[4:7], v[202:205], v[194:197], v[4:7]
	v_mfma_f32_16x16x32_bf16 v[0:3], v[210:213], v[194:197], v[0:3]
	v_mfma_f32_16x16x32_bf16 v[52:55], v[206:209], v[148:151], v[52:55]
	v_mfma_f32_16x16x32_bf16 v[48:51], v[214:217], v[148:151], v[48:51]
	v_mfma_f32_16x16x32_bf16 v[36:39], v[206:209], v[172:175], v[36:39]
	v_mfma_f32_16x16x32_bf16 v[32:35], v[214:217], v[172:175], v[32:35]
	v_mfma_f32_16x16x32_bf16 v[20:23], v[206:209], v[180:183], v[20:23]
	v_mfma_f32_16x16x32_bf16 v[16:19], v[214:217], v[180:183], v[16:19]
	v_mfma_f32_16x16x32_bf16 v[4:7], v[206:209], v[198:201], v[4:7]
	v_mfma_f32_16x16x32_bf16 v[0:3], v[214:217], v[198:201], v[0:3]
	s_setprio 0
	s_add_i32 s48, 0, 0x18000
	v_add_u32_e32 v140, s48, v187
	s_barrier
	ds_read_b128 v[128:131], v140
	ds_read_b128 v[132:135], v140 offset:1024
	ds_read_b128 v[136:139], v140 offset:2048
	ds_read_b128 v[140:143], v140 offset:3072
	s_add_u32 s14, s20, 0xb0000
	s_addc_u32 s15, s21, 0
	s_mov_b32 m0, s30
	v_lshl_add_u64 v[202:203], s[14:15], 0, v[152:153]
	ds_read_b128 v[144:147], v191 offset:32768
	ds_read_b128 v[148:151], v191 offset:33792
	ds_read_b128 v[168:171], v191 offset:34816
	ds_read_b128 v[172:175], v191 offset:35840
	ds_read_b128 v[176:179], v191 offset:36864
	ds_read_b128 v[180:183], v191 offset:37888
	ds_read_b128 v[194:197], v191 offset:38912
	ds_read_b128 v[198:201], v191 offset:39936
	global_load_lds_dwordx4 v[202:203], off
	v_lshl_add_u64 v[202:203], s[14:15], 0, v[156:157]
	s_mov_b32 m0, s31
	s_nop 0
	global_load_lds_dwordx4 v[202:203], off
	s_waitcnt lgkmcnt(8)
	s_barrier
	s_waitcnt lgkmcnt(0)
	s_setprio 1
	s_waitcnt lgkmcnt(0)
	v_mfma_f32_16x16x32_bf16 v[124:127], v[128:131], v[144:147], v[124:127]
	v_mfma_f32_16x16x32_bf16 v[120:123], v[136:139], v[144:147], v[120:123]
	v_mfma_f32_16x16x32_bf16 v[108:111], v[128:131], v[168:171], v[108:111]
	v_mfma_f32_16x16x32_bf16 v[104:107], v[136:139], v[168:171], v[104:107]
	v_mfma_f32_16x16x32_bf16 v[92:95], v[128:131], v[176:179], v[92:95]
	v_mfma_f32_16x16x32_bf16 v[88:91], v[136:139], v[176:179], v[88:91]
	v_mfma_f32_16x16x32_bf16 v[76:79], v[128:131], v[194:197], v[76:79]
	v_mfma_f32_16x16x32_bf16 v[72:75], v[136:139], v[194:197], v[72:75]
	v_mfma_f32_16x16x32_bf16 v[124:127], v[132:135], v[148:151], v[124:127]
	v_mfma_f32_16x16x32_bf16 v[120:123], v[140:143], v[148:151], v[120:123]
	v_mfma_f32_16x16x32_bf16 v[108:111], v[132:135], v[172:175], v[108:111]
	v_mfma_f32_16x16x32_bf16 v[104:107], v[140:143], v[172:175], v[104:107]
	v_mfma_f32_16x16x32_bf16 v[92:95], v[132:135], v[180:183], v[92:95]
	v_mfma_f32_16x16x32_bf16 v[88:91], v[140:143], v[180:183], v[88:91]
	v_mfma_f32_16x16x32_bf16 v[76:79], v[132:135], v[198:201], v[76:79]
	v_mfma_f32_16x16x32_bf16 v[72:75], v[140:143], v[198:201], v[72:75]
	s_setprio 0
	s_barrier
	s_add_i32 s20, 0, 0x1c000
	s_add_i32 s14, s48, s27
	v_add_u32_e32 v214, s20, v187
	v_lshl_add_u64 v[184:185], v[184:185], 0, s[12:13]
	s_mov_b32 m0, s14
	ds_read_b128 v[202:205], v214
	ds_read_b128 v[206:209], v214 offset:1024
	ds_read_b128 v[210:213], v214 offset:2048
	ds_read_b128 v[214:217], v214 offset:3072
	global_load_lds_dwordx4 v[184:185], off
	v_lshl_add_u64 v[184:185], v[218:219], 0, s[12:13]
	s_add_i32 m0, s14, 0x2000
	s_nop 0
	global_load_lds_dwordx4 v[184:185], off
	s_barrier
	s_waitcnt lgkmcnt(0)
	s_setprio 1
	s_waitcnt lgkmcnt(0)
	v_mfma_f32_16x16x32_bf16 v[116:119], v[202:205], v[144:147], v[116:119]
	v_mfma_f32_16x16x32_bf16 v[112:115], v[210:213], v[144:147], v[112:115]
	v_mfma_f32_16x16x32_bf16 v[100:103], v[202:205], v[168:171], v[100:103]
	v_mfma_f32_16x16x32_bf16 v[96:99], v[210:213], v[168:171], v[96:99]
	v_mfma_f32_16x16x32_bf16 v[84:87], v[202:205], v[176:179], v[84:87]
	v_mfma_f32_16x16x32_bf16 v[80:83], v[210:213], v[176:179], v[80:83]
	v_mfma_f32_16x16x32_bf16 v[68:71], v[202:205], v[194:197], v[68:71]
	v_mfma_f32_16x16x32_bf16 v[64:67], v[210:213], v[194:197], v[64:67]
	v_mfma_f32_16x16x32_bf16 v[116:119], v[206:209], v[148:151], v[116:119]
	v_mfma_f32_16x16x32_bf16 v[112:115], v[214:217], v[148:151], v[112:115]
	v_mfma_f32_16x16x32_bf16 v[100:103], v[206:209], v[172:175], v[100:103]
	v_mfma_f32_16x16x32_bf16 v[96:99], v[214:217], v[172:175], v[96:99]
	v_mfma_f32_16x16x32_bf16 v[84:87], v[206:209], v[180:183], v[84:87]
	v_mfma_f32_16x16x32_bf16 v[80:83], v[214:217], v[180:183], v[80:83]
	v_mfma_f32_16x16x32_bf16 v[68:71], v[206:209], v[198:201], v[68:71]
	v_mfma_f32_16x16x32_bf16 v[64:67], v[214:217], v[198:201], v[64:67]
	s_setprio 0
	s_mov_b32 m0, s35
	v_lshl_add_u64 v[184:185], v[220:221], 0, s[12:13]
	s_barrier
	ds_read_b128 v[144:147], v191 offset:49152
	ds_read_b128 v[148:151], v191 offset:50176
	ds_read_b128 v[168:171], v191 offset:51200
	ds_read_b128 v[172:175], v191 offset:52224
	ds_read_b128 v[176:179], v191 offset:53248
	ds_read_b128 v[180:183], v191 offset:54272
	ds_read_b128 v[194:197], v191 offset:55296
	ds_read_b128 v[198:201], v191 offset:56320
	global_load_lds_dwordx4 v[184:185], off
	v_lshl_add_u64 v[184:185], v[222:223], 0, s[12:13]
	s_mov_b32 m0, s36
	s_nop 0
	global_load_lds_dwordx4 v[184:185], off
	s_barrier
	s_waitcnt lgkmcnt(0)
	s_setprio 1
	s_waitcnt lgkmcnt(0)
	v_mfma_f32_16x16x32_bf16 v[60:63], v[128:131], v[144:147], v[60:63]
	v_mfma_f32_16x16x32_bf16 v[56:59], v[136:139], v[144:147], v[56:59]
	v_mfma_f32_16x16x32_bf16 v[44:47], v[128:131], v[168:171], v[44:47]
	v_mfma_f32_16x16x32_bf16 v[40:43], v[136:139], v[168:171], v[40:43]
	v_mfma_f32_16x16x32_bf16 v[28:31], v[128:131], v[176:179], v[28:31]
	v_mfma_f32_16x16x32_bf16 v[24:27], v[136:139], v[176:179], v[24:27]
	v_mfma_f32_16x16x32_bf16 v[12:15], v[128:131], v[194:197], v[12:15]
	v_mfma_f32_16x16x32_bf16 v[8:11], v[136:139], v[194:197], v[8:11]
	v_mfma_f32_16x16x32_bf16 v[60:63], v[132:135], v[148:151], v[60:63]
	v_mfma_f32_16x16x32_bf16 v[56:59], v[140:143], v[148:151], v[56:59]
	v_mfma_f32_16x16x32_bf16 v[44:47], v[132:135], v[172:175], v[44:47]
	v_mfma_f32_16x16x32_bf16 v[40:43], v[140:143], v[172:175], v[40:43]
	v_mfma_f32_16x16x32_bf16 v[28:31], v[132:135], v[180:183], v[28:31]
	v_mfma_f32_16x16x32_bf16 v[24:27], v[140:143], v[180:183], v[24:27]
	v_mfma_f32_16x16x32_bf16 v[12:15], v[132:135], v[198:201], v[12:15]
	v_mfma_f32_16x16x32_bf16 v[8:11], v[140:143], v[198:201], v[8:11]
	s_setprio 0
	s_barrier
	s_add_u32 s14, s18, 0xb0080
	s_addc_u32 s15, s19, 0
	s_add_i32 s18, s20, s27
	v_lshl_add_u64 v[128:129], s[14:15], 0, v[154:155]
	s_mov_b32 m0, s18
	s_nop 0
	global_load_lds_dwordx4 v[128:129], off
	v_lshl_add_u64 v[128:129], s[14:15], 0, v[158:159]
	s_add_i32 m0, s18, 0x2000
	s_nop 0
	global_load_lds_dwordx4 v[128:129], off
	s_waitcnt vmcnt(6)
	s_barrier
	s_setprio 1
	v_mfma_f32_16x16x32_bf16 v[52:55], v[202:205], v[144:147], v[52:55]
	v_mfma_f32_16x16x32_bf16 v[48:51], v[210:213], v[144:147], v[48:51]
	v_mfma_f32_16x16x32_bf16 v[36:39], v[202:205], v[168:171], v[36:39]
	v_mfma_f32_16x16x32_bf16 v[32:35], v[210:213], v[168:171], v[32:35]
	v_mfma_f32_16x16x32_bf16 v[20:23], v[202:205], v[176:179], v[20:23]
	v_mfma_f32_16x16x32_bf16 v[16:19], v[210:213], v[176:179], v[16:19]
	v_mfma_f32_16x16x32_bf16 v[4:7], v[202:205], v[194:197], v[4:7]
	v_mfma_f32_16x16x32_bf16 v[0:3], v[210:213], v[194:197], v[0:3]
	v_mfma_f32_16x16x32_bf16 v[52:55], v[206:209], v[148:151], v[52:55]
	v_mfma_f32_16x16x32_bf16 v[48:51], v[214:217], v[148:151], v[48:51]
	v_mfma_f32_16x16x32_bf16 v[36:39], v[206:209], v[172:175], v[36:39]
	v_mfma_f32_16x16x32_bf16 v[32:35], v[214:217], v[172:175], v[32:35]
	v_mfma_f32_16x16x32_bf16 v[20:23], v[206:209], v[180:183], v[20:23]
	v_mfma_f32_16x16x32_bf16 v[16:19], v[214:217], v[180:183], v[16:19]
	v_mfma_f32_16x16x32_bf16 v[4:7], v[206:209], v[198:201], v[4:7]
	v_mfma_f32_16x16x32_bf16 v[0:3], v[214:217], v[198:201], v[0:3]
	s_setprio 0
	s_add_i32 s47, s47, 2
	s_add_u32 s45, s45, 0x100
	s_addc_u32 s46, s46, 0
	s_cmp_gt_u32 s47, 41
	s_mov_b64 s[14:15], s[16:17]
	s_barrier
	s_cbranch_scc0 .LBB0_1741
	v_lshl_or_b32 v168, s10, 8, v189
	v_lshl_add_u32 v170, s44, 8, v186
	v_ashrrev_i32_e32 v169, 31, v168
	v_lshlrev_b64 v[202:203], 1, v[168:169]
	v_ashrrev_i32_e32 v171, 31, v170
	v_or_b32_e32 v182, 16, v170
	v_lshl_add_u64 v[172:173], s[64:65], 0, v[202:203]
	v_lshlrev_b64 v[204:205], 11, v[170:171]
	v_ashrrev_i32_e32 v183, 31, v182
	v_or_b32_e32 v178, 32, v170
	v_lshl_add_u64 v[128:129], v[172:173], 0, v[204:205]
	v_lshlrev_b64 v[184:185], 11, v[182:183]
	v_ashrrev_i32_e32 v179, 31, v178
	v_or_b32_e32 v174, 48, v170
	global_load_dwordx4 v[194:197], v[128:129], off
	global_load_dwordx4 v[198:201], v[128:129], off offset:256
	v_lshl_add_u64 v[128:129], v[172:173], 0, v[184:185]
	v_lshlrev_b64 v[180:181], 11, v[178:179]
	v_ashrrev_i32_e32 v175, 31, v174
	global_load_dwordx4 v[148:151], v[128:129], off
	global_load_dwordx4 v[144:147], v[128:129], off offset:256
	v_lshl_add_u64 v[128:129], v[172:173], 0, v[180:181]
	v_lshlrev_b64 v[176:177], 11, v[174:175]
	global_load_dwordx4 v[140:143], v[128:129], off
	global_load_dwordx4 v[136:139], v[128:129], off offset:256
	v_lshl_add_u64 v[128:129], v[172:173], 0, v[176:177]
	global_load_dwordx4 v[132:135], v[128:129], off
	s_nop 0
	global_load_dwordx4 v[128:131], v[128:129], off offset:256
	s_lshl_b32 s14, s10, 2
	s_ashr_i32 s15, s14, 31
	s_waitcnt vmcnt(0)
	v_lshlrev_b32_e32 v206, 16, v194
	v_and_b32_e32 v207, 0xffff0000, v194
	v_lshlrev_b32_e32 v194, 16, v195
	v_and_b32_e32 v195, 0xffff0000, v195
	v_lshlrev_b32_e32 v208, 16, v196
	v_and_b32_e32 v209, 0xffff0000, v196
	v_lshlrev_b32_e32 v196, 16, v197
	v_and_b32_e32 v197, 0xffff0000, v197
	v_pk_add_f32 v[126:127], v[126:127], v[194:195]
	v_pk_add_f32 v[124:125], v[124:125], v[206:207]
	v_pk_add_f32 v[194:195], v[122:123], v[196:197]
	v_pk_add_f32 v[122:123], v[120:121], v[208:209]
	v_mul_f32_e32 v120, v125, v125
	v_mul_f32_e32 v121, v127, v127
	v_fmac_f32_e32 v120, v124, v124
	v_fmac_f32_e32 v121, v126, v126
	v_add_f32_e32 v120, v120, v121
	v_mul_f32_e32 v121, v123, v123
	v_mul_f32_e32 v196, v195, v195
	v_fmac_f32_e32 v121, v122, v122
	v_fmac_f32_e32 v196, v194, v194
	v_add_f32_e32 v121, v121, v196
	v_add_f32_e32 v206, v120, v121
	v_cvt_pk_bf16_f32 v120, v124, v125
	v_cvt_pk_bf16_f32 v121, v126, v127
	v_lshlrev_b32_e32 v124, 16, v198
	v_and_b32_e32 v125, 0xffff0000, v198
	v_lshlrev_b32_e32 v126, 16, v199
	v_and_b32_e32 v127, 0xffff0000, v199
	v_cvt_pk_bf16_f32 v122, v122, v123
	v_cvt_pk_bf16_f32 v123, v194, v195
	v_lshlrev_b32_e32 v194, 16, v200
	v_and_b32_e32 v195, 0xffff0000, v200
	v_pk_add_f32 v[118:119], v[118:119], v[126:127]
	v_pk_add_f32 v[116:117], v[116:117], v[124:125]
	v_lshlrev_b32_e32 v196, 16, v201
	v_and_b32_e32 v197, 0xffff0000, v201
	v_pk_add_f32 v[126:127], v[112:113], v[194:195]
	v_mul_f32_e32 v112, v117, v117
	v_mul_f32_e32 v113, v119, v119
	v_pk_add_f32 v[124:125], v[114:115], v[196:197]
	v_fmac_f32_e32 v112, v116, v116
	v_fmac_f32_e32 v113, v118, v118
	v_add_f32_e32 v112, v112, v113
	v_mul_f32_e32 v113, v127, v127
	v_mul_f32_e32 v114, v125, v125
	v_fmac_f32_e32 v113, v126, v126
	v_fmac_f32_e32 v114, v124, v124
	v_add_f32_e32 v113, v113, v114
	v_add_f32_e32 v112, v112, v113
	v_and_b32_e32 v114, 64, v193
	v_add_f32_e32 v113, v206, v112
	v_xor_b32_e32 v112, 16, v193
	v_add_u32_e32 v196, 64, v114
	v_cmp_lt_i32_e32 vcc, v112, v196
	v_lshl_add_u64 v[114:115], s[64:65], 0, v[204:205]
	v_lshl_add_u64 v[194:195], v[114:115], 0, v[202:203]
	v_cndmask_b32_e32 v112, v193, v112, vcc
	v_lshlrev_b32_e32 v112, 2, v112
	ds_bpermute_b32 v197, v112, v113
	global_store_dwordx4 v[194:195], v[120:123], off nt
	v_cvt_pk_bf16_f32 v116, v116, v117
	v_cvt_pk_bf16_f32 v117, v118, v119
	v_cvt_pk_bf16_f32 v118, v126, v127
	s_waitcnt lgkmcnt(0)
	v_add_f32_e32 v114, v113, v197
	v_xor_b32_e32 v113, 32, v193
	v_cmp_lt_i32_e32 vcc, v113, v196
	v_cvt_pk_bf16_f32 v119, v124, v125
	global_store_dwordx4 v[194:195], v[116:119], off offset:256 nt
	s_nop 0
	v_cndmask_b32_e32 v113, v193, v113, vcc
	v_lshlrev_b32_e32 v113, 2, v113
	ds_bpermute_b32 v115, v113, v114
	s_and_saveexec_b64 s[16:17], s[2:3]
	s_cbranch_execz .LBB0_1744
	s_waitcnt lgkmcnt(0)
	v_add_f32_e32 v116, v114, v115
	v_lshlrev_b64 v[114:115], 6, v[170:171]
	v_lshl_add_u64 v[114:115], s[74:75], 0, v[114:115]
	v_lshl_add_u64 v[114:115], s[14:15], 2, v[114:115]
	s_lshl_b32 s10, s34, 2
	v_lshl_add_u64 v[114:115], v[114:115], 0, s[10:11]
	global_store_dword v[114:115], v116, off
.LBB0_1744:
	s_or_b64 exec, exec, s[16:17]
	v_lshlrev_b32_e32 v114, 16, v148
	s_waitcnt lgkmcnt(0)
	v_and_b32_e32 v115, 0xffff0000, v148
	v_lshlrev_b32_e32 v116, 16, v149
	v_and_b32_e32 v117, 0xffff0000, v149
	v_lshlrev_b32_e32 v118, 16, v150
	v_and_b32_e32 v119, 0xffff0000, v150
	v_lshlrev_b32_e32 v120, 16, v151
	v_and_b32_e32 v121, 0xffff0000, v151
	v_pk_add_f32 v[110:111], v[110:111], v[116:117]
	v_pk_add_f32 v[108:109], v[108:109], v[114:115]
	v_pk_add_f32 v[114:115], v[106:107], v[120:121]
	v_pk_add_f32 v[106:107], v[104:105], v[118:119]
	v_mul_f32_e32 v104, v109, v109
	v_mul_f32_e32 v105, v111, v111
	v_fmac_f32_e32 v104, v108, v108
	v_fmac_f32_e32 v105, v110, v110
	v_add_f32_e32 v104, v104, v105
	v_mul_f32_e32 v105, v107, v107
	v_mul_f32_e32 v116, v115, v115
	v_fmac_f32_e32 v105, v106, v106
	v_fmac_f32_e32 v116, v114, v114
	v_add_f32_e32 v105, v105, v116
	v_add_f32_e32 v118, v104, v105
	v_cvt_pk_bf16_f32 v104, v108, v109
	v_cvt_pk_bf16_f32 v105, v110, v111
	v_lshlrev_b32_e32 v108, 16, v144
	v_and_b32_e32 v109, 0xffff0000, v144
	v_lshlrev_b32_e32 v110, 16, v145
	v_and_b32_e32 v111, 0xffff0000, v145
	v_cvt_pk_bf16_f32 v106, v106, v107
	v_cvt_pk_bf16_f32 v107, v114, v115
	v_lshlrev_b32_e32 v114, 16, v146
	v_and_b32_e32 v115, 0xffff0000, v146
	v_pk_add_f32 v[102:103], v[102:103], v[110:111]
	v_pk_add_f32 v[100:101], v[100:101], v[108:109]
	v_lshlrev_b32_e32 v116, 16, v147
	v_and_b32_e32 v117, 0xffff0000, v147
	v_pk_add_f32 v[110:111], v[96:97], v[114:115]
	v_mul_f32_e32 v96, v101, v101
	v_mul_f32_e32 v97, v103, v103
	v_pk_add_f32 v[108:109], v[98:99], v[116:117]
	v_fmac_f32_e32 v96, v100, v100
	v_fmac_f32_e32 v97, v102, v102
	v_add_f32_e32 v96, v96, v97
	v_mul_f32_e32 v97, v111, v111
	v_mul_f32_e32 v98, v109, v109
	v_fmac_f32_e32 v97, v110, v110
	v_fmac_f32_e32 v98, v108, v108
	v_add_f32_e32 v97, v97, v98
	v_add_f32_e32 v96, v96, v97
	v_add_f32_e32 v99, v118, v96
	ds_bpermute_b32 v116, v112, v99
	v_lshl_add_u64 v[96:97], s[64:65], 0, v[184:185]
	v_lshl_add_u64 v[114:115], v[168:169], 1, v[96:97]
	global_store_dwordx4 v[114:115], v[104:107], off nt
	v_cvt_pk_bf16_f32 v98, v100, v101
	s_waitcnt lgkmcnt(0)
	v_add_f32_e32 v96, v99, v116
	ds_bpermute_b32 v97, v113, v96
	v_cvt_pk_bf16_f32 v99, v102, v103
	v_cvt_pk_bf16_f32 v100, v110, v111
	v_cvt_pk_bf16_f32 v101, v108, v109
	global_store_dwordx4 v[114:115], v[98:101], off offset:256 nt
	s_and_saveexec_b64 s[16:17], s[2:3]
	s_cbranch_execz .LBB0_1746
	s_waitcnt lgkmcnt(0)
	v_add_f32_e32 v98, v96, v97
	v_lshlrev_b64 v[96:97], 6, v[182:183]
	v_lshl_add_u64 v[96:97], s[74:75], 0, v[96:97]
	v_lshl_add_u64 v[96:97], s[14:15], 2, v[96:97]
	s_lshl_b32 s10, s34, 2
	v_lshl_add_u64 v[96:97], v[96:97], 0, s[10:11]
	global_store_dword v[96:97], v98, off
.LBB0_1746:
	s_or_b64 exec, exec, s[16:17]
	v_lshlrev_b32_e32 v96, 16, v140
	s_waitcnt lgkmcnt(0)
	v_and_b32_e32 v97, 0xffff0000, v140
	v_lshlrev_b32_e32 v98, 16, v141
	v_and_b32_e32 v99, 0xffff0000, v141
	v_lshlrev_b32_e32 v100, 16, v142
	v_and_b32_e32 v101, 0xffff0000, v142
	v_lshlrev_b32_e32 v102, 16, v143
	v_and_b32_e32 v103, 0xffff0000, v143
	v_pk_add_f32 v[94:95], v[94:95], v[98:99]
	v_pk_add_f32 v[92:93], v[92:93], v[96:97]
	v_pk_add_f32 v[96:97], v[90:91], v[102:103]
	v_pk_add_f32 v[90:91], v[88:89], v[100:101]
	v_mul_f32_e32 v88, v93, v93
	v_mul_f32_e32 v89, v95, v95
	v_fmac_f32_e32 v88, v92, v92
	v_fmac_f32_e32 v89, v94, v94
	v_add_f32_e32 v88, v88, v89
	v_mul_f32_e32 v89, v91, v91
	v_mul_f32_e32 v98, v97, v97
	v_fmac_f32_e32 v89, v90, v90
	v_fmac_f32_e32 v98, v96, v96
	v_add_f32_e32 v89, v89, v98
	v_add_f32_e32 v100, v88, v89
	v_cvt_pk_bf16_f32 v88, v92, v93
	v_cvt_pk_bf16_f32 v89, v94, v95
	v_lshlrev_b32_e32 v92, 16, v136
	v_and_b32_e32 v93, 0xffff0000, v136
	v_lshlrev_b32_e32 v94, 16, v137
	v_and_b32_e32 v95, 0xffff0000, v137
	v_cvt_pk_bf16_f32 v90, v90, v91
	v_cvt_pk_bf16_f32 v91, v96, v97
	v_lshlrev_b32_e32 v96, 16, v138
	v_and_b32_e32 v97, 0xffff0000, v138
	v_pk_add_f32 v[86:87], v[86:87], v[94:95]
	v_pk_add_f32 v[84:85], v[84:85], v[92:93]
	v_lshlrev_b32_e32 v98, 16, v139
	v_and_b32_e32 v99, 0xffff0000, v139
	v_pk_add_f32 v[94:95], v[80:81], v[96:97]
	v_mul_f32_e32 v80, v85, v85
	v_mul_f32_e32 v81, v87, v87
	v_pk_add_f32 v[92:93], v[82:83], v[98:99]
	v_fmac_f32_e32 v80, v84, v84
	v_fmac_f32_e32 v81, v86, v86
	v_add_f32_e32 v80, v80, v81
	v_mul_f32_e32 v81, v95, v95
	v_mul_f32_e32 v82, v93, v93
	v_fmac_f32_e32 v81, v94, v94
	v_fmac_f32_e32 v82, v92, v92
	v_add_f32_e32 v81, v81, v82
	v_add_f32_e32 v80, v80, v81
	v_add_f32_e32 v83, v100, v80
	ds_bpermute_b32 v98, v112, v83
	v_lshl_add_u64 v[80:81], s[64:65], 0, v[180:181]
	v_lshl_add_u64 v[96:97], v[168:169], 1, v[80:81]
	global_store_dwordx4 v[96:97], v[88:91], off nt
	v_cvt_pk_bf16_f32 v82, v84, v85
	s_waitcnt lgkmcnt(0)
	v_add_f32_e32 v80, v83, v98
	ds_bpermute_b32 v81, v113, v80
	v_cvt_pk_bf16_f32 v83, v86, v87
	v_cvt_pk_bf16_f32 v84, v94, v95
	v_cvt_pk_bf16_f32 v85, v92, v93
	global_store_dwordx4 v[96:97], v[82:85], off offset:256 nt
	s_and_saveexec_b64 s[16:17], s[2:3]
	s_cbranch_execz .LBB0_1748
	s_waitcnt lgkmcnt(0)
	v_add_f32_e32 v82, v80, v81
	v_lshlrev_b64 v[80:81], 6, v[178:179]
	v_lshl_add_u64 v[80:81], s[74:75], 0, v[80:81]
	v_lshl_add_u64 v[80:81], s[14:15], 2, v[80:81]
	s_lshl_b32 s10, s34, 2
	v_lshl_add_u64 v[80:81], v[80:81], 0, s[10:11]
	global_store_dword v[80:81], v82, off
.LBB0_1748:
	s_or_b64 exec, exec, s[16:17]
	v_lshlrev_b32_e32 v80, 16, v132
	s_waitcnt lgkmcnt(0)
	v_and_b32_e32 v81, 0xffff0000, v132
	v_lshlrev_b32_e32 v82, 16, v133
	v_and_b32_e32 v83, 0xffff0000, v133
	v_lshlrev_b32_e32 v84, 16, v134
	v_and_b32_e32 v85, 0xffff0000, v134
	v_lshlrev_b32_e32 v86, 16, v135
	v_and_b32_e32 v87, 0xffff0000, v135
	v_pk_add_f32 v[78:79], v[78:79], v[82:83]
	v_pk_add_f32 v[76:77], v[76:77], v[80:81]
	v_pk_add_f32 v[80:81], v[74:75], v[86:87]
	v_pk_add_f32 v[74:75], v[72:73], v[84:85]
	v_mul_f32_e32 v72, v77, v77
	v_mul_f32_e32 v73, v79, v79
	v_fmac_f32_e32 v72, v76, v76
	v_fmac_f32_e32 v73, v78, v78
	v_add_f32_e32 v72, v72, v73
	v_mul_f32_e32 v73, v75, v75
	v_mul_f32_e32 v82, v81, v81
	v_fmac_f32_e32 v73, v74, v74
	v_fmac_f32_e32 v82, v80, v80
	v_add_f32_e32 v73, v73, v82
	v_add_f32_e32 v84, v72, v73
	v_cvt_pk_bf16_f32 v72, v76, v77
	v_cvt_pk_bf16_f32 v73, v78, v79
	v_lshlrev_b32_e32 v76, 16, v128
	v_and_b32_e32 v77, 0xffff0000, v128
	v_lshlrev_b32_e32 v78, 16, v129
	v_and_b32_e32 v79, 0xffff0000, v129
	v_cvt_pk_bf16_f32 v74, v74, v75
	v_cvt_pk_bf16_f32 v75, v80, v81
	v_lshlrev_b32_e32 v80, 16, v130
	v_and_b32_e32 v81, 0xffff0000, v130
	v_pk_add_f32 v[70:71], v[70:71], v[78:79]
	v_pk_add_f32 v[68:69], v[68:69], v[76:77]
	v_lshlrev_b32_e32 v82, 16, v131
	v_and_b32_e32 v83, 0xffff0000, v131
	v_pk_add_f32 v[78:79], v[64:65], v[80:81]
	v_mul_f32_e32 v64, v69, v69
	v_mul_f32_e32 v65, v71, v71
	v_pk_add_f32 v[76:77], v[66:67], v[82:83]
	v_fmac_f32_e32 v64, v68, v68
	v_fmac_f32_e32 v65, v70, v70
	v_add_f32_e32 v64, v64, v65
	v_mul_f32_e32 v65, v79, v79
	v_mul_f32_e32 v66, v77, v77
	v_fmac_f32_e32 v65, v78, v78
	v_fmac_f32_e32 v66, v76, v76
	v_add_f32_e32 v65, v65, v66
	v_add_f32_e32 v64, v64, v65
	v_add_f32_e32 v67, v84, v64
	ds_bpermute_b32 v82, v112, v67
	v_lshl_add_u64 v[64:65], s[64:65], 0, v[176:177]
	v_lshl_add_u64 v[80:81], v[168:169], 1, v[64:65]
	global_store_dwordx4 v[80:81], v[72:75], off nt
	v_cvt_pk_bf16_f32 v66, v68, v69
	s_waitcnt lgkmcnt(0)
	v_add_f32_e32 v64, v67, v82
	ds_bpermute_b32 v65, v113, v64
	v_cvt_pk_bf16_f32 v67, v70, v71
	v_cvt_pk_bf16_f32 v68, v78, v79
	v_cvt_pk_bf16_f32 v69, v76, v77
	global_store_dwordx4 v[80:81], v[66:69], off offset:256 nt
	s_and_saveexec_b64 s[16:17], s[2:3]
	s_cbranch_execz .LBB0_1750
	s_waitcnt lgkmcnt(0)
	v_add_f32_e32 v66, v64, v65
	v_lshlrev_b64 v[64:65], 6, v[174:175]
	v_lshl_add_u64 v[64:65], s[74:75], 0, v[64:65]
	v_lshl_add_u64 v[64:65], s[14:15], 2, v[64:65]
	s_lshl_b32 s10, s34, 2
	v_lshl_add_u64 v[64:65], v[64:65], 0, s[10:11]
	global_store_dword v[64:65], v66, off
.LBB0_1750:
	s_or_b64 exec, exec, s[16:17]
	v_add_u32_e32 v100, 0x80, v170
	v_ashrrev_i32_e32 v101, 31, v100
	v_add_u32_e32 v96, 0x90, v170
	v_lshlrev_b64 v[110:111], 11, v[100:101]
	v_ashrrev_i32_e32 v97, 31, v96
	v_add_u32_e32 v92, 0xa0, v170
	s_waitcnt lgkmcnt(0)
	v_lshl_add_u64 v[64:65], v[172:173], 0, v[110:111]
	v_lshlrev_b64 v[98:99], 11, v[96:97]
	v_ashrrev_i32_e32 v93, 31, v92
	v_add_u32_e32 v88, 0xb0, v170
	global_load_dwordx4 v[102:105], v[64:65], off
	global_load_dwordx4 v[106:109], v[64:65], off offset:256
	v_lshl_add_u64 v[64:65], v[172:173], 0, v[98:99]
	v_lshlrev_b64 v[94:95], 11, v[92:93]
	v_ashrrev_i32_e32 v89, 31, v88
	global_load_dwordx4 v[84:87], v[64:65], off
	global_load_dwordx4 v[80:83], v[64:65], off offset:256
	v_lshl_add_u64 v[64:65], v[172:173], 0, v[94:95]
	v_lshlrev_b64 v[90:91], 11, v[88:89]
	global_load_dwordx4 v[76:79], v[64:65], off
	global_load_dwordx4 v[72:75], v[64:65], off offset:256
	v_lshl_add_u64 v[64:65], v[172:173], 0, v[90:91]
	global_load_dwordx4 v[68:71], v[64:65], off
	s_nop 0
	global_load_dwordx4 v[64:67], v[64:65], off offset:256
	s_waitcnt vmcnt(7)
	v_lshlrev_b32_e32 v114, 16, v102
	v_and_b32_e32 v115, 0xffff0000, v102
	v_lshlrev_b32_e32 v102, 16, v103
	v_and_b32_e32 v103, 0xffff0000, v103
	v_lshlrev_b32_e32 v116, 16, v104
	v_and_b32_e32 v117, 0xffff0000, v104
	v_lshlrev_b32_e32 v104, 16, v105
	v_and_b32_e32 v105, 0xffff0000, v105
	v_pk_add_f32 v[62:63], v[62:63], v[102:103]
	v_pk_add_f32 v[60:61], v[60:61], v[114:115]
	v_pk_add_f32 v[102:103], v[58:59], v[104:105]
	v_pk_add_f32 v[58:59], v[56:57], v[116:117]
	v_mul_f32_e32 v56, v61, v61
	v_mul_f32_e32 v57, v63, v63
	v_fmac_f32_e32 v56, v60, v60
	v_fmac_f32_e32 v57, v62, v62
	v_add_f32_e32 v56, v56, v57
	v_mul_f32_e32 v57, v59, v59
	v_mul_f32_e32 v104, v103, v103
	v_fmac_f32_e32 v57, v58, v58
	v_fmac_f32_e32 v104, v102, v102
	v_add_f32_e32 v57, v57, v104
	v_add_f32_e32 v114, v56, v57
	v_cvt_pk_bf16_f32 v56, v60, v61
	v_cvt_pk_bf16_f32 v57, v62, v63
	s_waitcnt vmcnt(6)
	v_lshlrev_b32_e32 v60, 16, v106
	v_and_b32_e32 v61, 0xffff0000, v106
	v_lshlrev_b32_e32 v62, 16, v107
	v_and_b32_e32 v63, 0xffff0000, v107
	v_cvt_pk_bf16_f32 v58, v58, v59
	v_cvt_pk_bf16_f32 v59, v102, v103
	v_lshlrev_b32_e32 v102, 16, v108
	v_and_b32_e32 v103, 0xffff0000, v108
	v_pk_add_f32 v[54:55], v[54:55], v[62:63]
	v_pk_add_f32 v[52:53], v[52:53], v[60:61]
	v_lshlrev_b32_e32 v104, 16, v109
	v_and_b32_e32 v105, 0xffff0000, v109
	v_pk_add_f32 v[62:63], v[48:49], v[102:103]
	v_mul_f32_e32 v48, v53, v53
	v_mul_f32_e32 v49, v55, v55
	v_pk_add_f32 v[60:61], v[50:51], v[104:105]
	v_fmac_f32_e32 v48, v52, v52
	v_fmac_f32_e32 v49, v54, v54
	v_add_f32_e32 v48, v48, v49
	v_mul_f32_e32 v49, v63, v63
	v_mul_f32_e32 v50, v61, v61
	v_fmac_f32_e32 v49, v62, v62
	v_fmac_f32_e32 v50, v60, v60
	v_add_f32_e32 v49, v49, v50
	v_add_f32_e32 v48, v48, v49
	v_add_f32_e32 v51, v114, v48
	ds_bpermute_b32 v104, v112, v51
	v_lshl_add_u64 v[48:49], s[64:65], 0, v[110:111]
	v_lshl_add_u64 v[102:103], v[168:169], 1, v[48:49]
	global_store_dwordx4 v[102:103], v[56:59], off nt
	v_cvt_pk_bf16_f32 v50, v52, v53
	s_waitcnt lgkmcnt(0)
	v_add_f32_e32 v48, v51, v104
	ds_bpermute_b32 v49, v113, v48
	v_cvt_pk_bf16_f32 v51, v54, v55
	v_cvt_pk_bf16_f32 v52, v62, v63
	v_cvt_pk_bf16_f32 v53, v60, v61
	global_store_dwordx4 v[102:103], v[50:53], off offset:256 nt
	s_and_saveexec_b64 s[16:17], s[2:3]
	s_cbranch_execz .LBB0_1752
	s_waitcnt lgkmcnt(0)
	v_add_f32_e32 v50, v48, v49
	v_lshlrev_b64 v[48:49], 6, v[100:101]
	v_lshl_add_u64 v[48:49], s[74:75], 0, v[48:49]
	v_lshl_add_u64 v[48:49], s[14:15], 2, v[48:49]
	s_lshl_b32 s10, s34, 2
	v_lshl_add_u64 v[48:49], v[48:49], 0, s[10:11]
	global_store_dword v[48:49], v50, off
.LBB0_1752:
	s_or_b64 exec, exec, s[16:17]
	s_waitcnt vmcnt(7)
	v_lshlrev_b32_e32 v48, 16, v84
	s_waitcnt lgkmcnt(0)
	v_and_b32_e32 v49, 0xffff0000, v84
	v_lshlrev_b32_e32 v50, 16, v85
	v_and_b32_e32 v51, 0xffff0000, v85
	v_lshlrev_b32_e32 v52, 16, v86
	v_and_b32_e32 v53, 0xffff0000, v86
	v_lshlrev_b32_e32 v54, 16, v87
	v_and_b32_e32 v55, 0xffff0000, v87
	v_pk_add_f32 v[46:47], v[46:47], v[50:51]
	v_pk_add_f32 v[44:45], v[44:45], v[48:49]
	v_pk_add_f32 v[48:49], v[42:43], v[54:55]
	v_pk_add_f32 v[42:43], v[40:41], v[52:53]
	v_mul_f32_e32 v40, v45, v45
	v_mul_f32_e32 v41, v47, v47
	v_fmac_f32_e32 v40, v44, v44
	v_fmac_f32_e32 v41, v46, v46
	v_add_f32_e32 v40, v40, v41
	v_mul_f32_e32 v41, v43, v43
	v_mul_f32_e32 v50, v49, v49
	v_fmac_f32_e32 v41, v42, v42
	v_fmac_f32_e32 v50, v48, v48
	v_add_f32_e32 v41, v41, v50
	v_add_f32_e32 v52, v40, v41
	v_cvt_pk_bf16_f32 v40, v44, v45
	v_cvt_pk_bf16_f32 v41, v46, v47
	s_waitcnt vmcnt(6)
	v_lshlrev_b32_e32 v44, 16, v80
	v_and_b32_e32 v45, 0xffff0000, v80
	v_lshlrev_b32_e32 v46, 16, v81
	v_and_b32_e32 v47, 0xffff0000, v81
	v_cvt_pk_bf16_f32 v42, v42, v43
	v_cvt_pk_bf16_f32 v43, v48, v49
	v_lshlrev_b32_e32 v48, 16, v82
	v_and_b32_e32 v49, 0xffff0000, v82
	v_pk_add_f32 v[38:39], v[38:39], v[46:47]
	v_pk_add_f32 v[36:37], v[36:37], v[44:45]
	v_lshlrev_b32_e32 v50, 16, v83
	v_and_b32_e32 v51, 0xffff0000, v83
	v_pk_add_f32 v[46:47], v[32:33], v[48:49]
	v_mul_f32_e32 v32, v37, v37
	v_mul_f32_e32 v33, v39, v39
	v_pk_add_f32 v[44:45], v[34:35], v[50:51]
	v_fmac_f32_e32 v32, v36, v36
	v_fmac_f32_e32 v33, v38, v38
	v_add_f32_e32 v32, v32, v33
	v_mul_f32_e32 v33, v47, v47
	v_mul_f32_e32 v34, v45, v45
	v_fmac_f32_e32 v33, v46, v46
	v_fmac_f32_e32 v34, v44, v44
	v_add_f32_e32 v33, v33, v34
	v_add_f32_e32 v32, v32, v33
	v_add_f32_e32 v35, v52, v32
	ds_bpermute_b32 v50, v112, v35
	v_lshl_add_u64 v[32:33], s[64:65], 0, v[98:99]
	v_lshl_add_u64 v[48:49], v[168:169], 1, v[32:33]
	global_store_dwordx4 v[48:49], v[40:43], off nt
	v_cvt_pk_bf16_f32 v34, v36, v37
	s_waitcnt lgkmcnt(0)
	v_add_f32_e32 v32, v35, v50
	ds_bpermute_b32 v33, v113, v32
	v_cvt_pk_bf16_f32 v35, v38, v39
	v_cvt_pk_bf16_f32 v36, v46, v47
	v_cvt_pk_bf16_f32 v37, v44, v45
	global_store_dwordx4 v[48:49], v[34:37], off offset:256 nt
	s_and_saveexec_b64 s[16:17], s[2:3]
	s_cbranch_execz .LBB0_1754
	s_waitcnt lgkmcnt(0)
	v_add_f32_e32 v34, v32, v33
	v_lshlrev_b64 v[32:33], 6, v[96:97]
	v_lshl_add_u64 v[32:33], s[74:75], 0, v[32:33]
	v_lshl_add_u64 v[32:33], s[14:15], 2, v[32:33]
	s_lshl_b32 s10, s34, 2
	v_lshl_add_u64 v[32:33], v[32:33], 0, s[10:11]
	global_store_dword v[32:33], v34, off
.LBB0_1754:
	s_or_b64 exec, exec, s[16:17]
	s_waitcnt vmcnt(7)
	v_lshlrev_b32_e32 v32, 16, v76
	s_waitcnt lgkmcnt(0)
	v_and_b32_e32 v33, 0xffff0000, v76
	v_lshlrev_b32_e32 v34, 16, v77
	v_and_b32_e32 v35, 0xffff0000, v77
	v_lshlrev_b32_e32 v36, 16, v78
	v_and_b32_e32 v37, 0xffff0000, v78
	v_lshlrev_b32_e32 v38, 16, v79
	v_and_b32_e32 v39, 0xffff0000, v79
	v_pk_add_f32 v[30:31], v[30:31], v[34:35]
	v_pk_add_f32 v[28:29], v[28:29], v[32:33]
	v_pk_add_f32 v[32:33], v[26:27], v[38:39]
	v_pk_add_f32 v[26:27], v[24:25], v[36:37]
	v_mul_f32_e32 v24, v29, v29
	v_mul_f32_e32 v25, v31, v31
	v_fmac_f32_e32 v24, v28, v28
	v_fmac_f32_e32 v25, v30, v30
	v_add_f32_e32 v24, v24, v25
	v_mul_f32_e32 v25, v27, v27
	v_mul_f32_e32 v34, v33, v33
	v_fmac_f32_e32 v25, v26, v26
	v_fmac_f32_e32 v34, v32, v32
	v_add_f32_e32 v25, v25, v34
	v_add_f32_e32 v36, v24, v25
	v_cvt_pk_bf16_f32 v24, v28, v29
	v_cvt_pk_bf16_f32 v25, v30, v31
	s_waitcnt vmcnt(6)
	v_lshlrev_b32_e32 v28, 16, v72
	v_and_b32_e32 v29, 0xffff0000, v72
	v_lshlrev_b32_e32 v30, 16, v73
	v_and_b32_e32 v31, 0xffff0000, v73
	v_cvt_pk_bf16_f32 v26, v26, v27
	v_cvt_pk_bf16_f32 v27, v32, v33
	v_lshlrev_b32_e32 v32, 16, v74
	v_and_b32_e32 v33, 0xffff0000, v74
	v_pk_add_f32 v[22:23], v[22:23], v[30:31]
	v_pk_add_f32 v[20:21], v[20:21], v[28:29]
	v_lshlrev_b32_e32 v34, 16, v75
	v_and_b32_e32 v35, 0xffff0000, v75
	v_pk_add_f32 v[30:31], v[16:17], v[32:33]
	v_mul_f32_e32 v16, v21, v21
	v_mul_f32_e32 v17, v23, v23
	v_pk_add_f32 v[28:29], v[18:19], v[34:35]
	v_fmac_f32_e32 v16, v20, v20
	v_fmac_f32_e32 v17, v22, v22
	v_add_f32_e32 v16, v16, v17
	v_mul_f32_e32 v17, v31, v31
	v_mul_f32_e32 v18, v29, v29
	v_fmac_f32_e32 v17, v30, v30
	v_fmac_f32_e32 v18, v28, v28
	v_add_f32_e32 v17, v17, v18
	v_add_f32_e32 v16, v16, v17
	v_add_f32_e32 v19, v36, v16
	ds_bpermute_b32 v34, v112, v19
	v_lshl_add_u64 v[16:17], s[64:65], 0, v[94:95]
	v_lshl_add_u64 v[32:33], v[168:169], 1, v[16:17]
	global_store_dwordx4 v[32:33], v[24:27], off nt
	v_cvt_pk_bf16_f32 v18, v20, v21
	s_waitcnt lgkmcnt(0)
	v_add_f32_e32 v16, v19, v34
	ds_bpermute_b32 v17, v113, v16
	v_cvt_pk_bf16_f32 v19, v22, v23
	v_cvt_pk_bf16_f32 v20, v30, v31
	v_cvt_pk_bf16_f32 v21, v28, v29
	global_store_dwordx4 v[32:33], v[18:21], off offset:256 nt
	s_and_saveexec_b64 s[16:17], s[2:3]
	s_cbranch_execz .LBB0_1756
	s_waitcnt lgkmcnt(0)
	v_add_f32_e32 v18, v16, v17
	v_lshlrev_b64 v[16:17], 6, v[92:93]
	v_lshl_add_u64 v[16:17], s[74:75], 0, v[16:17]
	v_lshl_add_u64 v[16:17], s[14:15], 2, v[16:17]
	s_lshl_b32 s10, s34, 2
	v_lshl_add_u64 v[16:17], v[16:17], 0, s[10:11]
	global_store_dword v[16:17], v18, off
.LBB0_1756:
	s_or_b64 exec, exec, s[16:17]
	s_waitcnt vmcnt(7)
	v_lshlrev_b32_e32 v16, 16, v68
	s_waitcnt lgkmcnt(0)
	v_and_b32_e32 v17, 0xffff0000, v68
	v_lshlrev_b32_e32 v18, 16, v69
	v_and_b32_e32 v19, 0xffff0000, v69
	v_lshlrev_b32_e32 v20, 16, v70
	v_and_b32_e32 v21, 0xffff0000, v70
	v_lshlrev_b32_e32 v22, 16, v71
	v_and_b32_e32 v23, 0xffff0000, v71
	v_pk_add_f32 v[14:15], v[14:15], v[18:19]
	v_pk_add_f32 v[12:13], v[12:13], v[16:17]
	v_pk_add_f32 v[16:17], v[10:11], v[22:23]
	v_pk_add_f32 v[10:11], v[8:9], v[20:21]
	v_mul_f32_e32 v8, v13, v13
	v_mul_f32_e32 v9, v15, v15
	v_fmac_f32_e32 v8, v12, v12
	v_fmac_f32_e32 v9, v14, v14
	v_add_f32_e32 v8, v8, v9
	v_mul_f32_e32 v9, v11, v11
	v_mul_f32_e32 v18, v17, v17
	v_fmac_f32_e32 v9, v10, v10
	v_fmac_f32_e32 v18, v16, v16
	v_add_f32_e32 v9, v9, v18
	v_add_f32_e32 v20, v8, v9
	v_cvt_pk_bf16_f32 v8, v12, v13
	v_cvt_pk_bf16_f32 v9, v14, v15
	s_waitcnt vmcnt(6)
	v_lshlrev_b32_e32 v12, 16, v64
	v_and_b32_e32 v13, 0xffff0000, v64
	v_lshlrev_b32_e32 v14, 16, v65
	v_and_b32_e32 v15, 0xffff0000, v65
	v_cvt_pk_bf16_f32 v10, v10, v11
	v_cvt_pk_bf16_f32 v11, v16, v17
	v_lshlrev_b32_e32 v16, 16, v66
	v_and_b32_e32 v17, 0xffff0000, v66
	v_pk_add_f32 v[6:7], v[6:7], v[14:15]
	v_pk_add_f32 v[4:5], v[4:5], v[12:13]
	v_lshlrev_b32_e32 v18, 16, v67
	v_and_b32_e32 v19, 0xffff0000, v67
	v_pk_add_f32 v[14:15], v[0:1], v[16:17]
	v_mul_f32_e32 v0, v5, v5
	v_mul_f32_e32 v1, v7, v7
	v_pk_add_f32 v[12:13], v[2:3], v[18:19]
	v_fmac_f32_e32 v0, v4, v4
	v_fmac_f32_e32 v1, v6, v6
	v_add_f32_e32 v0, v0, v1
	v_mul_f32_e32 v1, v15, v15
	v_mul_f32_e32 v2, v13, v13
	v_fmac_f32_e32 v1, v14, v14
	v_fmac_f32_e32 v2, v12, v12
	v_add_f32_e32 v1, v1, v2
	v_add_f32_e32 v0, v0, v1
	v_add_f32_e32 v3, v20, v0
	ds_bpermute_b32 v18, v112, v3
	v_lshl_add_u64 v[0:1], s[64:65], 0, v[90:91]
	v_lshl_add_u64 v[16:17], v[168:169], 1, v[0:1]
	global_store_dwordx4 v[16:17], v[8:11], off nt
	v_cvt_pk_bf16_f32 v2, v4, v5
	s_waitcnt lgkmcnt(0)
	v_add_f32_e32 v0, v3, v18
	ds_bpermute_b32 v1, v113, v0
	v_cvt_pk_bf16_f32 v3, v6, v7
	v_cvt_pk_bf16_f32 v4, v14, v15
	v_cvt_pk_bf16_f32 v5, v12, v13
	global_store_dwordx4 v[16:17], v[2:5], off offset:256 nt
	s_and_saveexec_b64 s[16:17], s[2:3]
	s_cbranch_execz .LBB0_1729
	s_waitcnt lgkmcnt(0)
	v_add_f32_e32 v2, v0, v1
	v_lshlrev_b64 v[0:1], 6, v[88:89]
	v_lshl_add_u64 v[0:1], s[74:75], 0, v[0:1]
	v_lshl_add_u64 v[0:1], s[14:15], 2, v[0:1]
	s_lshl_b32 s10, s34, 2
	v_lshl_add_u64 v[0:1], v[0:1], 0, s[10:11]
	global_store_dword v[0:1], v2, off
	s_branch .LBB0_1729
